# GEMM K-loops: 54 LDS-DMA loads switched to scalar-base + 32-bit lane-offset addressing, removing their per-iteration 64-bit VALU address adds; on top of v35
# speedup vs baseline: 1.0111x; 1.0033x over previous
; #define PG8_STAGE(bufoff, gbase, voff) do { _Pragma("unroll") for (int _i = 0; _i < 2; ++_i) \
;         __builtin_amdgcn_global_load_lds((const unsigned*)((const char*)(gbase) + (voff)[_i]), (PG8_LAS unsigned*)(lds + (bufoff) + ldsw + _i * 8192), 16, 0, 0); } while (0)
; #define PG8_LDA(dst, b, h) do { _Pragma("unroll") for (int m = 0; m < 4; ++m) _Pragma("unroll") for (int k = 0; k < 2; ++k) dst[m][k] = *(const PG8_LAS bf16x8*)(lds + PG8_SA(b, h) + aoff + m * 2048 + k * 1024); } while (0)
; #define PG8_LDB(dst, b, h) do { _Pragma("unroll") for (int n = 0; n < 2; ++n) _Pragma("unroll") for (int k = 0; k < 2; ++k) dst[n][k] = *(const PG8_LAS bf16x8*)(lds + PG8_SB(b, h) + boff + n * 2048 + k * 1024); } while (0)
; #define PG8_MMA(ai, bj, At, Bt) do { __builtin_amdgcn_s_setprio(1); _Pragma("unroll") for (int m = 0; m < 4; ++m) _Pragma("unroll") for (int n = 0; n < 2; ++n) _Pragma("unroll") for (int k = 0; k < 2; ++k) \
;         acc[ai][bj][m][n] = __builtin_amdgcn_mfma_f32_16x16x32_bf16(Bt[n][k], At[m][k], acc[ai][bj][m][n], 0, 0, 0); __builtin_amdgcn_s_setprio(0); } while (0)
; #define PG8_WAIT_V(n) asm volatile("s_waitcnt vmcnt(" #n ")" ::: "memory")
; #define PG8_WAIT_L(n) asm volatile("s_waitcnt lgkmcnt(" #n ")" ::: "memory")
; #define PG8_BAR __builtin_amdgcn_s_barrier()
; #define PG8_SCHED __builtin_amdgcn_sched_barrier(0)
; template <class Epi, class Sched, bool ALIGN_EPI = false, bool SP2 = false>
; __device__ __forceinline__ void gemm_phase(PG8_LAS unsigned char* lds, const Gemm g, const Sched& S, const Epi& E) {
;     ...
;             PG8_LDB(B0, 0, 0); PG8_LDB(B1, 0, 1); PG8_SCHED; PG8_LDA(At, 0, 0); PG8_STAGE(PG8_SA(1, 1), a1 + hstepA, voffA);
;             PG8_WAIT_V(8); PG8_WAIT_L(0); PG8_BAR; PG8_MMA(0, 0, At, B0); PG8_MMA(0, 1, At, B1); PG8_BAR; PG8_SCHED;
;             PG8_LDA(At, 0, 1); PG8_STAGE(PG8_SB(0, 0), b2, voffB); PG8_STAGE(PG8_SB(0, 1), b2 + hstepB, voffB); PG8_STAGE(PG8_SA(0, 0), a2, voffA);
;             PG8_WAIT_V(8); PG8_WAIT_L(0); PG8_BAR; PG8_MMA(1, 0, At, B0); PG8_MMA(1, 1, At, B1); PG8_BAR; PG8_SCHED;
.LBB0_254:
	s_add_u32 s28, s26, 0xfffc0080
	s_addc_u32 s29, s27, -1
	s_add_i32 s53, 0, 0x10000
	s_cmp_eq_u32 s52, 12
	s_cselect_b32 s31, s7, s29
	s_cselect_b32 s30, s9, s28
	v_add_u32_e32 v150, s53, v153
	s_cselect_b32 s29, s19, s51
	s_cselect_b32 s28, s21, s50
	s_add_i32 s56, 0, 0x14000
	ds_read_b128 v[142:145], v150
	ds_read_b128 v[146:149], v150 offset:1024
	ds_read_b128 v[158:161], v150 offset:2048
	ds_read_b128 v[162:165], v150 offset:3072
	v_add_u32_e32 v150, s56, v153
	ds_read_b128 v[166:169], v150
	ds_read_b128 v[170:173], v150 offset:1024
	ds_read_b128 v[174:177], v150 offset:2048
	ds_read_b128 v[178:181], v150 offset:3072
	s_add_i32 m0, s40, 0xc000
	ds_read_b128 v[182:185], v156
	ds_read_b128 v[202:205], v156 offset:1024
	ds_read_b128 v[206:209], v156 offset:2048
	ds_read_b128 v[210:213], v156 offset:3072
	ds_read_b128 v[232:235], v156 offset:4096
	ds_read_b128 v[236:239], v156 offset:5120
	ds_read_b128 v[240:243], v156 offset:6144
	ds_read_b128 v[244:247], v156 offset:7168
	global_load_lds_dwordx4 v138, s[26:27]
	s_add_i32 m0, s40, 0xe000
	s_nop 0
	global_load_lds_dwordx4 v140, s[26:27]
	s_waitcnt vmcnt(8)
	s_waitcnt lgkmcnt(0)
	s_barrier
	s_setprio 1
	s_waitcnt lgkmcnt(0)
	v_mfma_f32_16x16x32_bf16 v[126:129], v[142:145], v[182:185], v[126:129]
	v_mfma_f32_16x16x32_bf16 v[122:125], v[158:161], v[182:185], v[122:125]
	v_mfma_f32_16x16x32_bf16 v[110:113], v[142:145], v[206:209], v[110:113]
	v_mfma_f32_16x16x32_bf16 v[106:109], v[158:161], v[206:209], v[106:109]
	v_mfma_f32_16x16x32_bf16 v[94:97], v[142:145], v[232:235], v[94:97]
	v_mfma_f32_16x16x32_bf16 v[90:93], v[158:161], v[232:235], v[90:93]
	v_mfma_f32_16x16x32_bf16 v[78:81], v[142:145], v[240:243], v[78:81]
	v_mfma_f32_16x16x32_bf16 v[74:77], v[158:161], v[240:243], v[74:77]
	v_mfma_f32_16x16x32_bf16 v[126:129], v[146:149], v[202:205], v[126:129]
	v_mfma_f32_16x16x32_bf16 v[122:125], v[162:165], v[202:205], v[122:125]
	v_mfma_f32_16x16x32_bf16 v[110:113], v[146:149], v[210:213], v[110:113]
	v_mfma_f32_16x16x32_bf16 v[106:109], v[162:165], v[210:213], v[106:109]
	v_mfma_f32_16x16x32_bf16 v[94:97], v[146:149], v[236:239], v[94:97]
	v_mfma_f32_16x16x32_bf16 v[90:93], v[162:165], v[236:239], v[90:93]
	v_mfma_f32_16x16x32_bf16 v[78:81], v[146:149], v[244:247], v[78:81]
	v_mfma_f32_16x16x32_bf16 v[74:77], v[162:165], v[244:247], v[74:77]
	s_setprio 0
	s_setprio 1
	v_mfma_f32_16x16x32_bf16 v[118:121], v[166:169], v[182:185], v[118:121]
	v_mfma_f32_16x16x32_bf16 v[114:117], v[174:177], v[182:185], v[114:117]
	v_mfma_f32_16x16x32_bf16 v[102:105], v[166:169], v[206:209], v[102:105]
	v_mfma_f32_16x16x32_bf16 v[98:101], v[174:177], v[206:209], v[98:101]
	v_mfma_f32_16x16x32_bf16 v[86:89], v[166:169], v[232:235], v[86:89]
	v_mfma_f32_16x16x32_bf16 v[82:85], v[174:177], v[232:235], v[82:85]
	v_mfma_f32_16x16x32_bf16 v[70:73], v[166:169], v[240:243], v[70:73]
	v_mfma_f32_16x16x32_bf16 v[66:69], v[174:177], v[240:243], v[66:69]
	v_mfma_f32_16x16x32_bf16 v[118:121], v[170:173], v[202:205], v[118:121]
	v_mfma_f32_16x16x32_bf16 v[114:117], v[178:181], v[202:205], v[114:117]
	v_mfma_f32_16x16x32_bf16 v[102:105], v[170:173], v[210:213], v[102:105]
	v_mfma_f32_16x16x32_bf16 v[98:101], v[178:181], v[210:213], v[98:101]
	v_mfma_f32_16x16x32_bf16 v[86:89], v[170:173], v[236:239], v[86:89]
	v_mfma_f32_16x16x32_bf16 v[82:85], v[178:181], v[236:239], v[82:85]
	v_mfma_f32_16x16x32_bf16 v[70:73], v[170:173], v[244:247], v[70:73]
	v_mfma_f32_16x16x32_bf16 v[66:69], v[178:181], v[244:247], v[66:69]
	s_setprio 0
	s_barrier
	s_add_i32 s53, s53, s39
	v_lshl_add_u64 v[150:151], s[28:29], 0, v[132:133]
	s_mov_b32 m0, s53
	ds_read_b128 v[182:185], v156 offset:16384
	ds_read_b128 v[202:205], v156 offset:17408
	ds_read_b128 v[206:209], v156 offset:18432
	ds_read_b128 v[210:213], v156 offset:19456
	ds_read_b128 v[232:235], v156 offset:20480
	ds_read_b128 v[236:239], v156 offset:21504
	ds_read_b128 v[240:243], v156 offset:22528
	ds_read_b128 v[244:247], v156 offset:23552
	global_load_lds_dwordx4 v[150:151], off
	s_add_i32 m0, s53, 0x2000
	s_add_u32 s54, s28, 0x40000
	v_lshl_add_u64 v[186:187], s[28:29], 0, v[136:137]
	s_addc_u32 s55, s29, 0
	s_add_i32 s53, s56, s39
	global_load_lds_dwordx4 v[186:187], off
	s_mov_b32 m0, s53
	v_lshl_add_u64 v[248:249], s[30:31], 0, v[134:135]
	global_load_lds_dwordx4 v132, s[54:55]
	s_add_i32 m0, s53, 0x2000
	s_nop 0
	global_load_lds_dwordx4 v136, s[54:55]
	v_lshl_add_u64 v[214:215], s[30:31], 0, v[130:131]
	s_mov_b32 m0, s40
	s_nop 0
	global_load_lds_dwordx4 v[214:215], off
	s_mov_b32 m0, s41
	s_nop 0
	global_load_lds_dwordx4 v[248:249], off
	s_waitcnt vmcnt(8)
	s_waitcnt lgkmcnt(0)
	s_barrier
; #define PG8_STAGE(bufoff, gbase, voff) do { _Pragma("unroll") for (int _i = 0; _i < 2; ++_i) \
;         __builtin_amdgcn_global_load_lds((const unsigned*)((const char*)(gbase) + (voff)[_i]), (PG8_LAS unsigned*)(lds + (bufoff) + ldsw + _i * 8192), 16, 0, 0); } while (0)
; #define PG8_LDA(dst, b, h) do { _Pragma("unroll") for (int m = 0; m < 4; ++m) _Pragma("unroll") for (int k = 0; k < 2; ++k) dst[m][k] = *(const PG8_LAS bf16x8*)(lds + PG8_SA(b, h) + aoff + m * 2048 + k * 1024); } while (0)
; #define PG8_LDB(dst, b, h) do { _Pragma("unroll") for (int n = 0; n < 2; ++n) _Pragma("unroll") for (int k = 0; k < 2; ++k) dst[n][k] = *(const PG8_LAS bf16x8*)(lds + PG8_SB(b, h) + boff + n * 2048 + k * 1024); } while (0)
; #define PG8_MMA(ai, bj, At, Bt) do { __builtin_amdgcn_s_setprio(1); _Pragma("unroll") for (int m = 0; m < 4; ++m) _Pragma("unroll") for (int n = 0; n < 2; ++n) _Pragma("unroll") for (int k = 0; k < 2; ++k) \
;         acc[ai][bj][m][n] = __builtin_amdgcn_mfma_f32_16x16x32_bf16(Bt[n][k], At[m][k], acc[ai][bj][m][n], 0, 0, 0); __builtin_amdgcn_s_setprio(0); } while (0)
; #define PG8_WAIT_V(n) asm volatile("s_waitcnt vmcnt(" #n ")" ::: "memory")
; #define PG8_WAIT_L(n) asm volatile("s_waitcnt lgkmcnt(" #n ")" ::: "memory")
; #define PG8_BAR __builtin_amdgcn_s_barrier()
; #define PG8_SCHED __builtin_amdgcn_sched_barrier(0)
; template <class Epi, class Sched, bool ALIGN_EPI = false, bool SP2 = false>
; __device__ __forceinline__ void gemm_phase(PG8_LAS unsigned char* lds, const Gemm g, const Sched& S, const Epi& E) {
;     ...
;             PG8_WAIT_V(8); PG8_WAIT_L(0); PG8_BAR; PG8_MMA(1, 0, At, B0); PG8_MMA(1, 1, At, B1); PG8_BAR; PG8_SCHED;
;             PG8_LDB(B0, 1, 0); PG8_LDB(B1, 1, 1); PG8_SCHED; PG8_LDA(At, 1, 0); PG8_STAGE(PG8_SA(0, 1), a2 + hstepA, voffA);
;             PG8_WAIT_V(8); PG8_WAIT_L(0); PG8_BAR; PG8_MMA(0, 0, At, B0); PG8_MMA(0, 1, At, B1); PG8_BAR; PG8_SCHED;
	s_setprio 1
	s_waitcnt lgkmcnt(0)
	v_mfma_f32_16x16x32_bf16 v[62:65], v[142:145], v[182:185], v[62:65]
	v_mfma_f32_16x16x32_bf16 v[58:61], v[158:161], v[182:185], v[58:61]
	v_mfma_f32_16x16x32_bf16 v[46:49], v[142:145], v[206:209], v[46:49]
	v_mfma_f32_16x16x32_bf16 v[42:45], v[158:161], v[206:209], v[42:45]
	v_mfma_f32_16x16x32_bf16 v[30:33], v[142:145], v[232:235], v[30:33]
	v_mfma_f32_16x16x32_bf16 v[26:29], v[158:161], v[232:235], v[26:29]
	v_mfma_f32_16x16x32_bf16 v[14:17], v[142:145], v[240:243], v[14:17]
	v_mfma_f32_16x16x32_bf16 v[10:13], v[158:161], v[240:243], v[10:13]
	v_mfma_f32_16x16x32_bf16 v[62:65], v[146:149], v[202:205], v[62:65]
	v_mfma_f32_16x16x32_bf16 v[58:61], v[162:165], v[202:205], v[58:61]
	v_mfma_f32_16x16x32_bf16 v[46:49], v[146:149], v[210:213], v[46:49]
	v_mfma_f32_16x16x32_bf16 v[42:45], v[162:165], v[210:213], v[42:45]
	v_mfma_f32_16x16x32_bf16 v[30:33], v[146:149], v[236:239], v[30:33]
	v_mfma_f32_16x16x32_bf16 v[26:29], v[162:165], v[236:239], v[26:29]
	v_mfma_f32_16x16x32_bf16 v[14:17], v[146:149], v[244:247], v[14:17]
	v_mfma_f32_16x16x32_bf16 v[10:13], v[162:165], v[244:247], v[10:13]
	s_setprio 0
	s_setprio 1
	v_mfma_f32_16x16x32_bf16 v[54:57], v[166:169], v[182:185], v[54:57]
	v_mfma_f32_16x16x32_bf16 v[50:53], v[174:177], v[182:185], v[50:53]
	v_mfma_f32_16x16x32_bf16 v[38:41], v[166:169], v[206:209], v[38:41]
	v_mfma_f32_16x16x32_bf16 v[34:37], v[174:177], v[206:209], v[34:37]
	v_mfma_f32_16x16x32_bf16 v[22:25], v[166:169], v[232:235], v[22:25]
	v_mfma_f32_16x16x32_bf16 v[18:21], v[174:177], v[232:235], v[18:21]
	v_mfma_f32_16x16x32_bf16 v[6:9], v[166:169], v[240:243], v[6:9]
	v_mfma_f32_16x16x32_bf16 v[2:5], v[174:177], v[240:243], v[2:5]
	v_mfma_f32_16x16x32_bf16 v[54:57], v[170:173], v[202:205], v[54:57]
	v_mfma_f32_16x16x32_bf16 v[50:53], v[178:181], v[202:205], v[50:53]
	v_mfma_f32_16x16x32_bf16 v[38:41], v[170:173], v[210:213], v[38:41]
	v_mfma_f32_16x16x32_bf16 v[34:37], v[178:181], v[210:213], v[34:37]
	v_mfma_f32_16x16x32_bf16 v[22:25], v[170:173], v[236:239], v[22:25]
	v_mfma_f32_16x16x32_bf16 v[18:21], v[178:181], v[236:239], v[18:21]
	v_mfma_f32_16x16x32_bf16 v[6:9], v[170:173], v[244:247], v[6:9]
	v_mfma_f32_16x16x32_bf16 v[2:5], v[178:181], v[244:247], v[2:5]
	s_setprio 0
	s_barrier
	s_add_i32 s53, 0, 0x18000
	v_add_u32_e32 v157, s53, v153
	s_add_i32 s54, 0, 0x1c000
	ds_read_b128 v[142:145], v157
	ds_read_b128 v[146:149], v157 offset:1024
	ds_read_b128 v[158:161], v157 offset:2048
	ds_read_b128 v[162:165], v157 offset:3072
	v_add_u32_e32 v157, s54, v153
	ds_read_b128 v[166:169], v157
	ds_read_b128 v[170:173], v157 offset:1024
	ds_read_b128 v[174:177], v157 offset:2048
	ds_read_b128 v[178:181], v157 offset:3072
	s_add_u32 s30, s30, 0x40000
	s_addc_u32 s31, s31, 0
	s_mov_b32 m0, s42
	ds_read_b128 v[182:185], v156 offset:32768
	ds_read_b128 v[202:205], v156 offset:33792
	ds_read_b128 v[206:209], v156 offset:34816
	ds_read_b128 v[210:213], v156 offset:35840
	ds_read_b128 v[232:235], v156 offset:36864
	ds_read_b128 v[236:239], v156 offset:37888
	ds_read_b128 v[240:243], v156 offset:38912
	ds_read_b128 v[244:247], v156 offset:39936
	global_load_lds_dwordx4 v130, s[30:31]
	s_mov_b32 m0, s43
	s_nop 0
	global_load_lds_dwordx4 v134, s[30:31]
	s_waitcnt vmcnt(8)
	s_waitcnt lgkmcnt(0)
	s_barrier
	s_setprio 1
	s_waitcnt lgkmcnt(0)
	v_mfma_f32_16x16x32_bf16 v[126:129], v[142:145], v[182:185], v[126:129]
	v_mfma_f32_16x16x32_bf16 v[122:125], v[158:161], v[182:185], v[122:125]
	v_mfma_f32_16x16x32_bf16 v[110:113], v[142:145], v[206:209], v[110:113]
	v_mfma_f32_16x16x32_bf16 v[106:109], v[158:161], v[206:209], v[106:109]
	v_mfma_f32_16x16x32_bf16 v[94:97], v[142:145], v[232:235], v[94:97]
	v_mfma_f32_16x16x32_bf16 v[90:93], v[158:161], v[232:235], v[90:93]
	v_mfma_f32_16x16x32_bf16 v[78:81], v[142:145], v[240:243], v[78:81]
	v_mfma_f32_16x16x32_bf16 v[74:77], v[158:161], v[240:243], v[74:77]
	v_mfma_f32_16x16x32_bf16 v[126:129], v[146:149], v[202:205], v[126:129]
	v_mfma_f32_16x16x32_bf16 v[122:125], v[162:165], v[202:205], v[122:125]
	v_mfma_f32_16x16x32_bf16 v[110:113], v[146:149], v[210:213], v[110:113]
	v_mfma_f32_16x16x32_bf16 v[106:109], v[162:165], v[210:213], v[106:109]
	v_mfma_f32_16x16x32_bf16 v[94:97], v[146:149], v[236:239], v[94:97]
	v_mfma_f32_16x16x32_bf16 v[90:93], v[162:165], v[236:239], v[90:93]
	v_mfma_f32_16x16x32_bf16 v[78:81], v[146:149], v[244:247], v[78:81]
	v_mfma_f32_16x16x32_bf16 v[74:77], v[162:165], v[244:247], v[74:77]
	s_setprio 0
	s_setprio 1
	v_mfma_f32_16x16x32_bf16 v[118:121], v[166:169], v[182:185], v[118:121]
	v_mfma_f32_16x16x32_bf16 v[114:117], v[174:177], v[182:185], v[114:117]
	v_mfma_f32_16x16x32_bf16 v[102:105], v[166:169], v[206:209], v[102:105]
	v_mfma_f32_16x16x32_bf16 v[98:101], v[174:177], v[206:209], v[98:101]
	v_mfma_f32_16x16x32_bf16 v[86:89], v[166:169], v[232:235], v[86:89]
	v_mfma_f32_16x16x32_bf16 v[82:85], v[174:177], v[232:235], v[82:85]
	v_mfma_f32_16x16x32_bf16 v[70:73], v[166:169], v[240:243], v[70:73]
	v_mfma_f32_16x16x32_bf16 v[66:69], v[174:177], v[240:243], v[66:69]
	v_mfma_f32_16x16x32_bf16 v[118:121], v[170:173], v[202:205], v[118:121]
	v_mfma_f32_16x16x32_bf16 v[114:117], v[178:181], v[202:205], v[114:117]
	v_mfma_f32_16x16x32_bf16 v[102:105], v[170:173], v[210:213], v[102:105]
	v_mfma_f32_16x16x32_bf16 v[98:101], v[178:181], v[210:213], v[98:101]
	v_mfma_f32_16x16x32_bf16 v[86:89], v[170:173], v[236:239], v[86:89]
	v_mfma_f32_16x16x32_bf16 v[82:85], v[178:181], v[236:239], v[82:85]
	v_mfma_f32_16x16x32_bf16 v[70:73], v[170:173], v[244:247], v[70:73]
	v_mfma_f32_16x16x32_bf16 v[66:69], v[178:181], v[244:247], v[66:69]
	s_setprio 0
	s_barrier
; #define PG8_STAGE(bufoff, gbase, voff) do { _Pragma("unroll") for (int _i = 0; _i < 2; ++_i) \
;         __builtin_amdgcn_global_load_lds((const unsigned*)((const char*)(gbase) + (voff)[_i]), (PG8_LAS unsigned*)(lds + (bufoff) + ldsw + _i * 8192), 16, 0, 0); } while (0)
; #define PG8_LDA(dst, b, h) do { _Pragma("unroll") for (int m = 0; m < 4; ++m) _Pragma("unroll") for (int k = 0; k < 2; ++k) dst[m][k] = *(const PG8_LAS bf16x8*)(lds + PG8_SA(b, h) + aoff + m * 2048 + k * 1024); } while (0)
; #define PG8_MMA(ai, bj, At, Bt) do { __builtin_amdgcn_s_setprio(1); _Pragma("unroll") for (int m = 0; m < 4; ++m) _Pragma("unroll") for (int n = 0; n < 2; ++n) _Pragma("unroll") for (int k = 0; k < 2; ++k) \
;         acc[ai][bj][m][n] = __builtin_amdgcn_mfma_f32_16x16x32_bf16(Bt[n][k], At[m][k], acc[ai][bj][m][n], 0, 0, 0); __builtin_amdgcn_s_setprio(0); } while (0)
; #define PG8_WAIT_V(n) asm volatile("s_waitcnt vmcnt(" #n ")" ::: "memory")
; #define PG8_WAIT_L(n) asm volatile("s_waitcnt lgkmcnt(" #n ")" ::: "memory")
; #define PG8_BAR __builtin_amdgcn_s_barrier()
; #define PG8_SCHED __builtin_amdgcn_sched_barrier(0)
; template <class Epi, class Sched, bool ALIGN_EPI = false, bool SP2 = false>
; __device__ __forceinline__ void gemm_phase(PG8_LAS unsigned char* lds, const Gemm g, const Sched& S, const Epi& E) {
;     ...
;         for (int t = 0; t < nt; t += 2) {
;     ...
;             PG8_LDA(At, 1, 1); PG8_STAGE(PG8_SB(1, 0), b3, voffB); PG8_STAGE(PG8_SB(1, 1), b3 + hstepB, voffB); PG8_STAGE(PG8_SA(1, 0), a3, voffA);
;             PG8_WAIT_V(8); PG8_WAIT_L(0); PG8_BAR; PG8_MMA(1, 0, At, B0); PG8_MMA(1, 1, At, B1); PG8_BAR; PG8_SCHED;
	s_add_i32 s30, s53, s39
	v_lshl_add_u64 v[150:151], v[150:151], 0, s[96:97]
	s_mov_b32 m0, s30
	ds_read_b128 v[182:185], v156 offset:49152
	ds_read_b128 v[202:205], v156 offset:50176
	ds_read_b128 v[206:209], v156 offset:51200
	ds_read_b128 v[210:213], v156 offset:52224
	ds_read_b128 v[232:235], v156 offset:53248
	ds_read_b128 v[236:239], v156 offset:54272
	ds_read_b128 v[240:243], v156 offset:55296
	ds_read_b128 v[244:247], v156 offset:56320
	global_load_lds_dwordx4 v[150:151], off
	s_add_i32 m0, s30, 0x2000
	s_add_u32 s28, s28, 0x40080
	v_lshl_add_u64 v[150:151], v[186:187], 0, s[96:97]
	s_addc_u32 s29, s29, 0
	s_add_i32 s30, s54, s39
	global_load_lds_dwordx4 v[150:151], off
	s_mov_b32 m0, s30
	s_nop 0
	global_load_lds_dwordx4 v132, s[28:29]
	s_add_i32 m0, s30, 0x2000
	s_nop 0
	global_load_lds_dwordx4 v136, s[28:29]
	v_lshl_add_u64 v[150:151], v[214:215], 0, s[96:97]
	s_mov_b32 m0, s45
	s_nop 0
	global_load_lds_dwordx4 v[150:151], off
	v_lshl_add_u64 v[150:151], v[248:249], 0, s[96:97]
	s_mov_b32 m0, s46
	s_nop 0
	global_load_lds_dwordx4 v[150:151], off
	s_waitcnt vmcnt(8)
	s_waitcnt lgkmcnt(0)
	s_barrier
	s_setprio 1
	s_waitcnt lgkmcnt(0)
	v_mfma_f32_16x16x32_bf16 v[62:65], v[142:145], v[182:185], v[62:65]
	v_mfma_f32_16x16x32_bf16 v[58:61], v[158:161], v[182:185], v[58:61]
	v_mfma_f32_16x16x32_bf16 v[46:49], v[142:145], v[206:209], v[46:49]
	v_mfma_f32_16x16x32_bf16 v[42:45], v[158:161], v[206:209], v[42:45]
	v_mfma_f32_16x16x32_bf16 v[30:33], v[142:145], v[232:235], v[30:33]
	v_mfma_f32_16x16x32_bf16 v[26:29], v[158:161], v[232:235], v[26:29]
	v_mfma_f32_16x16x32_bf16 v[14:17], v[142:145], v[240:243], v[14:17]
	v_mfma_f32_16x16x32_bf16 v[10:13], v[158:161], v[240:243], v[10:13]
	v_mfma_f32_16x16x32_bf16 v[62:65], v[146:149], v[202:205], v[62:65]
	v_mfma_f32_16x16x32_bf16 v[58:61], v[162:165], v[202:205], v[58:61]
	v_mfma_f32_16x16x32_bf16 v[46:49], v[146:149], v[210:213], v[46:49]
	v_mfma_f32_16x16x32_bf16 v[42:45], v[162:165], v[210:213], v[42:45]
	v_mfma_f32_16x16x32_bf16 v[30:33], v[146:149], v[236:239], v[30:33]
	v_mfma_f32_16x16x32_bf16 v[26:29], v[162:165], v[236:239], v[26:29]
	v_mfma_f32_16x16x32_bf16 v[14:17], v[146:149], v[244:247], v[14:17]
	v_mfma_f32_16x16x32_bf16 v[10:13], v[162:165], v[244:247], v[10:13]
	s_setprio 0
	s_setprio 1
	v_mfma_f32_16x16x32_bf16 v[54:57], v[166:169], v[182:185], v[54:57]
	v_mfma_f32_16x16x32_bf16 v[50:53], v[174:177], v[182:185], v[50:53]
	v_mfma_f32_16x16x32_bf16 v[38:41], v[166:169], v[206:209], v[38:41]
	v_mfma_f32_16x16x32_bf16 v[34:37], v[174:177], v[206:209], v[34:37]
	v_mfma_f32_16x16x32_bf16 v[22:25], v[166:169], v[232:235], v[22:25]
	v_mfma_f32_16x16x32_bf16 v[18:21], v[174:177], v[232:235], v[18:21]
	v_mfma_f32_16x16x32_bf16 v[6:9], v[166:169], v[240:243], v[6:9]
	v_mfma_f32_16x16x32_bf16 v[2:5], v[174:177], v[240:243], v[2:5]
	v_mfma_f32_16x16x32_bf16 v[54:57], v[170:173], v[202:205], v[54:57]
	v_mfma_f32_16x16x32_bf16 v[50:53], v[178:181], v[202:205], v[50:53]
	v_mfma_f32_16x16x32_bf16 v[38:41], v[170:173], v[210:213], v[38:41]
	v_mfma_f32_16x16x32_bf16 v[34:37], v[178:181], v[210:213], v[34:37]
	v_mfma_f32_16x16x32_bf16 v[22:25], v[170:173], v[236:239], v[22:25]
	v_mfma_f32_16x16x32_bf16 v[18:21], v[178:181], v[236:239], v[18:21]
	v_mfma_f32_16x16x32_bf16 v[6:9], v[170:173], v[244:247], v[6:9]
	v_mfma_f32_16x16x32_bf16 v[2:5], v[178:181], v[244:247], v[2:5]
	s_setprio 0
	s_barrier
	s_add_i32 s52, s52, 2
	s_add_u32 s26, s26, 0x100
	s_addc_u32 s27, s27, 0
	s_add_u32 s50, s50, 0x100
	s_addc_u32 s51, s51, 0
	s_cmp_gt_u32 s52, 13
	s_cbranch_scc0 .LBB0_254
	s_and_b64 vcc, exec, s[16:17]
	s_cbranch_vccz .LBB0_257
	s_barrier

; #define PG8_STAGE(bufoff, gbase, voff) do { _Pragma("unroll") for (int _i = 0; _i < 2; ++_i) \
;         __builtin_amdgcn_global_load_lds((const unsigned*)((const char*)(gbase) + (voff)[_i]), (PG8_LAS unsigned*)(lds + (bufoff) + ldsw + _i * 8192), 16, 0, 0); } while (0)
; #define PG8_LDA(dst, b, h) do { _Pragma("unroll") for (int m = 0; m < 4; ++m) _Pragma("unroll") for (int k = 0; k < 2; ++k) dst[m][k] = *(const PG8_LAS bf16x8*)(lds + PG8_SA(b, h) + aoff + m * 2048 + k * 1024); } while (0)
; #define PG8_LDB(dst, b, h) do { _Pragma("unroll") for (int n = 0; n < 2; ++n) _Pragma("unroll") for (int k = 0; k < 2; ++k) dst[n][k] = *(const PG8_LAS bf16x8*)(lds + PG8_SB(b, h) + boff + n * 2048 + k * 1024); } while (0)
; #define PG8_MMA(ai, bj, At, Bt) do { __builtin_amdgcn_s_setprio(1); _Pragma("unroll") for (int m = 0; m < 4; ++m) _Pragma("unroll") for (int n = 0; n < 2; ++n) _Pragma("unroll") for (int k = 0; k < 2; ++k) \
;         acc[ai][bj][m][n] = __builtin_amdgcn_mfma_f32_16x16x32_bf16(Bt[n][k], At[m][k], acc[ai][bj][m][n], 0, 0, 0); __builtin_amdgcn_s_setprio(0); } while (0)
; #define PG8_WAIT_V(n) asm volatile("s_waitcnt vmcnt(" #n ")" ::: "memory")
; #define PG8_WAIT_L(n) asm volatile("s_waitcnt lgkmcnt(" #n ")" ::: "memory")
; #define PG8_BAR __builtin_amdgcn_s_barrier()
; #define PG8_SCHED __builtin_amdgcn_sched_barrier(0)
; template <class Epi, class Sched, bool ALIGN_EPI = false, bool SP2 = false>
; __device__ __forceinline__ void gemm_phase(PG8_LAS unsigned char* lds, const Gemm g, const Sched& S, const Epi& E) {
;     ...
;             PG8_LDB(B0, 0, 0); PG8_LDB(B1, 0, 1); PG8_SCHED; PG8_LDA(At, 0, 0); PG8_STAGE(PG8_SA(1, 1), a1 + hstepA, voffA);
;             PG8_WAIT_V(8); PG8_WAIT_L(0); PG8_BAR; PG8_MMA(0, 0, At, B0); PG8_MMA(0, 1, At, B1); PG8_BAR; PG8_SCHED;
;             PG8_LDA(At, 0, 1); PG8_STAGE(PG8_SB(0, 0), b2, voffB); PG8_STAGE(PG8_SB(0, 1), b2 + hstepB, voffB); PG8_STAGE(PG8_SA(0, 0), a2, voffA);
;             PG8_WAIT_V(8); PG8_WAIT_L(0); PG8_BAR; PG8_MMA(1, 0, At, B0); PG8_MMA(1, 1, At, B1); PG8_BAR; PG8_SCHED;
.LBB0_530:
	s_add_u32 s12, s1, s8
	s_addc_u32 s13, s28, s9
	s_add_u32 s12, s12, 0xfe00100
	s_addc_u32 s13, s13, 0
	s_add_u32 s34, s29, s8
	s_addc_u32 s35, s30, s9
	s_add_i32 s36, 0, 0x10000
	s_cmpk_eq_i32 s8, 0x700
	s_cselect_b32 s15, s7, s13
	s_cselect_b32 s14, s6, s12
	v_add_u32_e32 v145, s36, v143
	s_cselect_b32 s13, s5, s35
	s_cselect_b32 s12, s4, s34
	s_add_i32 s37, 0, 0x14000
	ds_read_b128 v[146:149], v145
	ds_read_b128 v[150:153], v145 offset:1024
	ds_read_b128 v[154:157], v145 offset:2048
	ds_read_b128 v[158:161], v145 offset:3072
	v_add_u32_e32 v145, s37, v143
	ds_read_b128 v[162:165], v145
	ds_read_b128 v[166:169], v145 offset:1024
	ds_read_b128 v[170:173], v145 offset:2048
	ds_read_b128 v[174:177], v145 offset:3072
	v_lshl_add_u64 v[186:187], v[138:139], 0, s[8:9]
	s_add_i32 m0, s21, 0xc000
	ds_read_b128 v[178:181], v144
	ds_read_b128 v[182:185], v144 offset:1024
	ds_read_b128 v[202:205], v144 offset:2048
	ds_read_b128 v[206:209], v144 offset:3072
	ds_read_b128 v[210:213], v144 offset:4096
	ds_read_b128 v[232:235], v144 offset:5120
	ds_read_b128 v[236:239], v144 offset:6144
	ds_read_b128 v[240:243], v144 offset:7168
	global_load_lds_dwordx4 v[186:187], off
	v_lshl_add_u64 v[186:187], v[140:141], 0, s[8:9]
	s_add_i32 m0, s21, 0xe000
	s_nop 0
	global_load_lds_dwordx4 v[186:187], off
	s_waitcnt vmcnt(8)
	s_waitcnt lgkmcnt(0)
	s_barrier
	s_setprio 1
	s_waitcnt lgkmcnt(0)
	v_mfma_f32_16x16x32_bf16 v[126:129], v[146:149], v[178:181], v[126:129]
	v_mfma_f32_16x16x32_bf16 v[122:125], v[154:157], v[178:181], v[122:125]
	v_mfma_f32_16x16x32_bf16 v[118:121], v[146:149], v[202:205], v[118:121]
	v_mfma_f32_16x16x32_bf16 v[114:117], v[154:157], v[202:205], v[114:117]
	v_mfma_f32_16x16x32_bf16 v[110:113], v[146:149], v[210:213], v[110:113]
	v_mfma_f32_16x16x32_bf16 v[106:109], v[154:157], v[210:213], v[106:109]
	v_mfma_f32_16x16x32_bf16 v[102:105], v[146:149], v[236:239], v[102:105]
	v_mfma_f32_16x16x32_bf16 v[98:101], v[154:157], v[236:239], v[98:101]
	v_mfma_f32_16x16x32_bf16 v[126:129], v[150:153], v[182:185], v[126:129]
	v_mfma_f32_16x16x32_bf16 v[122:125], v[158:161], v[182:185], v[122:125]
	v_mfma_f32_16x16x32_bf16 v[118:121], v[150:153], v[206:209], v[118:121]
	v_mfma_f32_16x16x32_bf16 v[114:117], v[158:161], v[206:209], v[114:117]
	v_mfma_f32_16x16x32_bf16 v[110:113], v[150:153], v[232:235], v[110:113]
	v_mfma_f32_16x16x32_bf16 v[106:109], v[158:161], v[232:235], v[106:109]
	v_mfma_f32_16x16x32_bf16 v[102:105], v[150:153], v[240:243], v[102:105]
	v_mfma_f32_16x16x32_bf16 v[98:101], v[158:161], v[240:243], v[98:101]
	s_setprio 0
	s_setprio 1
	v_mfma_f32_16x16x32_bf16 v[94:97], v[162:165], v[178:181], v[94:97]
	v_mfma_f32_16x16x32_bf16 v[86:89], v[170:173], v[178:181], v[86:89]
	v_mfma_f32_16x16x32_bf16 v[78:81], v[162:165], v[202:205], v[78:81]
	v_mfma_f32_16x16x32_bf16 v[74:77], v[170:173], v[202:205], v[74:77]
	v_mfma_f32_16x16x32_bf16 v[70:73], v[162:165], v[210:213], v[70:73]
	v_mfma_f32_16x16x32_bf16 v[62:65], v[170:173], v[210:213], v[62:65]
	v_mfma_f32_16x16x32_bf16 v[54:57], v[162:165], v[236:239], v[54:57]
	v_mfma_f32_16x16x32_bf16 v[50:53], v[170:173], v[236:239], v[50:53]
	v_mfma_f32_16x16x32_bf16 v[94:97], v[166:169], v[182:185], v[94:97]
	v_mfma_f32_16x16x32_bf16 v[86:89], v[174:177], v[182:185], v[86:89]
	v_mfma_f32_16x16x32_bf16 v[78:81], v[166:169], v[206:209], v[78:81]
	v_mfma_f32_16x16x32_bf16 v[74:77], v[174:177], v[206:209], v[74:77]
	v_mfma_f32_16x16x32_bf16 v[70:73], v[166:169], v[232:235], v[70:73]
	v_mfma_f32_16x16x32_bf16 v[62:65], v[174:177], v[232:235], v[62:65]
	v_mfma_f32_16x16x32_bf16 v[54:57], v[166:169], v[240:243], v[54:57]
	v_mfma_f32_16x16x32_bf16 v[50:53], v[174:177], v[240:243], v[50:53]
	s_setprio 0
	s_barrier
	s_add_i32 s34, s36, s20
	v_lshl_add_u64 v[186:187], s[12:13], 0, v[134:135]
	s_mov_b32 m0, s34
	ds_read_b128 v[178:181], v144 offset:16384
	ds_read_b128 v[182:185], v144 offset:17408
	ds_read_b128 v[202:205], v144 offset:18432
	ds_read_b128 v[206:209], v144 offset:19456
	ds_read_b128 v[210:213], v144 offset:20480
	ds_read_b128 v[232:235], v144 offset:21504
	ds_read_b128 v[236:239], v144 offset:22528
	ds_read_b128 v[240:243], v144 offset:23552
	global_load_lds_dwordx4 v[186:187], off
	s_add_i32 m0, s34, 0x2000
	s_add_u32 s34, s12, 0x80000
	v_lshl_add_u64 v[214:215], s[12:13], 0, v[130:131]
	s_addc_u32 s35, s13, 0
	s_add_i32 s36, s37, s20
	global_load_lds_dwordx4 v[214:215], off
	s_mov_b32 m0, s36
	v_lshl_add_u64 v[246:247], s[14:15], 0, v[132:133]
	global_load_lds_dwordx4 v134, s[34:35]
	s_add_i32 m0, s36, 0x2000
	s_nop 0
	global_load_lds_dwordx4 v130, s[34:35]
	v_lshl_add_u64 v[244:245], s[14:15], 0, v[136:137]
	s_mov_b32 m0, s21
	s_nop 0
	global_load_lds_dwordx4 v[244:245], off
	s_mov_b32 m0, s22
	s_nop 0
	global_load_lds_dwordx4 v[246:247], off
	s_waitcnt vmcnt(8)
	s_waitcnt lgkmcnt(0)
	s_barrier
; #define PG8_STAGE(bufoff, gbase, voff) do { _Pragma("unroll") for (int _i = 0; _i < 2; ++_i) \
;         __builtin_amdgcn_global_load_lds((const unsigned*)((const char*)(gbase) + (voff)[_i]), (PG8_LAS unsigned*)(lds + (bufoff) + ldsw + _i * 8192), 16, 0, 0); } while (0)
; #define PG8_LDA(dst, b, h) do { _Pragma("unroll") for (int m = 0; m < 4; ++m) _Pragma("unroll") for (int k = 0; k < 2; ++k) dst[m][k] = *(const PG8_LAS bf16x8*)(lds + PG8_SA(b, h) + aoff + m * 2048 + k * 1024); } while (0)
; #define PG8_LDB(dst, b, h) do { _Pragma("unroll") for (int n = 0; n < 2; ++n) _Pragma("unroll") for (int k = 0; k < 2; ++k) dst[n][k] = *(const PG8_LAS bf16x8*)(lds + PG8_SB(b, h) + boff + n * 2048 + k * 1024); } while (0)
; #define PG8_MMA(ai, bj, At, Bt) do { __builtin_amdgcn_s_setprio(1); _Pragma("unroll") for (int m = 0; m < 4; ++m) _Pragma("unroll") for (int n = 0; n < 2; ++n) _Pragma("unroll") for (int k = 0; k < 2; ++k) \
;         acc[ai][bj][m][n] = __builtin_amdgcn_mfma_f32_16x16x32_bf16(Bt[n][k], At[m][k], acc[ai][bj][m][n], 0, 0, 0); __builtin_amdgcn_s_setprio(0); } while (0)
; #define PG8_WAIT_V(n) asm volatile("s_waitcnt vmcnt(" #n ")" ::: "memory")
; #define PG8_WAIT_L(n) asm volatile("s_waitcnt lgkmcnt(" #n ")" ::: "memory")
; #define PG8_BAR __builtin_amdgcn_s_barrier()
; #define PG8_SCHED __builtin_amdgcn_sched_barrier(0)
; template <class Epi, class Sched, bool ALIGN_EPI = false, bool SP2 = false>
; __device__ __forceinline__ void gemm_phase(PG8_LAS unsigned char* lds, const Gemm g, const Sched& S, const Epi& E) {
;     ...
;             PG8_WAIT_V(8); PG8_WAIT_L(0); PG8_BAR; PG8_MMA(1, 0, At, B0); PG8_MMA(1, 1, At, B1); PG8_BAR; PG8_SCHED;
;             PG8_LDB(B0, 1, 0); PG8_LDB(B1, 1, 1); PG8_SCHED; PG8_LDA(At, 1, 0); PG8_STAGE(PG8_SA(0, 1), a2 + hstepA, voffA);
;             PG8_WAIT_V(8); PG8_WAIT_L(0); PG8_BAR; PG8_MMA(0, 0, At, B0); PG8_MMA(0, 1, At, B1); PG8_BAR; PG8_SCHED;
	s_setprio 1
	s_waitcnt lgkmcnt(0)
	v_mfma_f32_16x16x32_bf16 v[90:93], v[146:149], v[178:181], v[90:93]
	v_mfma_f32_16x16x32_bf16 v[82:85], v[154:157], v[178:181], v[82:85]
	v_mfma_f32_16x16x32_bf16 v[66:69], v[146:149], v[202:205], v[66:69]
	v_mfma_f32_16x16x32_bf16 v[58:61], v[154:157], v[202:205], v[58:61]
	v_mfma_f32_16x16x32_bf16 v[46:49], v[146:149], v[210:213], v[46:49]
	v_mfma_f32_16x16x32_bf16 v[42:45], v[154:157], v[210:213], v[42:45]
	v_mfma_f32_16x16x32_bf16 v[38:41], v[146:149], v[236:239], v[38:41]
	v_mfma_f32_16x16x32_bf16 v[34:37], v[154:157], v[236:239], v[34:37]
	v_mfma_f32_16x16x32_bf16 v[90:93], v[150:153], v[182:185], v[90:93]
	v_mfma_f32_16x16x32_bf16 v[82:85], v[158:161], v[182:185], v[82:85]
	v_mfma_f32_16x16x32_bf16 v[66:69], v[150:153], v[206:209], v[66:69]
	v_mfma_f32_16x16x32_bf16 v[58:61], v[158:161], v[206:209], v[58:61]
	v_mfma_f32_16x16x32_bf16 v[46:49], v[150:153], v[232:235], v[46:49]
	v_mfma_f32_16x16x32_bf16 v[42:45], v[158:161], v[232:235], v[42:45]
	v_mfma_f32_16x16x32_bf16 v[38:41], v[150:153], v[240:243], v[38:41]
	v_mfma_f32_16x16x32_bf16 v[34:37], v[158:161], v[240:243], v[34:37]
	s_setprio 0
	s_setprio 1
	v_mfma_f32_16x16x32_bf16 v[30:33], v[162:165], v[178:181], v[30:33]
	v_mfma_f32_16x16x32_bf16 v[26:29], v[170:173], v[178:181], v[26:29]
	v_mfma_f32_16x16x32_bf16 v[22:25], v[162:165], v[202:205], v[22:25]
	v_mfma_f32_16x16x32_bf16 v[18:21], v[170:173], v[202:205], v[18:21]
	v_mfma_f32_16x16x32_bf16 v[14:17], v[162:165], v[210:213], v[14:17]
	v_mfma_f32_16x16x32_bf16 v[10:13], v[170:173], v[210:213], v[10:13]
	v_mfma_f32_16x16x32_bf16 v[6:9], v[162:165], v[236:239], v[6:9]
	v_mfma_f32_16x16x32_bf16 v[2:5], v[170:173], v[236:239], v[2:5]
	v_mfma_f32_16x16x32_bf16 v[30:33], v[166:169], v[182:185], v[30:33]
	v_mfma_f32_16x16x32_bf16 v[26:29], v[174:177], v[182:185], v[26:29]
	v_mfma_f32_16x16x32_bf16 v[22:25], v[166:169], v[206:209], v[22:25]
	v_mfma_f32_16x16x32_bf16 v[18:21], v[174:177], v[206:209], v[18:21]
	v_mfma_f32_16x16x32_bf16 v[14:17], v[166:169], v[232:235], v[14:17]
	v_mfma_f32_16x16x32_bf16 v[10:13], v[174:177], v[232:235], v[10:13]
	v_mfma_f32_16x16x32_bf16 v[6:9], v[166:169], v[240:243], v[6:9]
	v_mfma_f32_16x16x32_bf16 v[2:5], v[174:177], v[240:243], v[2:5]
	s_setprio 0
	s_barrier
	s_add_i32 s34, 0, 0x18000
	v_add_u32_e32 v145, s34, v143
	s_add_i32 s35, 0, 0x1c000
	ds_read_b128 v[146:149], v145
	ds_read_b128 v[150:153], v145 offset:1024
	ds_read_b128 v[154:157], v145 offset:2048
	ds_read_b128 v[158:161], v145 offset:3072
	v_add_u32_e32 v145, s35, v143
	ds_read_b128 v[162:165], v145
	ds_read_b128 v[166:169], v145 offset:1024
	ds_read_b128 v[170:173], v145 offset:2048
	ds_read_b128 v[174:177], v145 offset:3072
	s_add_u32 s14, s14, 0x40000
	s_addc_u32 s15, s15, 0
	s_mov_b32 m0, s23
	ds_read_b128 v[178:181], v144 offset:32768
	ds_read_b128 v[182:185], v144 offset:33792
	ds_read_b128 v[202:205], v144 offset:34816
	ds_read_b128 v[206:209], v144 offset:35840
	ds_read_b128 v[210:213], v144 offset:36864
	ds_read_b128 v[232:235], v144 offset:37888
	ds_read_b128 v[236:239], v144 offset:38912
	ds_read_b128 v[240:243], v144 offset:39936
	global_load_lds_dwordx4 v136, s[14:15]
	s_mov_b32 m0, s24
	s_nop 0
	global_load_lds_dwordx4 v132, s[14:15]
	s_waitcnt vmcnt(8)
	s_waitcnt lgkmcnt(0)
	s_barrier
	s_setprio 1
	s_waitcnt lgkmcnt(0)
	v_mfma_f32_16x16x32_bf16 v[126:129], v[146:149], v[178:181], v[126:129]
	v_mfma_f32_16x16x32_bf16 v[122:125], v[154:157], v[178:181], v[122:125]
	v_mfma_f32_16x16x32_bf16 v[118:121], v[146:149], v[202:205], v[118:121]
	v_mfma_f32_16x16x32_bf16 v[114:117], v[154:157], v[202:205], v[114:117]
	v_mfma_f32_16x16x32_bf16 v[110:113], v[146:149], v[210:213], v[110:113]
	v_mfma_f32_16x16x32_bf16 v[106:109], v[154:157], v[210:213], v[106:109]
	v_mfma_f32_16x16x32_bf16 v[102:105], v[146:149], v[236:239], v[102:105]
	v_mfma_f32_16x16x32_bf16 v[98:101], v[154:157], v[236:239], v[98:101]
	v_mfma_f32_16x16x32_bf16 v[126:129], v[150:153], v[182:185], v[126:129]
	v_mfma_f32_16x16x32_bf16 v[122:125], v[158:161], v[182:185], v[122:125]
	v_mfma_f32_16x16x32_bf16 v[118:121], v[150:153], v[206:209], v[118:121]
	v_mfma_f32_16x16x32_bf16 v[114:117], v[158:161], v[206:209], v[114:117]
	v_mfma_f32_16x16x32_bf16 v[110:113], v[150:153], v[232:235], v[110:113]
	v_mfma_f32_16x16x32_bf16 v[106:109], v[158:161], v[232:235], v[106:109]
	v_mfma_f32_16x16x32_bf16 v[102:105], v[150:153], v[240:243], v[102:105]
	v_mfma_f32_16x16x32_bf16 v[98:101], v[158:161], v[240:243], v[98:101]
	s_setprio 0
	s_setprio 1
	v_mfma_f32_16x16x32_bf16 v[94:97], v[162:165], v[178:181], v[94:97]
	v_mfma_f32_16x16x32_bf16 v[86:89], v[170:173], v[178:181], v[86:89]
	v_mfma_f32_16x16x32_bf16 v[78:81], v[162:165], v[202:205], v[78:81]
	v_mfma_f32_16x16x32_bf16 v[74:77], v[170:173], v[202:205], v[74:77]
	v_mfma_f32_16x16x32_bf16 v[70:73], v[162:165], v[210:213], v[70:73]
	v_mfma_f32_16x16x32_bf16 v[62:65], v[170:173], v[210:213], v[62:65]
	v_mfma_f32_16x16x32_bf16 v[54:57], v[162:165], v[236:239], v[54:57]
	v_mfma_f32_16x16x32_bf16 v[50:53], v[170:173], v[236:239], v[50:53]
	v_mfma_f32_16x16x32_bf16 v[94:97], v[166:169], v[182:185], v[94:97]
	v_mfma_f32_16x16x32_bf16 v[86:89], v[174:177], v[182:185], v[86:89]
	v_mfma_f32_16x16x32_bf16 v[78:81], v[166:169], v[206:209], v[78:81]
	v_mfma_f32_16x16x32_bf16 v[74:77], v[174:177], v[206:209], v[74:77]
	v_mfma_f32_16x16x32_bf16 v[70:73], v[166:169], v[232:235], v[70:73]
	v_mfma_f32_16x16x32_bf16 v[62:65], v[174:177], v[232:235], v[62:65]
	v_mfma_f32_16x16x32_bf16 v[54:57], v[166:169], v[240:243], v[54:57]
	v_mfma_f32_16x16x32_bf16 v[50:53], v[174:177], v[240:243], v[50:53]
	s_setprio 0
	s_barrier
; #define PG8_STAGE(bufoff, gbase, voff) do { _Pragma("unroll") for (int _i = 0; _i < 2; ++_i) \
;         __builtin_amdgcn_global_load_lds((const unsigned*)((const char*)(gbase) + (voff)[_i]), (PG8_LAS unsigned*)(lds + (bufoff) + ldsw + _i * 8192), 16, 0, 0); } while (0)
; #define PG8_LDA(dst, b, h) do { _Pragma("unroll") for (int m = 0; m < 4; ++m) _Pragma("unroll") for (int k = 0; k < 2; ++k) dst[m][k] = *(const PG8_LAS bf16x8*)(lds + PG8_SA(b, h) + aoff + m * 2048 + k * 1024); } while (0)
; #define PG8_MMA(ai, bj, At, Bt) do { __builtin_amdgcn_s_setprio(1); _Pragma("unroll") for (int m = 0; m < 4; ++m) _Pragma("unroll") for (int n = 0; n < 2; ++n) _Pragma("unroll") for (int k = 0; k < 2; ++k) \
;         acc[ai][bj][m][n] = __builtin_amdgcn_mfma_f32_16x16x32_bf16(Bt[n][k], At[m][k], acc[ai][bj][m][n], 0, 0, 0); __builtin_amdgcn_s_setprio(0); } while (0)
; #define PG8_WAIT_V(n) asm volatile("s_waitcnt vmcnt(" #n ")" ::: "memory")
; #define PG8_WAIT_L(n) asm volatile("s_waitcnt lgkmcnt(" #n ")" ::: "memory")
; #define PG8_BAR __builtin_amdgcn_s_barrier()
; #define PG8_SCHED __builtin_amdgcn_sched_barrier(0)
; template <class Epi, class Sched, bool ALIGN_EPI = false, bool SP2 = false>
; __device__ __forceinline__ void gemm_phase(PG8_LAS unsigned char* lds, const Gemm g, const Sched& S, const Epi& E) {
;     ...
;         for (int t = 0; t < nt; t += 2) {
;     ...
;             PG8_LDA(At, 1, 1); PG8_STAGE(PG8_SB(1, 0), b3, voffB); PG8_STAGE(PG8_SB(1, 1), b3 + hstepB, voffB); PG8_STAGE(PG8_SA(1, 0), a3, voffA);
;             PG8_WAIT_V(8); PG8_WAIT_L(0); PG8_BAR; PG8_MMA(1, 0, At, B0); PG8_MMA(1, 1, At, B1); PG8_BAR; PG8_SCHED;
	s_add_i32 s14, s34, s20
	v_lshl_add_u64 v[186:187], v[186:187], 0, s[96:97]
	s_mov_b32 m0, s14
	ds_read_b128 v[178:181], v144 offset:49152
	ds_read_b128 v[182:185], v144 offset:50176
	ds_read_b128 v[202:205], v144 offset:51200
	ds_read_b128 v[206:209], v144 offset:52224
	ds_read_b128 v[210:213], v144 offset:53248
	ds_read_b128 v[232:235], v144 offset:54272
	ds_read_b128 v[236:239], v144 offset:55296
	ds_read_b128 v[240:243], v144 offset:56320
	global_load_lds_dwordx4 v[186:187], off
	s_add_i32 m0, s14, 0x2000
	s_add_u32 s12, s12, 0x80080
	v_lshl_add_u64 v[186:187], v[214:215], 0, s[96:97]
	s_addc_u32 s13, s13, 0
	s_add_i32 s14, s35, s20
	global_load_lds_dwordx4 v[186:187], off
	s_mov_b32 m0, s14
	s_nop 0
	global_load_lds_dwordx4 v134, s[12:13]
	s_add_i32 m0, s14, 0x2000
	s_nop 0
	global_load_lds_dwordx4 v130, s[12:13]
	v_lshl_add_u64 v[186:187], v[244:245], 0, s[96:97]
	s_mov_b32 m0, s26
	s_nop 0
	global_load_lds_dwordx4 v[186:187], off
	v_lshl_add_u64 v[186:187], v[246:247], 0, s[96:97]
	s_mov_b32 m0, s27
	s_nop 0
	global_load_lds_dwordx4 v[186:187], off
	s_waitcnt vmcnt(8)
	s_waitcnt lgkmcnt(0)
	s_barrier
	s_setprio 1
	s_waitcnt lgkmcnt(0)
	v_mfma_f32_16x16x32_bf16 v[90:93], v[146:149], v[178:181], v[90:93]
	v_mfma_f32_16x16x32_bf16 v[82:85], v[154:157], v[178:181], v[82:85]
	v_mfma_f32_16x16x32_bf16 v[66:69], v[146:149], v[202:205], v[66:69]
	v_mfma_f32_16x16x32_bf16 v[58:61], v[154:157], v[202:205], v[58:61]
	v_mfma_f32_16x16x32_bf16 v[46:49], v[146:149], v[210:213], v[46:49]
	v_mfma_f32_16x16x32_bf16 v[42:45], v[154:157], v[210:213], v[42:45]
	v_mfma_f32_16x16x32_bf16 v[38:41], v[146:149], v[236:239], v[38:41]
	v_mfma_f32_16x16x32_bf16 v[34:37], v[154:157], v[236:239], v[34:37]
	v_mfma_f32_16x16x32_bf16 v[90:93], v[150:153], v[182:185], v[90:93]
	v_mfma_f32_16x16x32_bf16 v[82:85], v[158:161], v[182:185], v[82:85]
	v_mfma_f32_16x16x32_bf16 v[66:69], v[150:153], v[206:209], v[66:69]
	v_mfma_f32_16x16x32_bf16 v[58:61], v[158:161], v[206:209], v[58:61]
	v_mfma_f32_16x16x32_bf16 v[46:49], v[150:153], v[232:235], v[46:49]
	v_mfma_f32_16x16x32_bf16 v[42:45], v[158:161], v[232:235], v[42:45]
	v_mfma_f32_16x16x32_bf16 v[38:41], v[150:153], v[240:243], v[38:41]
	v_mfma_f32_16x16x32_bf16 v[34:37], v[158:161], v[240:243], v[34:37]
	s_setprio 0
	s_setprio 1
	v_mfma_f32_16x16x32_bf16 v[30:33], v[162:165], v[178:181], v[30:33]
	v_mfma_f32_16x16x32_bf16 v[26:29], v[170:173], v[178:181], v[26:29]
	v_mfma_f32_16x16x32_bf16 v[22:25], v[162:165], v[202:205], v[22:25]
	v_mfma_f32_16x16x32_bf16 v[18:21], v[170:173], v[202:205], v[18:21]
	v_mfma_f32_16x16x32_bf16 v[14:17], v[162:165], v[210:213], v[14:17]
	v_mfma_f32_16x16x32_bf16 v[10:13], v[170:173], v[210:213], v[10:13]
	v_mfma_f32_16x16x32_bf16 v[6:9], v[162:165], v[236:239], v[6:9]
	v_mfma_f32_16x16x32_bf16 v[2:5], v[170:173], v[236:239], v[2:5]
	v_mfma_f32_16x16x32_bf16 v[30:33], v[166:169], v[182:185], v[30:33]
	v_mfma_f32_16x16x32_bf16 v[26:29], v[174:177], v[182:185], v[26:29]
	v_mfma_f32_16x16x32_bf16 v[22:25], v[166:169], v[206:209], v[22:25]
	v_mfma_f32_16x16x32_bf16 v[18:21], v[174:177], v[206:209], v[18:21]
	v_mfma_f32_16x16x32_bf16 v[14:17], v[166:169], v[232:235], v[14:17]
	v_mfma_f32_16x16x32_bf16 v[10:13], v[174:177], v[232:235], v[10:13]
	v_mfma_f32_16x16x32_bf16 v[6:9], v[166:169], v[240:243], v[6:9]
	v_mfma_f32_16x16x32_bf16 v[2:5], v[174:177], v[240:243], v[2:5]
	s_setprio 0
	s_barrier
	s_add_i32 s31, s31, 2
	s_add_u32 s8, s8, 0x100
	s_addc_u32 s9, s9, 0
	s_cmp_gt_u32 s31, 13
	s_cbranch_scc0 .LBB0_530
	s_cmpk_lt_u32 s19, 0x100
	s_cbranch_scc0 .LBB0_533
	s_barrier

; #define PG8_STAGE(bufoff, gbase, voff) do { _Pragma("unroll") for (int _i = 0; _i < 2; ++_i) \
;         __builtin_amdgcn_global_load_lds((const unsigned*)((const char*)(gbase) + (voff)[_i]), (PG8_LAS unsigned*)(lds + (bufoff) + ldsw + _i * 8192), 16, 0, 0); } while (0)
; #define PG8_LDA(dst, b, h) do { _Pragma("unroll") for (int m = 0; m < 4; ++m) _Pragma("unroll") for (int k = 0; k < 2; ++k) dst[m][k] = *(const PG8_LAS bf16x8*)(lds + PG8_SA(b, h) + aoff + m * 2048 + k * 1024); } while (0)
; #define PG8_LDB(dst, b, h) do { _Pragma("unroll") for (int n = 0; n < 2; ++n) _Pragma("unroll") for (int k = 0; k < 2; ++k) dst[n][k] = *(const PG8_LAS bf16x8*)(lds + PG8_SB(b, h) + boff + n * 2048 + k * 1024); } while (0)
; #define PG8_MMA(ai, bj, At, Bt) do { __builtin_amdgcn_s_setprio(1); _Pragma("unroll") for (int m = 0; m < 4; ++m) _Pragma("unroll") for (int n = 0; n < 2; ++n) _Pragma("unroll") for (int k = 0; k < 2; ++k) \
;         acc[ai][bj][m][n] = __builtin_amdgcn_mfma_f32_16x16x32_bf16(Bt[n][k], At[m][k], acc[ai][bj][m][n], 0, 0, 0); __builtin_amdgcn_s_setprio(0); } while (0)
; #define PG8_WAIT_V(n) asm volatile("s_waitcnt vmcnt(" #n ")" ::: "memory")
; #define PG8_WAIT_L(n) asm volatile("s_waitcnt lgkmcnt(" #n ")" ::: "memory")
; #define PG8_BAR __builtin_amdgcn_s_barrier()
; #define PG8_SCHED __builtin_amdgcn_sched_barrier(0)
; template <class Epi, class Sched, bool ALIGN_EPI = false, bool SP2 = false>
; __device__ __forceinline__ void gemm_phase(PG8_LAS unsigned char* lds, const Gemm g, const Sched& S, const Epi& E) {
;     ...
;             PG8_LDB(B0, 0, 0); PG8_LDB(B1, 0, 1); PG8_SCHED; PG8_LDA(At, 0, 0); PG8_STAGE(PG8_SA(1, 1), a1 + hstepA, voffA);
;             PG8_WAIT_V(8); PG8_WAIT_L(0); PG8_BAR; PG8_MMA(0, 0, At, B0); PG8_MMA(0, 1, At, B1); PG8_BAR; PG8_SCHED;
;             PG8_LDA(At, 0, 1); PG8_STAGE(PG8_SB(0, 0), b2, voffB); PG8_STAGE(PG8_SB(0, 1), b2 + hstepB, voffB); PG8_STAGE(PG8_SA(0, 0), a2, voffA);
;             PG8_WAIT_V(8); PG8_WAIT_L(0); PG8_BAR; PG8_MMA(1, 0, At, B0); PG8_MMA(1, 1, At, B1); PG8_BAR; PG8_SCHED;
.LBB0_1160:
	s_add_u32 s24, s22, 0x100
	s_addc_u32 s25, s23, 0
	s_add_i32 s57, 0, 0x10000
	s_cmp_eq_u32 s56, 4
	s_cselect_b32 s29, s17, s25
	s_cselect_b32 s28, s16, s24
	v_add_u32_e32 v145, s57, v142
	s_cselect_b32 s27, s52, s55
	s_cselect_b32 s26, s53, s54
	s_add_i32 s58, 0, 0x14000
	ds_read_b128 v[146:149], v145
	ds_read_b128 v[150:153], v145 offset:1024
	ds_read_b128 v[154:157], v145 offset:2048
	ds_read_b128 v[158:161], v145 offset:3072
	v_add_u32_e32 v145, s58, v142
	ds_read_b128 v[162:165], v145
	ds_read_b128 v[166:169], v145 offset:1024
	ds_read_b128 v[170:173], v145 offset:2048
	ds_read_b128 v[174:177], v145 offset:3072
	s_add_i32 m0, s39, 0xc000
	ds_read_b128 v[178:181], v143
	ds_read_b128 v[182:185], v143 offset:1024
	ds_read_b128 v[202:205], v143 offset:2048
	ds_read_b128 v[206:209], v143 offset:3072
	ds_read_b128 v[210:213], v143 offset:4096
	ds_read_b128 v[232:235], v143 offset:5120
	ds_read_b128 v[236:239], v143 offset:6144
	ds_read_b128 v[240:243], v143 offset:7168
	global_load_lds_dwordx4 v138, s[22:23]
	s_add_i32 m0, s39, 0xe000
	s_nop 0
	global_load_lds_dwordx4 v140, s[22:23]
	s_waitcnt vmcnt(8)
	s_waitcnt lgkmcnt(0)
	s_barrier
	s_setprio 1
	s_waitcnt lgkmcnt(0)
	v_mfma_f32_16x16x32_bf16 v[126:129], v[146:149], v[178:181], v[126:129]
	v_mfma_f32_16x16x32_bf16 v[122:125], v[154:157], v[178:181], v[122:125]
	v_mfma_f32_16x16x32_bf16 v[118:121], v[146:149], v[202:205], v[118:121]
	v_mfma_f32_16x16x32_bf16 v[114:117], v[154:157], v[202:205], v[114:117]
	v_mfma_f32_16x16x32_bf16 v[110:113], v[146:149], v[210:213], v[110:113]
	v_mfma_f32_16x16x32_bf16 v[106:109], v[154:157], v[210:213], v[106:109]
	v_mfma_f32_16x16x32_bf16 v[102:105], v[146:149], v[236:239], v[102:105]
	v_mfma_f32_16x16x32_bf16 v[98:101], v[154:157], v[236:239], v[98:101]
	v_mfma_f32_16x16x32_bf16 v[126:129], v[150:153], v[182:185], v[126:129]
	v_mfma_f32_16x16x32_bf16 v[122:125], v[158:161], v[182:185], v[122:125]
	v_mfma_f32_16x16x32_bf16 v[118:121], v[150:153], v[206:209], v[118:121]
	v_mfma_f32_16x16x32_bf16 v[114:117], v[158:161], v[206:209], v[114:117]
	v_mfma_f32_16x16x32_bf16 v[110:113], v[150:153], v[232:235], v[110:113]
	v_mfma_f32_16x16x32_bf16 v[106:109], v[158:161], v[232:235], v[106:109]
	v_mfma_f32_16x16x32_bf16 v[102:105], v[150:153], v[240:243], v[102:105]
	v_mfma_f32_16x16x32_bf16 v[98:101], v[158:161], v[240:243], v[98:101]
	s_setprio 0
	s_setprio 1
	v_mfma_f32_16x16x32_bf16 v[78:81], v[162:165], v[178:181], v[78:81]
	v_mfma_f32_16x16x32_bf16 v[70:73], v[170:173], v[178:181], v[70:73]
	v_mfma_f32_16x16x32_bf16 v[62:65], v[162:165], v[202:205], v[62:65]
	v_mfma_f32_16x16x32_bf16 v[54:57], v[170:173], v[202:205], v[54:57]
	v_mfma_f32_16x16x32_bf16 v[46:49], v[162:165], v[210:213], v[46:49]
	v_mfma_f32_16x16x32_bf16 v[42:45], v[170:173], v[210:213], v[42:45]
	v_mfma_f32_16x16x32_bf16 v[38:41], v[162:165], v[236:239], v[38:41]
	v_mfma_f32_16x16x32_bf16 v[34:37], v[170:173], v[236:239], v[34:37]
	v_mfma_f32_16x16x32_bf16 v[78:81], v[166:169], v[182:185], v[78:81]
	v_mfma_f32_16x16x32_bf16 v[70:73], v[174:177], v[182:185], v[70:73]
	v_mfma_f32_16x16x32_bf16 v[62:65], v[166:169], v[206:209], v[62:65]
	v_mfma_f32_16x16x32_bf16 v[54:57], v[174:177], v[206:209], v[54:57]
	v_mfma_f32_16x16x32_bf16 v[46:49], v[166:169], v[232:235], v[46:49]
	v_mfma_f32_16x16x32_bf16 v[42:45], v[174:177], v[232:235], v[42:45]
	v_mfma_f32_16x16x32_bf16 v[38:41], v[166:169], v[240:243], v[38:41]
	v_mfma_f32_16x16x32_bf16 v[34:37], v[174:177], v[240:243], v[34:37]
	s_setprio 0
	s_barrier
	s_add_i32 s22, s57, s38
	v_lshl_add_u64 v[186:187], s[26:27], 0, v[134:135]
	s_mov_b32 m0, s22
	ds_read_b128 v[178:181], v143 offset:16384
	ds_read_b128 v[182:185], v143 offset:17408
	ds_read_b128 v[202:205], v143 offset:18432
	ds_read_b128 v[206:209], v143 offset:19456
	ds_read_b128 v[210:213], v143 offset:20480
	ds_read_b128 v[232:235], v143 offset:21504
	ds_read_b128 v[236:239], v143 offset:22528
	ds_read_b128 v[240:243], v143 offset:23552
	global_load_lds_dwordx4 v[186:187], off
	s_add_i32 m0, s22, 0x2000
	s_add_u32 s22, s26, 0x20000
	v_lshl_add_u64 v[214:215], s[26:27], 0, v[130:131]
	s_addc_u32 s23, s27, 0
	s_add_i32 s57, s58, s38
	global_load_lds_dwordx4 v[214:215], off
	s_mov_b32 m0, s57
	v_lshl_add_u64 v[246:247], s[28:29], 0, v[132:133]
	global_load_lds_dwordx4 v134, s[22:23]
	s_add_i32 m0, s57, 0x2000
	s_nop 0
	global_load_lds_dwordx4 v130, s[22:23]
	v_lshl_add_u64 v[244:245], s[28:29], 0, v[136:137]
	s_mov_b32 m0, s39
	s_nop 0
	global_load_lds_dwordx4 v[244:245], off
	s_mov_b32 m0, s40
	s_nop 0
	global_load_lds_dwordx4 v[246:247], off
	s_waitcnt vmcnt(8)
	s_waitcnt lgkmcnt(0)
	s_barrier
; #define PG8_STAGE(bufoff, gbase, voff) do { _Pragma("unroll") for (int _i = 0; _i < 2; ++_i) \
;         __builtin_amdgcn_global_load_lds((const unsigned*)((const char*)(gbase) + (voff)[_i]), (PG8_LAS unsigned*)(lds + (bufoff) + ldsw + _i * 8192), 16, 0, 0); } while (0)
; #define PG8_LDA(dst, b, h) do { _Pragma("unroll") for (int m = 0; m < 4; ++m) _Pragma("unroll") for (int k = 0; k < 2; ++k) dst[m][k] = *(const PG8_LAS bf16x8*)(lds + PG8_SA(b, h) + aoff + m * 2048 + k * 1024); } while (0)
; #define PG8_LDB(dst, b, h) do { _Pragma("unroll") for (int n = 0; n < 2; ++n) _Pragma("unroll") for (int k = 0; k < 2; ++k) dst[n][k] = *(const PG8_LAS bf16x8*)(lds + PG8_SB(b, h) + boff + n * 2048 + k * 1024); } while (0)
; #define PG8_MMA(ai, bj, At, Bt) do { __builtin_amdgcn_s_setprio(1); _Pragma("unroll") for (int m = 0; m < 4; ++m) _Pragma("unroll") for (int n = 0; n < 2; ++n) _Pragma("unroll") for (int k = 0; k < 2; ++k) \
;         acc[ai][bj][m][n] = __builtin_amdgcn_mfma_f32_16x16x32_bf16(Bt[n][k], At[m][k], acc[ai][bj][m][n], 0, 0, 0); __builtin_amdgcn_s_setprio(0); } while (0)
; #define PG8_WAIT_V(n) asm volatile("s_waitcnt vmcnt(" #n ")" ::: "memory")
; #define PG8_WAIT_L(n) asm volatile("s_waitcnt lgkmcnt(" #n ")" ::: "memory")
; #define PG8_BAR __builtin_amdgcn_s_barrier()
; #define PG8_SCHED __builtin_amdgcn_sched_barrier(0)
; template <class Epi, class Sched, bool ALIGN_EPI = false, bool SP2 = false>
; __device__ __forceinline__ void gemm_phase(PG8_LAS unsigned char* lds, const Gemm g, const Sched& S, const Epi& E) {
;     ...
;             PG8_WAIT_V(8); PG8_WAIT_L(0); PG8_BAR; PG8_MMA(1, 0, At, B0); PG8_MMA(1, 1, At, B1); PG8_BAR; PG8_SCHED;
;             PG8_LDB(B0, 1, 0); PG8_LDB(B1, 1, 1); PG8_SCHED; PG8_LDA(At, 1, 0); PG8_STAGE(PG8_SA(0, 1), a2 + hstepA, voffA);
;             PG8_WAIT_V(8); PG8_WAIT_L(0); PG8_BAR; PG8_MMA(0, 0, At, B0); PG8_MMA(0, 1, At, B1); PG8_BAR; PG8_SCHED;
	s_setprio 1
	s_waitcnt lgkmcnt(0)
	v_mfma_f32_16x16x32_bf16 v[94:97], v[146:149], v[178:181], v[94:97]
	v_mfma_f32_16x16x32_bf16 v[90:93], v[154:157], v[178:181], v[90:93]
	v_mfma_f32_16x16x32_bf16 v[86:89], v[146:149], v[202:205], v[86:89]
	v_mfma_f32_16x16x32_bf16 v[82:85], v[154:157], v[202:205], v[82:85]
	v_mfma_f32_16x16x32_bf16 v[74:77], v[146:149], v[210:213], v[74:77]
	v_mfma_f32_16x16x32_bf16 v[66:69], v[154:157], v[210:213], v[66:69]
	v_mfma_f32_16x16x32_bf16 v[58:61], v[146:149], v[236:239], v[58:61]
	v_mfma_f32_16x16x32_bf16 v[50:53], v[154:157], v[236:239], v[50:53]
	v_mfma_f32_16x16x32_bf16 v[94:97], v[150:153], v[182:185], v[94:97]
	v_mfma_f32_16x16x32_bf16 v[90:93], v[158:161], v[182:185], v[90:93]
	v_mfma_f32_16x16x32_bf16 v[86:89], v[150:153], v[206:209], v[86:89]
	v_mfma_f32_16x16x32_bf16 v[82:85], v[158:161], v[206:209], v[82:85]
	v_mfma_f32_16x16x32_bf16 v[74:77], v[150:153], v[232:235], v[74:77]
	v_mfma_f32_16x16x32_bf16 v[66:69], v[158:161], v[232:235], v[66:69]
	v_mfma_f32_16x16x32_bf16 v[58:61], v[150:153], v[240:243], v[58:61]
	v_mfma_f32_16x16x32_bf16 v[50:53], v[158:161], v[240:243], v[50:53]
	s_setprio 0
	s_setprio 1
	v_mfma_f32_16x16x32_bf16 v[30:33], v[162:165], v[178:181], v[30:33]
	v_mfma_f32_16x16x32_bf16 v[26:29], v[170:173], v[178:181], v[26:29]
	v_mfma_f32_16x16x32_bf16 v[22:25], v[162:165], v[202:205], v[22:25]
	v_mfma_f32_16x16x32_bf16 v[18:21], v[170:173], v[202:205], v[18:21]
	v_mfma_f32_16x16x32_bf16 v[14:17], v[162:165], v[210:213], v[14:17]
	v_mfma_f32_16x16x32_bf16 v[10:13], v[170:173], v[210:213], v[10:13]
	v_mfma_f32_16x16x32_bf16 v[6:9], v[162:165], v[236:239], v[6:9]
	v_mfma_f32_16x16x32_bf16 v[2:5], v[170:173], v[236:239], v[2:5]
	v_mfma_f32_16x16x32_bf16 v[30:33], v[166:169], v[182:185], v[30:33]
	v_mfma_f32_16x16x32_bf16 v[26:29], v[174:177], v[182:185], v[26:29]
	v_mfma_f32_16x16x32_bf16 v[22:25], v[166:169], v[206:209], v[22:25]
	v_mfma_f32_16x16x32_bf16 v[18:21], v[174:177], v[206:209], v[18:21]
	v_mfma_f32_16x16x32_bf16 v[14:17], v[166:169], v[232:235], v[14:17]
	v_mfma_f32_16x16x32_bf16 v[10:13], v[174:177], v[232:235], v[10:13]
	v_mfma_f32_16x16x32_bf16 v[6:9], v[166:169], v[240:243], v[6:9]
	v_mfma_f32_16x16x32_bf16 v[2:5], v[174:177], v[240:243], v[2:5]
	s_setprio 0
	s_barrier
	s_add_i32 s57, 0, 0x18000
	v_add_u32_e32 v145, s57, v142
	s_add_i32 s58, 0, 0x1c000
	ds_read_b128 v[146:149], v145
	ds_read_b128 v[150:153], v145 offset:1024
	ds_read_b128 v[154:157], v145 offset:2048
	ds_read_b128 v[158:161], v145 offset:3072
	v_add_u32_e32 v145, s58, v142
	ds_read_b128 v[162:165], v145
	ds_read_b128 v[166:169], v145 offset:1024
	ds_read_b128 v[170:173], v145 offset:2048
	ds_read_b128 v[174:177], v145 offset:3072
	s_add_u32 s22, s28, 0x30000
	s_addc_u32 s23, s29, 0
	s_mov_b32 m0, s41
	ds_read_b128 v[178:181], v143 offset:32768
	ds_read_b128 v[182:185], v143 offset:33792
	ds_read_b128 v[202:205], v143 offset:34816
	ds_read_b128 v[206:209], v143 offset:35840
	ds_read_b128 v[210:213], v143 offset:36864
	ds_read_b128 v[232:235], v143 offset:37888
	ds_read_b128 v[236:239], v143 offset:38912
	ds_read_b128 v[240:243], v143 offset:39936
	global_load_lds_dwordx4 v136, s[22:23]
	s_mov_b32 m0, s42
	s_nop 0
	global_load_lds_dwordx4 v132, s[22:23]
	s_waitcnt vmcnt(8)
	s_waitcnt lgkmcnt(0)
	s_barrier
	s_setprio 1
	s_waitcnt lgkmcnt(0)
	v_mfma_f32_16x16x32_bf16 v[126:129], v[146:149], v[178:181], v[126:129]
	v_mfma_f32_16x16x32_bf16 v[122:125], v[154:157], v[178:181], v[122:125]
	v_mfma_f32_16x16x32_bf16 v[118:121], v[146:149], v[202:205], v[118:121]
	v_mfma_f32_16x16x32_bf16 v[114:117], v[154:157], v[202:205], v[114:117]
	v_mfma_f32_16x16x32_bf16 v[110:113], v[146:149], v[210:213], v[110:113]
	v_mfma_f32_16x16x32_bf16 v[106:109], v[154:157], v[210:213], v[106:109]
	v_mfma_f32_16x16x32_bf16 v[102:105], v[146:149], v[236:239], v[102:105]
	v_mfma_f32_16x16x32_bf16 v[98:101], v[154:157], v[236:239], v[98:101]
	v_mfma_f32_16x16x32_bf16 v[126:129], v[150:153], v[182:185], v[126:129]
	v_mfma_f32_16x16x32_bf16 v[122:125], v[158:161], v[182:185], v[122:125]
	v_mfma_f32_16x16x32_bf16 v[118:121], v[150:153], v[206:209], v[118:121]
	v_mfma_f32_16x16x32_bf16 v[114:117], v[158:161], v[206:209], v[114:117]
	v_mfma_f32_16x16x32_bf16 v[110:113], v[150:153], v[232:235], v[110:113]
	v_mfma_f32_16x16x32_bf16 v[106:109], v[158:161], v[232:235], v[106:109]
	v_mfma_f32_16x16x32_bf16 v[102:105], v[150:153], v[240:243], v[102:105]
	v_mfma_f32_16x16x32_bf16 v[98:101], v[158:161], v[240:243], v[98:101]
	s_setprio 0
	s_setprio 1
	v_mfma_f32_16x16x32_bf16 v[78:81], v[162:165], v[178:181], v[78:81]
	v_mfma_f32_16x16x32_bf16 v[70:73], v[170:173], v[178:181], v[70:73]
	v_mfma_f32_16x16x32_bf16 v[62:65], v[162:165], v[202:205], v[62:65]
	v_mfma_f32_16x16x32_bf16 v[54:57], v[170:173], v[202:205], v[54:57]
	v_mfma_f32_16x16x32_bf16 v[46:49], v[162:165], v[210:213], v[46:49]
	v_mfma_f32_16x16x32_bf16 v[42:45], v[170:173], v[210:213], v[42:45]
	v_mfma_f32_16x16x32_bf16 v[38:41], v[162:165], v[236:239], v[38:41]
	v_mfma_f32_16x16x32_bf16 v[34:37], v[170:173], v[236:239], v[34:37]
	v_mfma_f32_16x16x32_bf16 v[78:81], v[166:169], v[182:185], v[78:81]
	v_mfma_f32_16x16x32_bf16 v[70:73], v[174:177], v[182:185], v[70:73]
	v_mfma_f32_16x16x32_bf16 v[62:65], v[166:169], v[206:209], v[62:65]
	v_mfma_f32_16x16x32_bf16 v[54:57], v[174:177], v[206:209], v[54:57]
	v_mfma_f32_16x16x32_bf16 v[46:49], v[166:169], v[232:235], v[46:49]
	v_mfma_f32_16x16x32_bf16 v[42:45], v[174:177], v[232:235], v[42:45]
	v_mfma_f32_16x16x32_bf16 v[38:41], v[166:169], v[240:243], v[38:41]
	v_mfma_f32_16x16x32_bf16 v[34:37], v[174:177], v[240:243], v[34:37]
	s_setprio 0
	s_barrier
; #define PG8_STAGE(bufoff, gbase, voff) do { _Pragma("unroll") for (int _i = 0; _i < 2; ++_i) \
;         __builtin_amdgcn_global_load_lds((const unsigned*)((const char*)(gbase) + (voff)[_i]), (PG8_LAS unsigned*)(lds + (bufoff) + ldsw + _i * 8192), 16, 0, 0); } while (0)
; #define PG8_LDA(dst, b, h) do { _Pragma("unroll") for (int m = 0; m < 4; ++m) _Pragma("unroll") for (int k = 0; k < 2; ++k) dst[m][k] = *(const PG8_LAS bf16x8*)(lds + PG8_SA(b, h) + aoff + m * 2048 + k * 1024); } while (0)
; #define PG8_MMA(ai, bj, At, Bt) do { __builtin_amdgcn_s_setprio(1); _Pragma("unroll") for (int m = 0; m < 4; ++m) _Pragma("unroll") for (int n = 0; n < 2; ++n) _Pragma("unroll") for (int k = 0; k < 2; ++k) \
;         acc[ai][bj][m][n] = __builtin_amdgcn_mfma_f32_16x16x32_bf16(Bt[n][k], At[m][k], acc[ai][bj][m][n], 0, 0, 0); __builtin_amdgcn_s_setprio(0); } while (0)
; #define PG8_WAIT_V(n) asm volatile("s_waitcnt vmcnt(" #n ")" ::: "memory")
; #define PG8_WAIT_L(n) asm volatile("s_waitcnt lgkmcnt(" #n ")" ::: "memory")
; #define PG8_BAR __builtin_amdgcn_s_barrier()
; #define PG8_SCHED __builtin_amdgcn_sched_barrier(0)
; template <class Epi, class Sched, bool ALIGN_EPI = false, bool SP2 = false>
; __device__ __forceinline__ void gemm_phase(PG8_LAS unsigned char* lds, const Gemm g, const Sched& S, const Epi& E) {
;     ...
;         for (int t = 0; t < nt; t += 2) {
;     ...
;             PG8_LDA(At, 1, 1); PG8_STAGE(PG8_SB(1, 0), b3, voffB); PG8_STAGE(PG8_SB(1, 1), b3 + hstepB, voffB); PG8_STAGE(PG8_SA(1, 0), a3, voffA);
;             PG8_WAIT_V(8); PG8_WAIT_L(0); PG8_BAR; PG8_MMA(1, 0, At, B0); PG8_MMA(1, 1, At, B1); PG8_BAR; PG8_SCHED;
	s_add_i32 s22, s57, s38
	v_lshl_add_u64 v[186:187], v[186:187], 0, s[96:97]
	s_mov_b32 m0, s22
	ds_read_b128 v[178:181], v143 offset:49152
	ds_read_b128 v[182:185], v143 offset:50176
	ds_read_b128 v[202:205], v143 offset:51200
	ds_read_b128 v[206:209], v143 offset:52224
	ds_read_b128 v[210:213], v143 offset:53248
	ds_read_b128 v[232:235], v143 offset:54272
	ds_read_b128 v[236:239], v143 offset:55296
	ds_read_b128 v[240:243], v143 offset:56320
	global_load_lds_dwordx4 v[186:187], off
	s_add_i32 m0, s22, 0x2000
	s_add_u32 s22, s26, 0x20080
	v_lshl_add_u64 v[186:187], v[214:215], 0, s[96:97]
	s_addc_u32 s23, s27, 0
	s_add_i32 s26, s58, s38
	global_load_lds_dwordx4 v[186:187], off
	s_mov_b32 m0, s26
	s_nop 0
	global_load_lds_dwordx4 v134, s[22:23]
	s_add_i32 m0, s26, 0x2000
	s_nop 0
	global_load_lds_dwordx4 v130, s[22:23]
	v_lshl_add_u64 v[186:187], v[244:245], 0, s[96:97]
	s_mov_b32 m0, s43
	s_nop 0
	global_load_lds_dwordx4 v[186:187], off
	v_lshl_add_u64 v[186:187], v[246:247], 0, s[96:97]
	s_mov_b32 m0, s46
	s_nop 0
	global_load_lds_dwordx4 v[186:187], off
	s_waitcnt vmcnt(8)
	s_waitcnt lgkmcnt(0)
	s_barrier
	s_setprio 1
	s_waitcnt lgkmcnt(0)
	v_mfma_f32_16x16x32_bf16 v[94:97], v[146:149], v[178:181], v[94:97]
	v_mfma_f32_16x16x32_bf16 v[90:93], v[154:157], v[178:181], v[90:93]
	v_mfma_f32_16x16x32_bf16 v[86:89], v[146:149], v[202:205], v[86:89]
	v_mfma_f32_16x16x32_bf16 v[82:85], v[154:157], v[202:205], v[82:85]
	v_mfma_f32_16x16x32_bf16 v[74:77], v[146:149], v[210:213], v[74:77]
	v_mfma_f32_16x16x32_bf16 v[66:69], v[154:157], v[210:213], v[66:69]
	v_mfma_f32_16x16x32_bf16 v[58:61], v[146:149], v[236:239], v[58:61]
	v_mfma_f32_16x16x32_bf16 v[50:53], v[154:157], v[236:239], v[50:53]
	v_mfma_f32_16x16x32_bf16 v[94:97], v[150:153], v[182:185], v[94:97]
	v_mfma_f32_16x16x32_bf16 v[90:93], v[158:161], v[182:185], v[90:93]
	v_mfma_f32_16x16x32_bf16 v[86:89], v[150:153], v[206:209], v[86:89]
	v_mfma_f32_16x16x32_bf16 v[82:85], v[158:161], v[206:209], v[82:85]
	v_mfma_f32_16x16x32_bf16 v[74:77], v[150:153], v[232:235], v[74:77]
	v_mfma_f32_16x16x32_bf16 v[66:69], v[158:161], v[232:235], v[66:69]
	v_mfma_f32_16x16x32_bf16 v[58:61], v[150:153], v[240:243], v[58:61]
	v_mfma_f32_16x16x32_bf16 v[50:53], v[158:161], v[240:243], v[50:53]
	s_setprio 0
	s_setprio 1
	v_mfma_f32_16x16x32_bf16 v[30:33], v[162:165], v[178:181], v[30:33]
	v_mfma_f32_16x16x32_bf16 v[26:29], v[170:173], v[178:181], v[26:29]
	v_mfma_f32_16x16x32_bf16 v[22:25], v[162:165], v[202:205], v[22:25]
	v_mfma_f32_16x16x32_bf16 v[18:21], v[170:173], v[202:205], v[18:21]
	v_mfma_f32_16x16x32_bf16 v[14:17], v[162:165], v[210:213], v[14:17]
	v_mfma_f32_16x16x32_bf16 v[10:13], v[170:173], v[210:213], v[10:13]
	v_mfma_f32_16x16x32_bf16 v[6:9], v[162:165], v[236:239], v[6:9]
	v_mfma_f32_16x16x32_bf16 v[2:5], v[170:173], v[236:239], v[2:5]
	v_mfma_f32_16x16x32_bf16 v[30:33], v[166:169], v[182:185], v[30:33]
	v_mfma_f32_16x16x32_bf16 v[26:29], v[174:177], v[182:185], v[26:29]
	v_mfma_f32_16x16x32_bf16 v[22:25], v[166:169], v[206:209], v[22:25]
	v_mfma_f32_16x16x32_bf16 v[18:21], v[174:177], v[206:209], v[18:21]
	v_mfma_f32_16x16x32_bf16 v[14:17], v[166:169], v[232:235], v[14:17]
	v_mfma_f32_16x16x32_bf16 v[10:13], v[174:177], v[232:235], v[10:13]
	v_mfma_f32_16x16x32_bf16 v[6:9], v[166:169], v[240:243], v[6:9]
	v_mfma_f32_16x16x32_bf16 v[2:5], v[174:177], v[240:243], v[2:5]
	s_setprio 0
	s_barrier
	s_add_i32 s56, s56, 2
	s_add_u32 s54, s54, 0x100
	s_addc_u32 s55, s55, 0
	s_cmp_gt_u32 s56, 5
	s_mov_b64 s[22:23], s[24:25]
	s_cbranch_scc0 .LBB0_1160
	s_and_b64 vcc, exec, s[8:9]
	s_cbranch_vccz .LBB0_1163
	s_barrier

; #define PG8_STAGE(bufoff, gbase, voff) do { _Pragma("unroll") for (int _i = 0; _i < 2; ++_i) \
;         __builtin_amdgcn_global_load_lds((const unsigned*)((const char*)(gbase) + (voff)[_i]), (PG8_LAS unsigned*)(lds + (bufoff) + ldsw + _i * 8192), 16, 0, 0); } while (0)
; #define PG8_LDA(dst, b, h) do { _Pragma("unroll") for (int m = 0; m < 4; ++m) _Pragma("unroll") for (int k = 0; k < 2; ++k) dst[m][k] = *(const PG8_LAS bf16x8*)(lds + PG8_SA(b, h) + aoff + m * 2048 + k * 1024); } while (0)
; #define PG8_LDB(dst, b, h) do { _Pragma("unroll") for (int n = 0; n < 2; ++n) _Pragma("unroll") for (int k = 0; k < 2; ++k) dst[n][k] = *(const PG8_LAS bf16x8*)(lds + PG8_SB(b, h) + boff + n * 2048 + k * 1024); } while (0)
; #define PG8_MMA(ai, bj, At, Bt) do { __builtin_amdgcn_s_setprio(1); _Pragma("unroll") for (int m = 0; m < 4; ++m) _Pragma("unroll") for (int n = 0; n < 2; ++n) _Pragma("unroll") for (int k = 0; k < 2; ++k) \
;         acc[ai][bj][m][n] = __builtin_amdgcn_mfma_f32_16x16x32_bf16(Bt[n][k], At[m][k], acc[ai][bj][m][n], 0, 0, 0); __builtin_amdgcn_s_setprio(0); } while (0)
; #define PG8_WAIT_V(n) asm volatile("s_waitcnt vmcnt(" #n ")" ::: "memory")
; #define PG8_WAIT_L(n) asm volatile("s_waitcnt lgkmcnt(" #n ")" ::: "memory")
; #define PG8_BAR __builtin_amdgcn_s_barrier()
; #define PG8_SCHED __builtin_amdgcn_sched_barrier(0)
; template <class Epi, class Sched, bool ALIGN_EPI = false, bool SP2 = false>
; __device__ __forceinline__ void gemm_phase(PG8_LAS unsigned char* lds, const Gemm g, const Sched& S, const Epi& E) {
;     ...
;             PG8_LDB(B0, 0, 0); PG8_LDB(B1, 0, 1); PG8_SCHED; PG8_LDA(At, 0, 0); PG8_STAGE(PG8_SA(1, 1), a1 + hstepA, voffA);
;             PG8_WAIT_V(8); PG8_WAIT_L(0); PG8_BAR; PG8_MMA(0, 0, At, B0); PG8_MMA(0, 1, At, B1); PG8_BAR; PG8_SCHED;
;             PG8_LDA(At, 0, 1); PG8_STAGE(PG8_SB(0, 0), b2, voffB); PG8_STAGE(PG8_SB(0, 1), b2 + hstepB, voffB); PG8_STAGE(PG8_SA(0, 0), a2, voffA);
;             PG8_WAIT_V(8); PG8_WAIT_L(0); PG8_BAR; PG8_MMA(1, 0, At, B0); PG8_MMA(1, 1, At, B1); PG8_BAR; PG8_SCHED;
.LBB0_1190:
	s_add_u32 s24, s22, 0xfffc0080
	s_addc_u32 s25, s23, -1
	s_add_i32 s51, 0, 0x10000
	s_cmp_eq_u32 s50, 12
	s_cselect_b32 s27, s44, s25
	s_cselect_b32 s26, s45, s24
	s_cselect_b32 s25, s46, s49
	s_cselect_b32 s24, s47, s48
	s_add_i32 s54, 0, 0x14000
	v_add_u32_e32 v142, s51, v168
	v_add_u32_e32 v166, s54, v168
	ds_read_b128 v[130:133], v142
	ds_read_b128 v[134:137], v142 offset:1024
	ds_read_b128 v[138:141], v142 offset:2048
	ds_read_b128 v[142:145], v142 offset:3072
	ds_read_b128 v[158:161], v166
	ds_read_b128 v[162:165], v166 offset:1024
	ds_read_b128 v[172:175], v166 offset:2048
	ds_read_b128 v[176:179], v166 offset:3072
	s_add_i32 m0, s7, 0xc000
	ds_read_b128 v[180:183], v171
	ds_read_b128 v[184:187], v171 offset:1024
	ds_read_b128 v[202:205], v171 offset:2048
	ds_read_b128 v[206:209], v171 offset:3072
	ds_read_b128 v[210:213], v171 offset:4096
	ds_read_b128 v[232:235], v171 offset:5120
	ds_read_b128 v[236:239], v171 offset:6144
	ds_read_b128 v[240:243], v171 offset:7168
	global_load_lds_dwordx4 v154, s[22:23]
	s_add_i32 m0, s7, 0xe000
	s_nop 0
	global_load_lds_dwordx4 v156, s[22:23]
	s_waitcnt vmcnt(8)
	s_waitcnt lgkmcnt(0)
	s_barrier
	s_setprio 1
	s_waitcnt lgkmcnt(0)
	v_mfma_f32_16x16x32_bf16 v[126:129], v[130:133], v[180:183], v[126:129]
	v_mfma_f32_16x16x32_bf16 v[118:121], v[138:141], v[180:183], v[118:121]
	v_mfma_f32_16x16x32_bf16 v[110:113], v[130:133], v[202:205], v[110:113]
	v_mfma_f32_16x16x32_bf16 v[102:105], v[138:141], v[202:205], v[102:105]
	v_mfma_f32_16x16x32_bf16 v[94:97], v[130:133], v[210:213], v[94:97]
	v_mfma_f32_16x16x32_bf16 v[86:89], v[138:141], v[210:213], v[86:89]
	v_mfma_f32_16x16x32_bf16 v[78:81], v[130:133], v[236:239], v[78:81]
	v_mfma_f32_16x16x32_bf16 v[70:73], v[138:141], v[236:239], v[70:73]
	v_mfma_f32_16x16x32_bf16 v[126:129], v[134:137], v[184:187], v[126:129]
	v_mfma_f32_16x16x32_bf16 v[118:121], v[142:145], v[184:187], v[118:121]
	v_mfma_f32_16x16x32_bf16 v[110:113], v[134:137], v[206:209], v[110:113]
	v_mfma_f32_16x16x32_bf16 v[102:105], v[142:145], v[206:209], v[102:105]
	v_mfma_f32_16x16x32_bf16 v[94:97], v[134:137], v[232:235], v[94:97]
	v_mfma_f32_16x16x32_bf16 v[86:89], v[142:145], v[232:235], v[86:89]
	v_mfma_f32_16x16x32_bf16 v[78:81], v[134:137], v[240:243], v[78:81]
	v_mfma_f32_16x16x32_bf16 v[70:73], v[142:145], v[240:243], v[70:73]
	s_setprio 0
	s_setprio 1
	v_mfma_f32_16x16x32_bf16 v[122:125], v[158:161], v[180:183], v[122:125]
	v_mfma_f32_16x16x32_bf16 v[114:117], v[172:175], v[180:183], v[114:117]
	v_mfma_f32_16x16x32_bf16 v[106:109], v[158:161], v[202:205], v[106:109]
	v_mfma_f32_16x16x32_bf16 v[98:101], v[172:175], v[202:205], v[98:101]
	v_mfma_f32_16x16x32_bf16 v[90:93], v[158:161], v[210:213], v[90:93]
	v_mfma_f32_16x16x32_bf16 v[82:85], v[172:175], v[210:213], v[82:85]
	v_mfma_f32_16x16x32_bf16 v[74:77], v[158:161], v[236:239], v[74:77]
	v_mfma_f32_16x16x32_bf16 v[66:69], v[172:175], v[236:239], v[66:69]
	v_mfma_f32_16x16x32_bf16 v[122:125], v[162:165], v[184:187], v[122:125]
	v_mfma_f32_16x16x32_bf16 v[114:117], v[176:179], v[184:187], v[114:117]
	v_mfma_f32_16x16x32_bf16 v[106:109], v[162:165], v[206:209], v[106:109]
	v_mfma_f32_16x16x32_bf16 v[98:101], v[176:179], v[206:209], v[98:101]
	v_mfma_f32_16x16x32_bf16 v[90:93], v[162:165], v[232:235], v[90:93]
	v_mfma_f32_16x16x32_bf16 v[82:85], v[176:179], v[232:235], v[82:85]
	v_mfma_f32_16x16x32_bf16 v[74:77], v[162:165], v[240:243], v[74:77]
	v_mfma_f32_16x16x32_bf16 v[66:69], v[176:179], v[240:243], v[66:69]
	s_setprio 0
	s_barrier
	s_add_i32 s51, s51, s30
	v_lshl_add_u64 v[166:167], s[24:25], 0, v[150:151]
	s_mov_b32 m0, s51
	ds_read_b128 v[180:183], v171 offset:16384
	ds_read_b128 v[184:187], v171 offset:17408
	ds_read_b128 v[202:205], v171 offset:18432
	ds_read_b128 v[206:209], v171 offset:19456
	ds_read_b128 v[210:213], v171 offset:20480
	ds_read_b128 v[232:235], v171 offset:21504
	ds_read_b128 v[236:239], v171 offset:22528
	ds_read_b128 v[240:243], v171 offset:23552
	global_load_lds_dwordx4 v[166:167], off
	s_add_i32 m0, s51, 0x2000
	s_add_u32 s52, s24, 0x40000
	v_lshl_add_u64 v[214:215], s[24:25], 0, v[146:147]
	s_addc_u32 s53, s25, 0
	s_add_i32 s51, s54, s30
	global_load_lds_dwordx4 v[214:215], off
	s_mov_b32 m0, s51
	v_lshl_add_u64 v[246:247], s[26:27], 0, v[148:149]
	global_load_lds_dwordx4 v150, s[52:53]
	s_add_i32 m0, s51, 0x2000
	s_nop 0
	global_load_lds_dwordx4 v146, s[52:53]
	v_lshl_add_u64 v[244:245], s[26:27], 0, v[152:153]
	s_mov_b32 m0, s7
	s_nop 0
	global_load_lds_dwordx4 v[244:245], off
	s_mov_b32 m0, s36
	s_nop 0
	global_load_lds_dwordx4 v[246:247], off
	s_waitcnt vmcnt(8)
	s_waitcnt lgkmcnt(0)
	s_barrier
; #define PG8_STAGE(bufoff, gbase, voff) do { _Pragma("unroll") for (int _i = 0; _i < 2; ++_i) \
;         __builtin_amdgcn_global_load_lds((const unsigned*)((const char*)(gbase) + (voff)[_i]), (PG8_LAS unsigned*)(lds + (bufoff) + ldsw + _i * 8192), 16, 0, 0); } while (0)
; #define PG8_LDA(dst, b, h) do { _Pragma("unroll") for (int m = 0; m < 4; ++m) _Pragma("unroll") for (int k = 0; k < 2; ++k) dst[m][k] = *(const PG8_LAS bf16x8*)(lds + PG8_SA(b, h) + aoff + m * 2048 + k * 1024); } while (0)
; #define PG8_LDB(dst, b, h) do { _Pragma("unroll") for (int n = 0; n < 2; ++n) _Pragma("unroll") for (int k = 0; k < 2; ++k) dst[n][k] = *(const PG8_LAS bf16x8*)(lds + PG8_SB(b, h) + boff + n * 2048 + k * 1024); } while (0)
; #define PG8_MMA(ai, bj, At, Bt) do { __builtin_amdgcn_s_setprio(1); _Pragma("unroll") for (int m = 0; m < 4; ++m) _Pragma("unroll") for (int n = 0; n < 2; ++n) _Pragma("unroll") for (int k = 0; k < 2; ++k) \
;         acc[ai][bj][m][n] = __builtin_amdgcn_mfma_f32_16x16x32_bf16(Bt[n][k], At[m][k], acc[ai][bj][m][n], 0, 0, 0); __builtin_amdgcn_s_setprio(0); } while (0)
; #define PG8_WAIT_V(n) asm volatile("s_waitcnt vmcnt(" #n ")" ::: "memory")
; #define PG8_WAIT_L(n) asm volatile("s_waitcnt lgkmcnt(" #n ")" ::: "memory")
; #define PG8_BAR __builtin_amdgcn_s_barrier()
; #define PG8_SCHED __builtin_amdgcn_sched_barrier(0)
; template <class Epi, class Sched, bool ALIGN_EPI = false, bool SP2 = false>
; __device__ __forceinline__ void gemm_phase(PG8_LAS unsigned char* lds, const Gemm g, const Sched& S, const Epi& E) {
;     ...
;             PG8_WAIT_V(8); PG8_WAIT_L(0); PG8_BAR; PG8_MMA(1, 0, At, B0); PG8_MMA(1, 1, At, B1); PG8_BAR; PG8_SCHED;
;             PG8_LDB(B0, 1, 0); PG8_LDB(B1, 1, 1); PG8_SCHED; PG8_LDA(At, 1, 0); PG8_STAGE(PG8_SA(0, 1), a2 + hstepA, voffA);
;             PG8_WAIT_V(8); PG8_WAIT_L(0); PG8_BAR; PG8_MMA(0, 0, At, B0); PG8_MMA(0, 1, At, B1); PG8_BAR; PG8_SCHED;
	s_setprio 1
	s_waitcnt lgkmcnt(0)
	v_mfma_f32_16x16x32_bf16 v[62:65], v[130:133], v[180:183], v[62:65]
	v_mfma_f32_16x16x32_bf16 v[54:57], v[138:141], v[180:183], v[54:57]
	v_mfma_f32_16x16x32_bf16 v[46:49], v[130:133], v[202:205], v[46:49]
	v_mfma_f32_16x16x32_bf16 v[38:41], v[138:141], v[202:205], v[38:41]
	v_mfma_f32_16x16x32_bf16 v[30:33], v[130:133], v[210:213], v[30:33]
	v_mfma_f32_16x16x32_bf16 v[22:25], v[138:141], v[210:213], v[22:25]
	v_mfma_f32_16x16x32_bf16 v[14:17], v[130:133], v[236:239], v[14:17]
	v_mfma_f32_16x16x32_bf16 v[6:9], v[138:141], v[236:239], v[6:9]
	v_mfma_f32_16x16x32_bf16 v[62:65], v[134:137], v[184:187], v[62:65]
	v_mfma_f32_16x16x32_bf16 v[54:57], v[142:145], v[184:187], v[54:57]
	v_mfma_f32_16x16x32_bf16 v[46:49], v[134:137], v[206:209], v[46:49]
	v_mfma_f32_16x16x32_bf16 v[38:41], v[142:145], v[206:209], v[38:41]
	v_mfma_f32_16x16x32_bf16 v[30:33], v[134:137], v[232:235], v[30:33]
	v_mfma_f32_16x16x32_bf16 v[22:25], v[142:145], v[232:235], v[22:25]
	v_mfma_f32_16x16x32_bf16 v[14:17], v[134:137], v[240:243], v[14:17]
	v_mfma_f32_16x16x32_bf16 v[6:9], v[142:145], v[240:243], v[6:9]
	s_setprio 0
	s_setprio 1
	v_mfma_f32_16x16x32_bf16 v[58:61], v[158:161], v[180:183], v[58:61]
	v_mfma_f32_16x16x32_bf16 v[50:53], v[172:175], v[180:183], v[50:53]
	v_mfma_f32_16x16x32_bf16 v[42:45], v[158:161], v[202:205], v[42:45]
	v_mfma_f32_16x16x32_bf16 v[34:37], v[172:175], v[202:205], v[34:37]
	v_mfma_f32_16x16x32_bf16 v[26:29], v[158:161], v[210:213], v[26:29]
	v_mfma_f32_16x16x32_bf16 v[18:21], v[172:175], v[210:213], v[18:21]
	v_mfma_f32_16x16x32_bf16 v[10:13], v[158:161], v[236:239], v[10:13]
	v_mfma_f32_16x16x32_bf16 v[2:5], v[172:175], v[236:239], v[2:5]
	v_mfma_f32_16x16x32_bf16 v[58:61], v[162:165], v[184:187], v[58:61]
	v_mfma_f32_16x16x32_bf16 v[50:53], v[176:179], v[184:187], v[50:53]
	v_mfma_f32_16x16x32_bf16 v[42:45], v[162:165], v[206:209], v[42:45]
	v_mfma_f32_16x16x32_bf16 v[34:37], v[176:179], v[206:209], v[34:37]
	v_mfma_f32_16x16x32_bf16 v[26:29], v[162:165], v[232:235], v[26:29]
	v_mfma_f32_16x16x32_bf16 v[18:21], v[176:179], v[232:235], v[18:21]
	v_mfma_f32_16x16x32_bf16 v[10:13], v[162:165], v[240:243], v[10:13]
	v_mfma_f32_16x16x32_bf16 v[2:5], v[176:179], v[240:243], v[2:5]
	s_setprio 0
	s_barrier
	s_add_i32 s51, 0, 0x18000
	s_add_i32 s52, 0, 0x1c000
	v_add_u32_e32 v142, s51, v168
	v_add_u32_e32 v176, s52, v168
	ds_read_b128 v[130:133], v142
	ds_read_b128 v[134:137], v142 offset:1024
	ds_read_b128 v[138:141], v142 offset:2048
	ds_read_b128 v[142:145], v142 offset:3072
	ds_read_b128 v[158:161], v176
	ds_read_b128 v[162:165], v176 offset:1024
	ds_read_b128 v[172:175], v176 offset:2048
	ds_read_b128 v[176:179], v176 offset:3072
	s_add_u32 s26, s26, 0x40000
	s_addc_u32 s27, s27, 0
	s_mov_b32 m0, s37
	ds_read_b128 v[180:183], v171 offset:32768
	ds_read_b128 v[184:187], v171 offset:33792
	ds_read_b128 v[202:205], v171 offset:34816
	ds_read_b128 v[206:209], v171 offset:35840
	ds_read_b128 v[210:213], v171 offset:36864
	ds_read_b128 v[232:235], v171 offset:37888
	ds_read_b128 v[236:239], v171 offset:38912
	ds_read_b128 v[240:243], v171 offset:39936
	global_load_lds_dwordx4 v152, s[26:27]
	s_mov_b32 m0, s38
	s_nop 0
	global_load_lds_dwordx4 v148, s[26:27]
	s_waitcnt vmcnt(8)
	s_waitcnt lgkmcnt(0)
	s_barrier
	s_setprio 1
	s_waitcnt lgkmcnt(0)
	v_mfma_f32_16x16x32_bf16 v[126:129], v[130:133], v[180:183], v[126:129]
	v_mfma_f32_16x16x32_bf16 v[118:121], v[138:141], v[180:183], v[118:121]
	v_mfma_f32_16x16x32_bf16 v[110:113], v[130:133], v[202:205], v[110:113]
	v_mfma_f32_16x16x32_bf16 v[102:105], v[138:141], v[202:205], v[102:105]
	v_mfma_f32_16x16x32_bf16 v[94:97], v[130:133], v[210:213], v[94:97]
	v_mfma_f32_16x16x32_bf16 v[86:89], v[138:141], v[210:213], v[86:89]
	v_mfma_f32_16x16x32_bf16 v[78:81], v[130:133], v[236:239], v[78:81]
	v_mfma_f32_16x16x32_bf16 v[70:73], v[138:141], v[236:239], v[70:73]
	v_mfma_f32_16x16x32_bf16 v[126:129], v[134:137], v[184:187], v[126:129]
	v_mfma_f32_16x16x32_bf16 v[118:121], v[142:145], v[184:187], v[118:121]
	v_mfma_f32_16x16x32_bf16 v[110:113], v[134:137], v[206:209], v[110:113]
	v_mfma_f32_16x16x32_bf16 v[102:105], v[142:145], v[206:209], v[102:105]
	v_mfma_f32_16x16x32_bf16 v[94:97], v[134:137], v[232:235], v[94:97]
	v_mfma_f32_16x16x32_bf16 v[86:89], v[142:145], v[232:235], v[86:89]
	v_mfma_f32_16x16x32_bf16 v[78:81], v[134:137], v[240:243], v[78:81]
	v_mfma_f32_16x16x32_bf16 v[70:73], v[142:145], v[240:243], v[70:73]
	s_setprio 0
	s_setprio 1
	v_mfma_f32_16x16x32_bf16 v[122:125], v[158:161], v[180:183], v[122:125]
	v_mfma_f32_16x16x32_bf16 v[114:117], v[172:175], v[180:183], v[114:117]
	v_mfma_f32_16x16x32_bf16 v[106:109], v[158:161], v[202:205], v[106:109]
	v_mfma_f32_16x16x32_bf16 v[98:101], v[172:175], v[202:205], v[98:101]
	v_mfma_f32_16x16x32_bf16 v[90:93], v[158:161], v[210:213], v[90:93]
	v_mfma_f32_16x16x32_bf16 v[82:85], v[172:175], v[210:213], v[82:85]
	v_mfma_f32_16x16x32_bf16 v[74:77], v[158:161], v[236:239], v[74:77]
	v_mfma_f32_16x16x32_bf16 v[66:69], v[172:175], v[236:239], v[66:69]
	v_mfma_f32_16x16x32_bf16 v[122:125], v[162:165], v[184:187], v[122:125]
	v_mfma_f32_16x16x32_bf16 v[114:117], v[176:179], v[184:187], v[114:117]
	v_mfma_f32_16x16x32_bf16 v[106:109], v[162:165], v[206:209], v[106:109]
	v_mfma_f32_16x16x32_bf16 v[98:101], v[176:179], v[206:209], v[98:101]
	v_mfma_f32_16x16x32_bf16 v[90:93], v[162:165], v[232:235], v[90:93]
	v_mfma_f32_16x16x32_bf16 v[82:85], v[176:179], v[232:235], v[82:85]
	v_mfma_f32_16x16x32_bf16 v[74:77], v[162:165], v[240:243], v[74:77]
	v_mfma_f32_16x16x32_bf16 v[66:69], v[176:179], v[240:243], v[66:69]
	s_setprio 0
	s_barrier
; #define PG8_STAGE(bufoff, gbase, voff) do { _Pragma("unroll") for (int _i = 0; _i < 2; ++_i) \
;         __builtin_amdgcn_global_load_lds((const unsigned*)((const char*)(gbase) + (voff)[_i]), (PG8_LAS unsigned*)(lds + (bufoff) + ldsw + _i * 8192), 16, 0, 0); } while (0)
; #define PG8_LDA(dst, b, h) do { _Pragma("unroll") for (int m = 0; m < 4; ++m) _Pragma("unroll") for (int k = 0; k < 2; ++k) dst[m][k] = *(const PG8_LAS bf16x8*)(lds + PG8_SA(b, h) + aoff + m * 2048 + k * 1024); } while (0)
; #define PG8_MMA(ai, bj, At, Bt) do { __builtin_amdgcn_s_setprio(1); _Pragma("unroll") for (int m = 0; m < 4; ++m) _Pragma("unroll") for (int n = 0; n < 2; ++n) _Pragma("unroll") for (int k = 0; k < 2; ++k) \
;         acc[ai][bj][m][n] = __builtin_amdgcn_mfma_f32_16x16x32_bf16(Bt[n][k], At[m][k], acc[ai][bj][m][n], 0, 0, 0); __builtin_amdgcn_s_setprio(0); } while (0)
; #define PG8_WAIT_V(n) asm volatile("s_waitcnt vmcnt(" #n ")" ::: "memory")
; #define PG8_WAIT_L(n) asm volatile("s_waitcnt lgkmcnt(" #n ")" ::: "memory")
; #define PG8_BAR __builtin_amdgcn_s_barrier()
; #define PG8_SCHED __builtin_amdgcn_sched_barrier(0)
; template <class Epi, class Sched, bool ALIGN_EPI = false, bool SP2 = false>
; __device__ __forceinline__ void gemm_phase(PG8_LAS unsigned char* lds, const Gemm g, const Sched& S, const Epi& E) {
;     ...
;         for (int t = 0; t < nt; t += 2) {
;     ...
;             PG8_LDA(At, 1, 1); PG8_STAGE(PG8_SB(1, 0), b3, voffB); PG8_STAGE(PG8_SB(1, 1), b3 + hstepB, voffB); PG8_STAGE(PG8_SA(1, 0), a3, voffA);
;             PG8_WAIT_V(8); PG8_WAIT_L(0); PG8_BAR; PG8_MMA(1, 0, At, B0); PG8_MMA(1, 1, At, B1); PG8_BAR; PG8_SCHED;
	s_add_i32 s26, s51, s30
	v_lshl_add_u64 v[166:167], v[166:167], 0, s[96:97]
	s_mov_b32 m0, s26
	ds_read_b128 v[180:183], v171 offset:49152
	ds_read_b128 v[184:187], v171 offset:50176
	ds_read_b128 v[202:205], v171 offset:51200
	ds_read_b128 v[206:209], v171 offset:52224
	ds_read_b128 v[210:213], v171 offset:53248
	ds_read_b128 v[232:235], v171 offset:54272
	ds_read_b128 v[236:239], v171 offset:55296
	ds_read_b128 v[240:243], v171 offset:56320
	global_load_lds_dwordx4 v[166:167], off
	s_add_i32 m0, s26, 0x2000
	s_add_u32 s24, s24, 0x40080
	v_lshl_add_u64 v[166:167], v[214:215], 0, s[96:97]
	s_addc_u32 s25, s25, 0
	s_add_i32 s26, s52, s30
	global_load_lds_dwordx4 v[166:167], off
	s_mov_b32 m0, s26
	s_nop 0
	global_load_lds_dwordx4 v150, s[24:25]
	s_add_i32 m0, s26, 0x2000
	s_nop 0
	global_load_lds_dwordx4 v146, s[24:25]
	v_lshl_add_u64 v[166:167], v[244:245], 0, s[96:97]
	s_mov_b32 m0, s39
	s_nop 0
	global_load_lds_dwordx4 v[166:167], off
	v_lshl_add_u64 v[166:167], v[246:247], 0, s[96:97]
	s_mov_b32 m0, s40
	s_nop 0
	global_load_lds_dwordx4 v[166:167], off
	s_waitcnt vmcnt(8)
	s_waitcnt lgkmcnt(0)
	s_barrier
	s_setprio 1
	s_waitcnt lgkmcnt(0)
	v_mfma_f32_16x16x32_bf16 v[62:65], v[130:133], v[180:183], v[62:65]
	v_mfma_f32_16x16x32_bf16 v[54:57], v[138:141], v[180:183], v[54:57]
	v_mfma_f32_16x16x32_bf16 v[46:49], v[130:133], v[202:205], v[46:49]
	v_mfma_f32_16x16x32_bf16 v[38:41], v[138:141], v[202:205], v[38:41]
	v_mfma_f32_16x16x32_bf16 v[30:33], v[130:133], v[210:213], v[30:33]
	v_mfma_f32_16x16x32_bf16 v[22:25], v[138:141], v[210:213], v[22:25]
	v_mfma_f32_16x16x32_bf16 v[14:17], v[130:133], v[236:239], v[14:17]
	v_mfma_f32_16x16x32_bf16 v[6:9], v[138:141], v[236:239], v[6:9]
	v_mfma_f32_16x16x32_bf16 v[62:65], v[134:137], v[184:187], v[62:65]
	v_mfma_f32_16x16x32_bf16 v[54:57], v[142:145], v[184:187], v[54:57]
	v_mfma_f32_16x16x32_bf16 v[46:49], v[134:137], v[206:209], v[46:49]
	v_mfma_f32_16x16x32_bf16 v[38:41], v[142:145], v[206:209], v[38:41]
	v_mfma_f32_16x16x32_bf16 v[30:33], v[134:137], v[232:235], v[30:33]
	v_mfma_f32_16x16x32_bf16 v[22:25], v[142:145], v[232:235], v[22:25]
	v_mfma_f32_16x16x32_bf16 v[14:17], v[134:137], v[240:243], v[14:17]
	v_mfma_f32_16x16x32_bf16 v[6:9], v[142:145], v[240:243], v[6:9]
	s_setprio 0
	s_setprio 1
	v_mfma_f32_16x16x32_bf16 v[58:61], v[158:161], v[180:183], v[58:61]
	v_mfma_f32_16x16x32_bf16 v[50:53], v[172:175], v[180:183], v[50:53]
	v_mfma_f32_16x16x32_bf16 v[42:45], v[158:161], v[202:205], v[42:45]
	v_mfma_f32_16x16x32_bf16 v[34:37], v[172:175], v[202:205], v[34:37]
	v_mfma_f32_16x16x32_bf16 v[26:29], v[158:161], v[210:213], v[26:29]
	v_mfma_f32_16x16x32_bf16 v[18:21], v[172:175], v[210:213], v[18:21]
	v_mfma_f32_16x16x32_bf16 v[10:13], v[158:161], v[236:239], v[10:13]
	v_mfma_f32_16x16x32_bf16 v[2:5], v[172:175], v[236:239], v[2:5]
	v_mfma_f32_16x16x32_bf16 v[58:61], v[162:165], v[184:187], v[58:61]
	v_mfma_f32_16x16x32_bf16 v[50:53], v[176:179], v[184:187], v[50:53]
	v_mfma_f32_16x16x32_bf16 v[42:45], v[162:165], v[206:209], v[42:45]
	v_mfma_f32_16x16x32_bf16 v[34:37], v[176:179], v[206:209], v[34:37]
	v_mfma_f32_16x16x32_bf16 v[26:29], v[162:165], v[232:235], v[26:29]
	v_mfma_f32_16x16x32_bf16 v[18:21], v[176:179], v[232:235], v[18:21]
	v_mfma_f32_16x16x32_bf16 v[10:13], v[162:165], v[240:243], v[10:13]
	v_mfma_f32_16x16x32_bf16 v[2:5], v[176:179], v[240:243], v[2:5]
	s_setprio 0
	s_barrier
	s_add_i32 s50, s50, 2
	s_add_u32 s22, s22, 0x100
	s_addc_u32 s23, s23, 0
	s_add_u32 s48, s48, 0x100
	s_addc_u32 s49, s49, 0
	s_cmp_gt_u32 s50, 13
	s_cbranch_scc0 .LBB0_1190
	s_and_b64 vcc, exec, s[18:19]
	s_cbranch_vccz .LBB0_1193
	s_barrier

; #define PG8_STAGE(bufoff, gbase, voff) do { _Pragma("unroll") for (int _i = 0; _i < 2; ++_i) \
;         __builtin_amdgcn_global_load_lds((const unsigned*)((const char*)(gbase) + (voff)[_i]), (PG8_LAS unsigned*)(lds + (bufoff) + ldsw + _i * 8192), 16, 0, 0); } while (0)
; #define PG8_LDA(dst, b, h) do { _Pragma("unroll") for (int m = 0; m < 4; ++m) _Pragma("unroll") for (int k = 0; k < 2; ++k) dst[m][k] = *(const PG8_LAS bf16x8*)(lds + PG8_SA(b, h) + aoff + m * 2048 + k * 1024); } while (0)
; #define PG8_LDB(dst, b, h) do { _Pragma("unroll") for (int n = 0; n < 2; ++n) _Pragma("unroll") for (int k = 0; k < 2; ++k) dst[n][k] = *(const PG8_LAS bf16x8*)(lds + PG8_SB(b, h) + boff + n * 2048 + k * 1024); } while (0)
; #define PG8_MMA(ai, bj, At, Bt) do { __builtin_amdgcn_s_setprio(1); _Pragma("unroll") for (int m = 0; m < 4; ++m) _Pragma("unroll") for (int n = 0; n < 2; ++n) _Pragma("unroll") for (int k = 0; k < 2; ++k) \
;         acc[ai][bj][m][n] = __builtin_amdgcn_mfma_f32_16x16x32_bf16(Bt[n][k], At[m][k], acc[ai][bj][m][n], 0, 0, 0); __builtin_amdgcn_s_setprio(0); } while (0)
; #define PG8_WAIT_V(n) asm volatile("s_waitcnt vmcnt(" #n ")" ::: "memory")
; #define PG8_WAIT_L(n) asm volatile("s_waitcnt lgkmcnt(" #n ")" ::: "memory")
; #define PG8_BAR __builtin_amdgcn_s_barrier()
; #define PG8_SCHED __builtin_amdgcn_sched_barrier(0)
; template <class Epi, class Sched, bool ALIGN_EPI = false, bool SP2 = false>
; __device__ __forceinline__ void gemm_phase(PG8_LAS unsigned char* lds, const Gemm g, const Sched& S, const Epi& E) {
;     ...
;             PG8_LDB(B0, 0, 0); PG8_LDB(B1, 0, 1); PG8_SCHED; PG8_LDA(At, 0, 0); PG8_STAGE(PG8_SA(1, 1), a1 + hstepA, voffA);
;             PG8_WAIT_V(8); PG8_WAIT_L(0); PG8_BAR; PG8_MMA(0, 0, At, B0); PG8_MMA(0, 1, At, B1); PG8_BAR; PG8_SCHED;
;             PG8_LDA(At, 0, 1); PG8_STAGE(PG8_SB(0, 0), b2, voffB); PG8_STAGE(PG8_SB(0, 1), b2 + hstepB, voffB); PG8_STAGE(PG8_SA(0, 0), a2, voffA);
;             PG8_WAIT_V(8); PG8_WAIT_L(0); PG8_BAR; PG8_MMA(1, 0, At, B0); PG8_MMA(1, 1, At, B1); PG8_BAR; PG8_SCHED;
.LBB0_1270:
	s_add_u32 s28, s26, 0xfffc0080
	s_addc_u32 s29, s27, -1
	s_add_i32 s52, 0, 0x10000
	s_cmp_eq_u32 s51, 12
	s_cselect_b32 s31, s17, s29
	s_cselect_b32 s30, s23, s28
	s_cselect_b32 s29, s15, s50
	s_cselect_b32 s28, s25, s49
	s_add_i32 s54, 0, 0x14000
	v_add_u32_e32 v142, s52, v186
	v_add_u32_e32 v172, s54, v186
	ds_read_b128 v[130:133], v142
	ds_read_b128 v[134:137], v142 offset:1024
	ds_read_b128 v[138:141], v142 offset:2048
	ds_read_b128 v[142:145], v142 offset:3072
	ds_read_b128 v[146:149], v172
	ds_read_b128 v[150:153], v172 offset:1024
	ds_read_b128 v[168:171], v172 offset:2048
	ds_read_b128 v[172:175], v172 offset:3072
	s_add_i32 m0, s39, 0xc000
	ds_read_b128 v[176:179], v200
	ds_read_b128 v[180:183], v200 offset:1024
	ds_read_b128 v[202:205], v200 offset:2048
	ds_read_b128 v[206:209], v200 offset:3072
	ds_read_b128 v[210:213], v200 offset:4096
	ds_read_b128 v[232:235], v200 offset:5120
	ds_read_b128 v[236:239], v200 offset:6144
	ds_read_b128 v[240:243], v200 offset:7168
	global_load_lds_dwordx4 v164, s[26:27]
	s_add_i32 m0, s39, 0xe000
	s_nop 0
	global_load_lds_dwordx4 v166, s[26:27]
	s_waitcnt vmcnt(8)
	s_waitcnt lgkmcnt(0)
	s_barrier
	s_setprio 1
	s_waitcnt lgkmcnt(0)
	v_mfma_f32_16x16x32_bf16 v[126:129], v[130:133], v[176:179], v[126:129]
	v_mfma_f32_16x16x32_bf16 v[122:125], v[138:141], v[176:179], v[122:125]
	v_mfma_f32_16x16x32_bf16 v[110:113], v[130:133], v[202:205], v[110:113]
	v_mfma_f32_16x16x32_bf16 v[106:109], v[138:141], v[202:205], v[106:109]
	v_mfma_f32_16x16x32_bf16 v[94:97], v[130:133], v[210:213], v[94:97]
	v_mfma_f32_16x16x32_bf16 v[90:93], v[138:141], v[210:213], v[90:93]
	v_mfma_f32_16x16x32_bf16 v[78:81], v[130:133], v[236:239], v[78:81]
	v_mfma_f32_16x16x32_bf16 v[74:77], v[138:141], v[236:239], v[74:77]
	v_mfma_f32_16x16x32_bf16 v[126:129], v[134:137], v[180:183], v[126:129]
	v_mfma_f32_16x16x32_bf16 v[122:125], v[142:145], v[180:183], v[122:125]
	v_mfma_f32_16x16x32_bf16 v[110:113], v[134:137], v[206:209], v[110:113]
	v_mfma_f32_16x16x32_bf16 v[106:109], v[142:145], v[206:209], v[106:109]
	v_mfma_f32_16x16x32_bf16 v[94:97], v[134:137], v[232:235], v[94:97]
	v_mfma_f32_16x16x32_bf16 v[90:93], v[142:145], v[232:235], v[90:93]
	v_mfma_f32_16x16x32_bf16 v[78:81], v[134:137], v[240:243], v[78:81]
	v_mfma_f32_16x16x32_bf16 v[74:77], v[142:145], v[240:243], v[74:77]
	s_setprio 0
	s_setprio 1
	v_mfma_f32_16x16x32_bf16 v[118:121], v[146:149], v[176:179], v[118:121]
	v_mfma_f32_16x16x32_bf16 v[114:117], v[168:171], v[176:179], v[114:117]
	v_mfma_f32_16x16x32_bf16 v[102:105], v[146:149], v[202:205], v[102:105]
	v_mfma_f32_16x16x32_bf16 v[98:101], v[168:171], v[202:205], v[98:101]
	v_mfma_f32_16x16x32_bf16 v[86:89], v[146:149], v[210:213], v[86:89]
	v_mfma_f32_16x16x32_bf16 v[82:85], v[168:171], v[210:213], v[82:85]
	v_mfma_f32_16x16x32_bf16 v[70:73], v[146:149], v[236:239], v[70:73]
	v_mfma_f32_16x16x32_bf16 v[66:69], v[168:171], v[236:239], v[66:69]
	v_mfma_f32_16x16x32_bf16 v[118:121], v[150:153], v[180:183], v[118:121]
	v_mfma_f32_16x16x32_bf16 v[114:117], v[172:175], v[180:183], v[114:117]
	v_mfma_f32_16x16x32_bf16 v[102:105], v[150:153], v[206:209], v[102:105]
	v_mfma_f32_16x16x32_bf16 v[98:101], v[172:175], v[206:209], v[98:101]
	v_mfma_f32_16x16x32_bf16 v[86:89], v[150:153], v[232:235], v[86:89]
	v_mfma_f32_16x16x32_bf16 v[82:85], v[172:175], v[232:235], v[82:85]
	v_mfma_f32_16x16x32_bf16 v[70:73], v[150:153], v[240:243], v[70:73]
	v_mfma_f32_16x16x32_bf16 v[66:69], v[172:175], v[240:243], v[66:69]
	s_setprio 0
	s_barrier
	s_add_i32 s52, s52, s38
	v_lshl_add_u64 v[184:185], s[28:29], 0, v[156:157]
	s_mov_b32 m0, s52
	ds_read_b128 v[176:179], v200 offset:16384
	ds_read_b128 v[180:183], v200 offset:17408
	ds_read_b128 v[202:205], v200 offset:18432
	ds_read_b128 v[206:209], v200 offset:19456
	ds_read_b128 v[210:213], v200 offset:20480
	ds_read_b128 v[232:235], v200 offset:21504
	ds_read_b128 v[236:239], v200 offset:22528
	ds_read_b128 v[240:243], v200 offset:23552
	global_load_lds_dwordx4 v[184:185], off
	s_add_i32 m0, s52, 0x2000
	s_add_u32 s52, s28, 0x40000
	v_lshl_add_u64 v[214:215], s[28:29], 0, v[160:161]
	s_addc_u32 s53, s29, 0
	s_add_i32 s54, s54, s38
	global_load_lds_dwordx4 v[214:215], off
	s_mov_b32 m0, s54
	v_lshl_add_u64 v[246:247], s[30:31], 0, v[158:159]
	global_load_lds_dwordx4 v156, s[52:53]
	s_add_i32 m0, s54, 0x2000
	s_nop 0
	global_load_lds_dwordx4 v160, s[52:53]
	v_lshl_add_u64 v[244:245], s[30:31], 0, v[154:155]
	s_mov_b32 m0, s39
	s_nop 0
	global_load_lds_dwordx4 v[244:245], off
	s_mov_b32 m0, s40
	s_nop 0
	global_load_lds_dwordx4 v[246:247], off
	s_waitcnt vmcnt(8)
	s_waitcnt lgkmcnt(0)
	s_barrier
; #define PG8_STAGE(bufoff, gbase, voff) do { _Pragma("unroll") for (int _i = 0; _i < 2; ++_i) \
;         __builtin_amdgcn_global_load_lds((const unsigned*)((const char*)(gbase) + (voff)[_i]), (PG8_LAS unsigned*)(lds + (bufoff) + ldsw + _i * 8192), 16, 0, 0); } while (0)
; #define PG8_LDA(dst, b, h) do { _Pragma("unroll") for (int m = 0; m < 4; ++m) _Pragma("unroll") for (int k = 0; k < 2; ++k) dst[m][k] = *(const PG8_LAS bf16x8*)(lds + PG8_SA(b, h) + aoff + m * 2048 + k * 1024); } while (0)
; #define PG8_LDB(dst, b, h) do { _Pragma("unroll") for (int n = 0; n < 2; ++n) _Pragma("unroll") for (int k = 0; k < 2; ++k) dst[n][k] = *(const PG8_LAS bf16x8*)(lds + PG8_SB(b, h) + boff + n * 2048 + k * 1024); } while (0)
; #define PG8_MMA(ai, bj, At, Bt) do { __builtin_amdgcn_s_setprio(1); _Pragma("unroll") for (int m = 0; m < 4; ++m) _Pragma("unroll") for (int n = 0; n < 2; ++n) _Pragma("unroll") for (int k = 0; k < 2; ++k) \
;         acc[ai][bj][m][n] = __builtin_amdgcn_mfma_f32_16x16x32_bf16(Bt[n][k], At[m][k], acc[ai][bj][m][n], 0, 0, 0); __builtin_amdgcn_s_setprio(0); } while (0)
; #define PG8_WAIT_V(n) asm volatile("s_waitcnt vmcnt(" #n ")" ::: "memory")
; #define PG8_WAIT_L(n) asm volatile("s_waitcnt lgkmcnt(" #n ")" ::: "memory")
; #define PG8_BAR __builtin_amdgcn_s_barrier()
; #define PG8_SCHED __builtin_amdgcn_sched_barrier(0)
; template <class Epi, class Sched, bool ALIGN_EPI = false, bool SP2 = false>
; __device__ __forceinline__ void gemm_phase(PG8_LAS unsigned char* lds, const Gemm g, const Sched& S, const Epi& E) {
;     ...
;             PG8_WAIT_V(8); PG8_WAIT_L(0); PG8_BAR; PG8_MMA(1, 0, At, B0); PG8_MMA(1, 1, At, B1); PG8_BAR; PG8_SCHED;
;             PG8_LDB(B0, 1, 0); PG8_LDB(B1, 1, 1); PG8_SCHED; PG8_LDA(At, 1, 0); PG8_STAGE(PG8_SA(0, 1), a2 + hstepA, voffA);
;             PG8_WAIT_V(8); PG8_WAIT_L(0); PG8_BAR; PG8_MMA(0, 0, At, B0); PG8_MMA(0, 1, At, B1); PG8_BAR; PG8_SCHED;
	s_setprio 1
	s_waitcnt lgkmcnt(0)
	v_mfma_f32_16x16x32_bf16 v[62:65], v[130:133], v[176:179], v[62:65]
	v_mfma_f32_16x16x32_bf16 v[58:61], v[138:141], v[176:179], v[58:61]
	v_mfma_f32_16x16x32_bf16 v[46:49], v[130:133], v[202:205], v[46:49]
	v_mfma_f32_16x16x32_bf16 v[42:45], v[138:141], v[202:205], v[42:45]
	v_mfma_f32_16x16x32_bf16 v[30:33], v[130:133], v[210:213], v[30:33]
	v_mfma_f32_16x16x32_bf16 v[26:29], v[138:141], v[210:213], v[26:29]
	v_mfma_f32_16x16x32_bf16 v[14:17], v[130:133], v[236:239], v[14:17]
	v_mfma_f32_16x16x32_bf16 v[10:13], v[138:141], v[236:239], v[10:13]
	v_mfma_f32_16x16x32_bf16 v[62:65], v[134:137], v[180:183], v[62:65]
	v_mfma_f32_16x16x32_bf16 v[58:61], v[142:145], v[180:183], v[58:61]
	v_mfma_f32_16x16x32_bf16 v[46:49], v[134:137], v[206:209], v[46:49]
	v_mfma_f32_16x16x32_bf16 v[42:45], v[142:145], v[206:209], v[42:45]
	v_mfma_f32_16x16x32_bf16 v[30:33], v[134:137], v[232:235], v[30:33]
	v_mfma_f32_16x16x32_bf16 v[26:29], v[142:145], v[232:235], v[26:29]
	v_mfma_f32_16x16x32_bf16 v[14:17], v[134:137], v[240:243], v[14:17]
	v_mfma_f32_16x16x32_bf16 v[10:13], v[142:145], v[240:243], v[10:13]
	s_setprio 0
	s_setprio 1
	v_mfma_f32_16x16x32_bf16 v[54:57], v[146:149], v[176:179], v[54:57]
	v_mfma_f32_16x16x32_bf16 v[50:53], v[168:171], v[176:179], v[50:53]
	v_mfma_f32_16x16x32_bf16 v[38:41], v[146:149], v[202:205], v[38:41]
	v_mfma_f32_16x16x32_bf16 v[34:37], v[168:171], v[202:205], v[34:37]
	v_mfma_f32_16x16x32_bf16 v[22:25], v[146:149], v[210:213], v[22:25]
	v_mfma_f32_16x16x32_bf16 v[18:21], v[168:171], v[210:213], v[18:21]
	v_mfma_f32_16x16x32_bf16 v[6:9], v[146:149], v[236:239], v[6:9]
	v_mfma_f32_16x16x32_bf16 v[2:5], v[168:171], v[236:239], v[2:5]
	v_mfma_f32_16x16x32_bf16 v[54:57], v[150:153], v[180:183], v[54:57]
	v_mfma_f32_16x16x32_bf16 v[50:53], v[172:175], v[180:183], v[50:53]
	v_mfma_f32_16x16x32_bf16 v[38:41], v[150:153], v[206:209], v[38:41]
	v_mfma_f32_16x16x32_bf16 v[34:37], v[172:175], v[206:209], v[34:37]
	v_mfma_f32_16x16x32_bf16 v[22:25], v[150:153], v[232:235], v[22:25]
	v_mfma_f32_16x16x32_bf16 v[18:21], v[172:175], v[232:235], v[18:21]
	v_mfma_f32_16x16x32_bf16 v[6:9], v[150:153], v[240:243], v[6:9]
	v_mfma_f32_16x16x32_bf16 v[2:5], v[172:175], v[240:243], v[2:5]
	s_setprio 0
	s_barrier
	s_add_i32 s52, 0, 0x18000
	s_add_i32 s53, 0, 0x1c000
	v_add_u32_e32 v142, s52, v186
	v_add_u32_e32 v172, s53, v186
	ds_read_b128 v[130:133], v142
	ds_read_b128 v[134:137], v142 offset:1024
	ds_read_b128 v[138:141], v142 offset:2048
	ds_read_b128 v[142:145], v142 offset:3072
	ds_read_b128 v[146:149], v172
	ds_read_b128 v[150:153], v172 offset:1024
	ds_read_b128 v[168:171], v172 offset:2048
	ds_read_b128 v[172:175], v172 offset:3072
	s_add_u32 s30, s30, 0x40000
	s_addc_u32 s31, s31, 0
	s_mov_b32 m0, s41
	ds_read_b128 v[176:179], v200 offset:32768
	ds_read_b128 v[180:183], v200 offset:33792
	ds_read_b128 v[202:205], v200 offset:34816
	ds_read_b128 v[206:209], v200 offset:35840
	ds_read_b128 v[210:213], v200 offset:36864
	ds_read_b128 v[232:235], v200 offset:37888
	ds_read_b128 v[236:239], v200 offset:38912
	ds_read_b128 v[240:243], v200 offset:39936
	global_load_lds_dwordx4 v154, s[30:31]
	s_mov_b32 m0, s42
	s_nop 0
	global_load_lds_dwordx4 v158, s[30:31]
	s_waitcnt vmcnt(8)
	s_waitcnt lgkmcnt(0)
	s_barrier
	s_setprio 1
	s_waitcnt lgkmcnt(0)
	v_mfma_f32_16x16x32_bf16 v[126:129], v[130:133], v[176:179], v[126:129]
	v_mfma_f32_16x16x32_bf16 v[122:125], v[138:141], v[176:179], v[122:125]
	v_mfma_f32_16x16x32_bf16 v[110:113], v[130:133], v[202:205], v[110:113]
	v_mfma_f32_16x16x32_bf16 v[106:109], v[138:141], v[202:205], v[106:109]
	v_mfma_f32_16x16x32_bf16 v[94:97], v[130:133], v[210:213], v[94:97]
	v_mfma_f32_16x16x32_bf16 v[90:93], v[138:141], v[210:213], v[90:93]
	v_mfma_f32_16x16x32_bf16 v[78:81], v[130:133], v[236:239], v[78:81]
	v_mfma_f32_16x16x32_bf16 v[74:77], v[138:141], v[236:239], v[74:77]
	v_mfma_f32_16x16x32_bf16 v[126:129], v[134:137], v[180:183], v[126:129]
	v_mfma_f32_16x16x32_bf16 v[122:125], v[142:145], v[180:183], v[122:125]
	v_mfma_f32_16x16x32_bf16 v[110:113], v[134:137], v[206:209], v[110:113]
	v_mfma_f32_16x16x32_bf16 v[106:109], v[142:145], v[206:209], v[106:109]
	v_mfma_f32_16x16x32_bf16 v[94:97], v[134:137], v[232:235], v[94:97]
	v_mfma_f32_16x16x32_bf16 v[90:93], v[142:145], v[232:235], v[90:93]
	v_mfma_f32_16x16x32_bf16 v[78:81], v[134:137], v[240:243], v[78:81]
	v_mfma_f32_16x16x32_bf16 v[74:77], v[142:145], v[240:243], v[74:77]
	s_setprio 0
	s_setprio 1
	v_mfma_f32_16x16x32_bf16 v[118:121], v[146:149], v[176:179], v[118:121]
	v_mfma_f32_16x16x32_bf16 v[114:117], v[168:171], v[176:179], v[114:117]
	v_mfma_f32_16x16x32_bf16 v[102:105], v[146:149], v[202:205], v[102:105]
	v_mfma_f32_16x16x32_bf16 v[98:101], v[168:171], v[202:205], v[98:101]
	v_mfma_f32_16x16x32_bf16 v[86:89], v[146:149], v[210:213], v[86:89]
	v_mfma_f32_16x16x32_bf16 v[82:85], v[168:171], v[210:213], v[82:85]
	v_mfma_f32_16x16x32_bf16 v[70:73], v[146:149], v[236:239], v[70:73]
	v_mfma_f32_16x16x32_bf16 v[66:69], v[168:171], v[236:239], v[66:69]
	v_mfma_f32_16x16x32_bf16 v[118:121], v[150:153], v[180:183], v[118:121]
	v_mfma_f32_16x16x32_bf16 v[114:117], v[172:175], v[180:183], v[114:117]
	v_mfma_f32_16x16x32_bf16 v[102:105], v[150:153], v[206:209], v[102:105]
	v_mfma_f32_16x16x32_bf16 v[98:101], v[172:175], v[206:209], v[98:101]
	v_mfma_f32_16x16x32_bf16 v[86:89], v[150:153], v[232:235], v[86:89]
	v_mfma_f32_16x16x32_bf16 v[82:85], v[172:175], v[232:235], v[82:85]
	v_mfma_f32_16x16x32_bf16 v[70:73], v[150:153], v[240:243], v[70:73]
	v_mfma_f32_16x16x32_bf16 v[66:69], v[172:175], v[240:243], v[66:69]
	s_setprio 0
	s_barrier
; #define PG8_STAGE(bufoff, gbase, voff) do { _Pragma("unroll") for (int _i = 0; _i < 2; ++_i) \
;         __builtin_amdgcn_global_load_lds((const unsigned*)((const char*)(gbase) + (voff)[_i]), (PG8_LAS unsigned*)(lds + (bufoff) + ldsw + _i * 8192), 16, 0, 0); } while (0)
; #define PG8_LDA(dst, b, h) do { _Pragma("unroll") for (int m = 0; m < 4; ++m) _Pragma("unroll") for (int k = 0; k < 2; ++k) dst[m][k] = *(const PG8_LAS bf16x8*)(lds + PG8_SA(b, h) + aoff + m * 2048 + k * 1024); } while (0)
; #define PG8_MMA(ai, bj, At, Bt) do { __builtin_amdgcn_s_setprio(1); _Pragma("unroll") for (int m = 0; m < 4; ++m) _Pragma("unroll") for (int n = 0; n < 2; ++n) _Pragma("unroll") for (int k = 0; k < 2; ++k) \
;         acc[ai][bj][m][n] = __builtin_amdgcn_mfma_f32_16x16x32_bf16(Bt[n][k], At[m][k], acc[ai][bj][m][n], 0, 0, 0); __builtin_amdgcn_s_setprio(0); } while (0)
; #define PG8_WAIT_V(n) asm volatile("s_waitcnt vmcnt(" #n ")" ::: "memory")
; #define PG8_WAIT_L(n) asm volatile("s_waitcnt lgkmcnt(" #n ")" ::: "memory")
; #define PG8_BAR __builtin_amdgcn_s_barrier()
; #define PG8_SCHED __builtin_amdgcn_sched_barrier(0)
; template <class Epi, class Sched, bool ALIGN_EPI = false, bool SP2 = false>
; __device__ __forceinline__ void gemm_phase(PG8_LAS unsigned char* lds, const Gemm g, const Sched& S, const Epi& E) {
;     ...
;         for (int t = 0; t < nt; t += 2) {
;     ...
;             PG8_LDA(At, 1, 1); PG8_STAGE(PG8_SB(1, 0), b3, voffB); PG8_STAGE(PG8_SB(1, 1), b3 + hstepB, voffB); PG8_STAGE(PG8_SA(1, 0), a3, voffA);
;             PG8_WAIT_V(8); PG8_WAIT_L(0); PG8_BAR; PG8_MMA(1, 0, At, B0); PG8_MMA(1, 1, At, B1); PG8_BAR; PG8_SCHED;
	s_add_i32 s30, s52, s38
	v_lshl_add_u64 v[184:185], v[184:185], 0, s[96:97]
	s_mov_b32 m0, s30
	ds_read_b128 v[176:179], v200 offset:49152
	ds_read_b128 v[180:183], v200 offset:50176
	ds_read_b128 v[202:205], v200 offset:51200
	ds_read_b128 v[206:209], v200 offset:52224
	ds_read_b128 v[210:213], v200 offset:53248
	ds_read_b128 v[232:235], v200 offset:54272
	ds_read_b128 v[236:239], v200 offset:55296
	ds_read_b128 v[240:243], v200 offset:56320
	global_load_lds_dwordx4 v[184:185], off
	s_add_i32 m0, s30, 0x2000
	s_add_u32 s28, s28, 0x40080
	v_lshl_add_u64 v[184:185], v[214:215], 0, s[96:97]
	s_addc_u32 s29, s29, 0
	s_add_i32 s30, s53, s38
	global_load_lds_dwordx4 v[184:185], off
	s_mov_b32 m0, s30
	s_nop 0
	global_load_lds_dwordx4 v156, s[28:29]
	s_add_i32 m0, s30, 0x2000
	s_nop 0
	global_load_lds_dwordx4 v160, s[28:29]
	v_lshl_add_u64 v[184:185], v[244:245], 0, s[96:97]
	s_mov_b32 m0, s44
	s_nop 0
	global_load_lds_dwordx4 v[184:185], off
	v_lshl_add_u64 v[184:185], v[246:247], 0, s[96:97]
	s_mov_b32 m0, s45
	s_nop 0
	global_load_lds_dwordx4 v[184:185], off
	s_waitcnt vmcnt(8)
	s_waitcnt lgkmcnt(0)
	s_barrier
	s_setprio 1
	s_waitcnt lgkmcnt(0)
	v_mfma_f32_16x16x32_bf16 v[62:65], v[130:133], v[176:179], v[62:65]
	v_mfma_f32_16x16x32_bf16 v[58:61], v[138:141], v[176:179], v[58:61]
	v_mfma_f32_16x16x32_bf16 v[46:49], v[130:133], v[202:205], v[46:49]
	v_mfma_f32_16x16x32_bf16 v[42:45], v[138:141], v[202:205], v[42:45]
	v_mfma_f32_16x16x32_bf16 v[30:33], v[130:133], v[210:213], v[30:33]
	v_mfma_f32_16x16x32_bf16 v[26:29], v[138:141], v[210:213], v[26:29]
	v_mfma_f32_16x16x32_bf16 v[14:17], v[130:133], v[236:239], v[14:17]
	v_mfma_f32_16x16x32_bf16 v[10:13], v[138:141], v[236:239], v[10:13]
	v_mfma_f32_16x16x32_bf16 v[62:65], v[134:137], v[180:183], v[62:65]
	v_mfma_f32_16x16x32_bf16 v[58:61], v[142:145], v[180:183], v[58:61]
	v_mfma_f32_16x16x32_bf16 v[46:49], v[134:137], v[206:209], v[46:49]
	v_mfma_f32_16x16x32_bf16 v[42:45], v[142:145], v[206:209], v[42:45]
	v_mfma_f32_16x16x32_bf16 v[30:33], v[134:137], v[232:235], v[30:33]
	v_mfma_f32_16x16x32_bf16 v[26:29], v[142:145], v[232:235], v[26:29]
	v_mfma_f32_16x16x32_bf16 v[14:17], v[134:137], v[240:243], v[14:17]
	v_mfma_f32_16x16x32_bf16 v[10:13], v[142:145], v[240:243], v[10:13]
	s_setprio 0
	s_setprio 1
	v_mfma_f32_16x16x32_bf16 v[54:57], v[146:149], v[176:179], v[54:57]
	v_mfma_f32_16x16x32_bf16 v[50:53], v[168:171], v[176:179], v[50:53]
	v_mfma_f32_16x16x32_bf16 v[38:41], v[146:149], v[202:205], v[38:41]
	v_mfma_f32_16x16x32_bf16 v[34:37], v[168:171], v[202:205], v[34:37]
	v_mfma_f32_16x16x32_bf16 v[22:25], v[146:149], v[210:213], v[22:25]
	v_mfma_f32_16x16x32_bf16 v[18:21], v[168:171], v[210:213], v[18:21]
	v_mfma_f32_16x16x32_bf16 v[6:9], v[146:149], v[236:239], v[6:9]
	v_mfma_f32_16x16x32_bf16 v[2:5], v[168:171], v[236:239], v[2:5]
	v_mfma_f32_16x16x32_bf16 v[54:57], v[150:153], v[180:183], v[54:57]
	v_mfma_f32_16x16x32_bf16 v[50:53], v[172:175], v[180:183], v[50:53]
	v_mfma_f32_16x16x32_bf16 v[38:41], v[150:153], v[206:209], v[38:41]
	v_mfma_f32_16x16x32_bf16 v[34:37], v[172:175], v[206:209], v[34:37]
	v_mfma_f32_16x16x32_bf16 v[22:25], v[150:153], v[232:235], v[22:25]
	v_mfma_f32_16x16x32_bf16 v[18:21], v[172:175], v[232:235], v[18:21]
	v_mfma_f32_16x16x32_bf16 v[6:9], v[150:153], v[240:243], v[6:9]
	v_mfma_f32_16x16x32_bf16 v[2:5], v[172:175], v[240:243], v[2:5]
	s_setprio 0
	s_barrier
	s_add_i32 s51, s51, 2
	s_add_u32 s26, s26, 0x100
	s_addc_u32 s27, s27, 0
	s_add_u32 s49, s49, 0x100
	s_addc_u32 s50, s50, 0
	s_cmp_gt_u32 s51, 13
	s_cbranch_scc0 .LBB0_1270
	s_and_b64 vcc, exec, s[12:13]
	s_cbranch_vccz .LBB0_1273
	s_barrier

; #define PG8_STAGE(bufoff, gbase, voff) do { _Pragma("unroll") for (int _i = 0; _i < 2; ++_i) \
;         __builtin_amdgcn_global_load_lds((const unsigned*)((const char*)(gbase) + (voff)[_i]), (PG8_LAS unsigned*)(lds + (bufoff) + ldsw + _i * 8192), 16, 0, 0); } while (0)
; #define PG8_LDA(dst, b, h) do { _Pragma("unroll") for (int m = 0; m < 4; ++m) _Pragma("unroll") for (int k = 0; k < 2; ++k) dst[m][k] = *(const PG8_LAS bf16x8*)(lds + PG8_SA(b, h) + aoff + m * 2048 + k * 1024); } while (0)
; #define PG8_LDB(dst, b, h) do { _Pragma("unroll") for (int n = 0; n < 2; ++n) _Pragma("unroll") for (int k = 0; k < 2; ++k) dst[n][k] = *(const PG8_LAS bf16x8*)(lds + PG8_SB(b, h) + boff + n * 2048 + k * 1024); } while (0)
; #define PG8_MMA(ai, bj, At, Bt) do { __builtin_amdgcn_s_setprio(1); _Pragma("unroll") for (int m = 0; m < 4; ++m) _Pragma("unroll") for (int n = 0; n < 2; ++n) _Pragma("unroll") for (int k = 0; k < 2; ++k) \
;         acc[ai][bj][m][n] = __builtin_amdgcn_mfma_f32_16x16x32_bf16(Bt[n][k], At[m][k], acc[ai][bj][m][n], 0, 0, 0); __builtin_amdgcn_s_setprio(0); } while (0)
; #define PG8_WAIT_V(n) asm volatile("s_waitcnt vmcnt(" #n ")" ::: "memory")
; #define PG8_WAIT_L(n) asm volatile("s_waitcnt lgkmcnt(" #n ")" ::: "memory")
; #define PG8_BAR __builtin_amdgcn_s_barrier()
; #define PG8_SCHED __builtin_amdgcn_sched_barrier(0)
; template <class Epi, class Sched, bool ALIGN_EPI = false, bool SP2 = false>
; __device__ __forceinline__ void gemm_phase(PG8_LAS unsigned char* lds, const Gemm g, const Sched& S, const Epi& E) {
;     ...
;             PG8_LDB(B0, 0, 0); PG8_LDB(B1, 0, 1); PG8_SCHED; PG8_LDA(At, 0, 0); PG8_STAGE(PG8_SA(1, 1), a1 + hstepA, voffA);
;             PG8_WAIT_V(8); PG8_WAIT_L(0); PG8_BAR; PG8_MMA(0, 0, At, B0); PG8_MMA(0, 1, At, B1); PG8_BAR; PG8_SCHED;
;             PG8_LDA(At, 0, 1); PG8_STAGE(PG8_SB(0, 0), b2, voffB); PG8_STAGE(PG8_SB(0, 1), b2 + hstepB, voffB); PG8_STAGE(PG8_SA(0, 0), a2, voffA);
;             PG8_WAIT_V(8); PG8_WAIT_L(0); PG8_BAR; PG8_MMA(1, 0, At, B0); PG8_MMA(1, 1, At, B1); PG8_BAR; PG8_SCHED;
.LBB0_1354:
	s_add_u32 s24, s22, 0xfffc0080
	s_addc_u32 s25, s23, -1
	s_add_i32 s49, 0, 0x10000
	s_cmp_eq_u32 s48, 12
	s_cselect_b32 s27, s15, s25
	s_cselect_b32 s26, s21, s24
	v_add_u32_e32 v142, s49, v145
	s_cselect_b32 s25, s13, s47
	s_cselect_b32 s24, s45, s46
	s_add_i32 s52, 0, 0x14000
	ds_read_b128 v[150:153], v142
	ds_read_b128 v[154:157], v142 offset:1024
	ds_read_b128 v[158:161], v142 offset:2048
	ds_read_b128 v[162:165], v142 offset:3072
	v_add_u32_e32 v142, s52, v145
	ds_read_b128 v[166:169], v142
	ds_read_b128 v[170:173], v142 offset:1024
	ds_read_b128 v[174:177], v142 offset:2048
	ds_read_b128 v[178:181], v142 offset:3072
	s_add_i32 m0, s36, 0xc000
	ds_read_b128 v[182:185], v148
	ds_read_b128 v[202:205], v148 offset:1024
	ds_read_b128 v[206:209], v148 offset:2048
	ds_read_b128 v[210:213], v148 offset:3072
	ds_read_b128 v[232:235], v148 offset:4096
	ds_read_b128 v[236:239], v148 offset:5120
	ds_read_b128 v[240:243], v148 offset:6144
	ds_read_b128 v[244:247], v148 offset:7168
	global_load_lds_dwordx4 v138, s[22:23]
	s_add_i32 m0, s36, 0xe000
	s_nop 0
	global_load_lds_dwordx4 v140, s[22:23]
	s_waitcnt vmcnt(8)
	s_waitcnt lgkmcnt(0)
	s_barrier
	s_setprio 1
	s_waitcnt lgkmcnt(0)
	v_mfma_f32_16x16x32_bf16 v[126:129], v[150:153], v[182:185], v[126:129]
	v_mfma_f32_16x16x32_bf16 v[122:125], v[158:161], v[182:185], v[122:125]
	v_mfma_f32_16x16x32_bf16 v[114:117], v[150:153], v[206:209], v[114:117]
	v_mfma_f32_16x16x32_bf16 v[106:109], v[158:161], v[206:209], v[106:109]
	v_mfma_f32_16x16x32_bf16 v[98:101], v[150:153], v[232:235], v[98:101]
	v_mfma_f32_16x16x32_bf16 v[90:93], v[158:161], v[232:235], v[90:93]
	v_mfma_f32_16x16x32_bf16 v[78:81], v[150:153], v[240:243], v[78:81]
	v_mfma_f32_16x16x32_bf16 v[74:77], v[158:161], v[240:243], v[74:77]
	v_mfma_f32_16x16x32_bf16 v[126:129], v[154:157], v[202:205], v[126:129]
	v_mfma_f32_16x16x32_bf16 v[122:125], v[162:165], v[202:205], v[122:125]
	v_mfma_f32_16x16x32_bf16 v[114:117], v[154:157], v[210:213], v[114:117]
	v_mfma_f32_16x16x32_bf16 v[106:109], v[162:165], v[210:213], v[106:109]
	v_mfma_f32_16x16x32_bf16 v[98:101], v[154:157], v[236:239], v[98:101]
	v_mfma_f32_16x16x32_bf16 v[90:93], v[162:165], v[236:239], v[90:93]
	v_mfma_f32_16x16x32_bf16 v[78:81], v[154:157], v[244:247], v[78:81]
	v_mfma_f32_16x16x32_bf16 v[74:77], v[162:165], v[244:247], v[74:77]
	s_setprio 0
	s_setprio 1
	v_mfma_f32_16x16x32_bf16 v[118:121], v[166:169], v[182:185], v[118:121]
	v_mfma_f32_16x16x32_bf16 v[110:113], v[174:177], v[182:185], v[110:113]
	v_mfma_f32_16x16x32_bf16 v[102:105], v[166:169], v[206:209], v[102:105]
	v_mfma_f32_16x16x32_bf16 v[94:97], v[174:177], v[206:209], v[94:97]
	v_mfma_f32_16x16x32_bf16 v[86:89], v[166:169], v[232:235], v[86:89]
	v_mfma_f32_16x16x32_bf16 v[82:85], v[174:177], v[232:235], v[82:85]
	v_mfma_f32_16x16x32_bf16 v[70:73], v[166:169], v[240:243], v[70:73]
	v_mfma_f32_16x16x32_bf16 v[66:69], v[174:177], v[240:243], v[66:69]
	v_mfma_f32_16x16x32_bf16 v[118:121], v[170:173], v[202:205], v[118:121]
	v_mfma_f32_16x16x32_bf16 v[110:113], v[178:181], v[202:205], v[110:113]
	v_mfma_f32_16x16x32_bf16 v[102:105], v[170:173], v[210:213], v[102:105]
	v_mfma_f32_16x16x32_bf16 v[94:97], v[178:181], v[210:213], v[94:97]
	v_mfma_f32_16x16x32_bf16 v[86:89], v[170:173], v[236:239], v[86:89]
	v_mfma_f32_16x16x32_bf16 v[82:85], v[178:181], v[236:239], v[82:85]
	v_mfma_f32_16x16x32_bf16 v[70:73], v[170:173], v[244:247], v[70:73]
	v_mfma_f32_16x16x32_bf16 v[66:69], v[178:181], v[244:247], v[66:69]
	s_setprio 0
	s_barrier
	s_add_i32 s49, s49, s34
	v_lshl_add_u64 v[142:143], s[24:25], 0, v[134:135]
	s_mov_b32 m0, s49
	ds_read_b128 v[182:185], v148 offset:16384
	ds_read_b128 v[202:205], v148 offset:17408
	ds_read_b128 v[206:209], v148 offset:18432
	ds_read_b128 v[210:213], v148 offset:19456
	ds_read_b128 v[232:235], v148 offset:20480
	ds_read_b128 v[236:239], v148 offset:21504
	ds_read_b128 v[240:243], v148 offset:22528
	ds_read_b128 v[244:247], v148 offset:23552
	global_load_lds_dwordx4 v[142:143], off
	s_add_i32 m0, s49, 0x2000
	s_add_u32 s50, s24, 0x40000
	v_lshl_add_u64 v[186:187], s[24:25], 0, v[130:131]
	s_addc_u32 s51, s25, 0
	s_add_i32 s49, s52, s34
	global_load_lds_dwordx4 v[186:187], off
	s_mov_b32 m0, s49
	v_lshl_add_u64 v[248:249], s[26:27], 0, v[132:133]
	global_load_lds_dwordx4 v134, s[50:51]
	s_add_i32 m0, s49, 0x2000
	s_nop 0
	global_load_lds_dwordx4 v130, s[50:51]
	v_lshl_add_u64 v[214:215], s[26:27], 0, v[136:137]
	s_mov_b32 m0, s36
	s_nop 0
	global_load_lds_dwordx4 v[214:215], off
	s_mov_b32 m0, s37
	s_nop 0
	global_load_lds_dwordx4 v[248:249], off
	s_waitcnt vmcnt(8)
	s_waitcnt lgkmcnt(0)
	s_barrier
; #define PG8_STAGE(bufoff, gbase, voff) do { _Pragma("unroll") for (int _i = 0; _i < 2; ++_i) \
;         __builtin_amdgcn_global_load_lds((const unsigned*)((const char*)(gbase) + (voff)[_i]), (PG8_LAS unsigned*)(lds + (bufoff) + ldsw + _i * 8192), 16, 0, 0); } while (0)
; #define PG8_LDA(dst, b, h) do { _Pragma("unroll") for (int m = 0; m < 4; ++m) _Pragma("unroll") for (int k = 0; k < 2; ++k) dst[m][k] = *(const PG8_LAS bf16x8*)(lds + PG8_SA(b, h) + aoff + m * 2048 + k * 1024); } while (0)
; #define PG8_LDB(dst, b, h) do { _Pragma("unroll") for (int n = 0; n < 2; ++n) _Pragma("unroll") for (int k = 0; k < 2; ++k) dst[n][k] = *(const PG8_LAS bf16x8*)(lds + PG8_SB(b, h) + boff + n * 2048 + k * 1024); } while (0)
; #define PG8_MMA(ai, bj, At, Bt) do { __builtin_amdgcn_s_setprio(1); _Pragma("unroll") for (int m = 0; m < 4; ++m) _Pragma("unroll") for (int n = 0; n < 2; ++n) _Pragma("unroll") for (int k = 0; k < 2; ++k) \
;         acc[ai][bj][m][n] = __builtin_amdgcn_mfma_f32_16x16x32_bf16(Bt[n][k], At[m][k], acc[ai][bj][m][n], 0, 0, 0); __builtin_amdgcn_s_setprio(0); } while (0)
; #define PG8_WAIT_V(n) asm volatile("s_waitcnt vmcnt(" #n ")" ::: "memory")
; #define PG8_WAIT_L(n) asm volatile("s_waitcnt lgkmcnt(" #n ")" ::: "memory")
; #define PG8_BAR __builtin_amdgcn_s_barrier()
; #define PG8_SCHED __builtin_amdgcn_sched_barrier(0)
; template <class Epi, class Sched, bool ALIGN_EPI = false, bool SP2 = false>
; __device__ __forceinline__ void gemm_phase(PG8_LAS unsigned char* lds, const Gemm g, const Sched& S, const Epi& E) {
;     ...
;             PG8_WAIT_V(8); PG8_WAIT_L(0); PG8_BAR; PG8_MMA(1, 0, At, B0); PG8_MMA(1, 1, At, B1); PG8_BAR; PG8_SCHED;
;             PG8_LDB(B0, 1, 0); PG8_LDB(B1, 1, 1); PG8_SCHED; PG8_LDA(At, 1, 0); PG8_STAGE(PG8_SA(0, 1), a2 + hstepA, voffA);
;             PG8_WAIT_V(8); PG8_WAIT_L(0); PG8_BAR; PG8_MMA(0, 0, At, B0); PG8_MMA(0, 1, At, B1); PG8_BAR; PG8_SCHED;
	s_setprio 1
	s_waitcnt lgkmcnt(0)
	v_mfma_f32_16x16x32_bf16 v[62:65], v[150:153], v[182:185], v[62:65]
	v_mfma_f32_16x16x32_bf16 v[58:61], v[158:161], v[182:185], v[58:61]
	v_mfma_f32_16x16x32_bf16 v[46:49], v[150:153], v[206:209], v[46:49]
	v_mfma_f32_16x16x32_bf16 v[42:45], v[158:161], v[206:209], v[42:45]
	v_mfma_f32_16x16x32_bf16 v[30:33], v[150:153], v[232:235], v[30:33]
	v_mfma_f32_16x16x32_bf16 v[26:29], v[158:161], v[232:235], v[26:29]
	v_mfma_f32_16x16x32_bf16 v[14:17], v[150:153], v[240:243], v[14:17]
	v_mfma_f32_16x16x32_bf16 v[10:13], v[158:161], v[240:243], v[10:13]
	v_mfma_f32_16x16x32_bf16 v[62:65], v[154:157], v[202:205], v[62:65]
	v_mfma_f32_16x16x32_bf16 v[58:61], v[162:165], v[202:205], v[58:61]
	v_mfma_f32_16x16x32_bf16 v[46:49], v[154:157], v[210:213], v[46:49]
	v_mfma_f32_16x16x32_bf16 v[42:45], v[162:165], v[210:213], v[42:45]
	v_mfma_f32_16x16x32_bf16 v[30:33], v[154:157], v[236:239], v[30:33]
	v_mfma_f32_16x16x32_bf16 v[26:29], v[162:165], v[236:239], v[26:29]
	v_mfma_f32_16x16x32_bf16 v[14:17], v[154:157], v[244:247], v[14:17]
	v_mfma_f32_16x16x32_bf16 v[10:13], v[162:165], v[244:247], v[10:13]
	s_setprio 0
	s_setprio 1
	v_mfma_f32_16x16x32_bf16 v[54:57], v[166:169], v[182:185], v[54:57]
	v_mfma_f32_16x16x32_bf16 v[50:53], v[174:177], v[182:185], v[50:53]
	v_mfma_f32_16x16x32_bf16 v[38:41], v[166:169], v[206:209], v[38:41]
	v_mfma_f32_16x16x32_bf16 v[34:37], v[174:177], v[206:209], v[34:37]
	v_mfma_f32_16x16x32_bf16 v[22:25], v[166:169], v[232:235], v[22:25]
	v_mfma_f32_16x16x32_bf16 v[18:21], v[174:177], v[232:235], v[18:21]
	v_mfma_f32_16x16x32_bf16 v[6:9], v[166:169], v[240:243], v[6:9]
	v_mfma_f32_16x16x32_bf16 v[2:5], v[174:177], v[240:243], v[2:5]
	v_mfma_f32_16x16x32_bf16 v[54:57], v[170:173], v[202:205], v[54:57]
	v_mfma_f32_16x16x32_bf16 v[50:53], v[178:181], v[202:205], v[50:53]
	v_mfma_f32_16x16x32_bf16 v[38:41], v[170:173], v[210:213], v[38:41]
	v_mfma_f32_16x16x32_bf16 v[34:37], v[178:181], v[210:213], v[34:37]
	v_mfma_f32_16x16x32_bf16 v[22:25], v[170:173], v[236:239], v[22:25]
	v_mfma_f32_16x16x32_bf16 v[18:21], v[178:181], v[236:239], v[18:21]
	v_mfma_f32_16x16x32_bf16 v[6:9], v[170:173], v[244:247], v[6:9]
	v_mfma_f32_16x16x32_bf16 v[2:5], v[178:181], v[244:247], v[2:5]
	s_setprio 0
	s_barrier
	s_add_i32 s49, 0, 0x18000
	v_add_u32_e32 v144, s49, v145
	s_add_i32 s50, 0, 0x1c000
	ds_read_b128 v[150:153], v144
	ds_read_b128 v[154:157], v144 offset:1024
	ds_read_b128 v[158:161], v144 offset:2048
	ds_read_b128 v[162:165], v144 offset:3072
	v_add_u32_e32 v144, s50, v145
	ds_read_b128 v[166:169], v144
	ds_read_b128 v[170:173], v144 offset:1024
	ds_read_b128 v[174:177], v144 offset:2048
	ds_read_b128 v[178:181], v144 offset:3072
	s_add_u32 s26, s26, 0x40000
	s_addc_u32 s27, s27, 0
	s_mov_b32 m0, s38
	ds_read_b128 v[182:185], v148 offset:32768
	ds_read_b128 v[202:205], v148 offset:33792
	ds_read_b128 v[206:209], v148 offset:34816
	ds_read_b128 v[210:213], v148 offset:35840
	ds_read_b128 v[232:235], v148 offset:36864
	ds_read_b128 v[236:239], v148 offset:37888
	ds_read_b128 v[240:243], v148 offset:38912
	ds_read_b128 v[244:247], v148 offset:39936
	global_load_lds_dwordx4 v136, s[26:27]
	s_mov_b32 m0, s39
	s_nop 0
	global_load_lds_dwordx4 v132, s[26:27]
	s_waitcnt vmcnt(8)
	s_waitcnt lgkmcnt(0)
	s_barrier
	s_setprio 1
	s_waitcnt lgkmcnt(0)
	v_mfma_f32_16x16x32_bf16 v[126:129], v[150:153], v[182:185], v[126:129]
	v_mfma_f32_16x16x32_bf16 v[122:125], v[158:161], v[182:185], v[122:125]
	v_mfma_f32_16x16x32_bf16 v[114:117], v[150:153], v[206:209], v[114:117]
	v_mfma_f32_16x16x32_bf16 v[106:109], v[158:161], v[206:209], v[106:109]
	v_mfma_f32_16x16x32_bf16 v[98:101], v[150:153], v[232:235], v[98:101]
	v_mfma_f32_16x16x32_bf16 v[90:93], v[158:161], v[232:235], v[90:93]
	v_mfma_f32_16x16x32_bf16 v[78:81], v[150:153], v[240:243], v[78:81]
	v_mfma_f32_16x16x32_bf16 v[74:77], v[158:161], v[240:243], v[74:77]
	v_mfma_f32_16x16x32_bf16 v[126:129], v[154:157], v[202:205], v[126:129]
	v_mfma_f32_16x16x32_bf16 v[122:125], v[162:165], v[202:205], v[122:125]
	v_mfma_f32_16x16x32_bf16 v[114:117], v[154:157], v[210:213], v[114:117]
	v_mfma_f32_16x16x32_bf16 v[106:109], v[162:165], v[210:213], v[106:109]
	v_mfma_f32_16x16x32_bf16 v[98:101], v[154:157], v[236:239], v[98:101]
	v_mfma_f32_16x16x32_bf16 v[90:93], v[162:165], v[236:239], v[90:93]
	v_mfma_f32_16x16x32_bf16 v[78:81], v[154:157], v[244:247], v[78:81]
	v_mfma_f32_16x16x32_bf16 v[74:77], v[162:165], v[244:247], v[74:77]
	s_setprio 0
	s_setprio 1
	v_mfma_f32_16x16x32_bf16 v[118:121], v[166:169], v[182:185], v[118:121]
	v_mfma_f32_16x16x32_bf16 v[110:113], v[174:177], v[182:185], v[110:113]
	v_mfma_f32_16x16x32_bf16 v[102:105], v[166:169], v[206:209], v[102:105]
	v_mfma_f32_16x16x32_bf16 v[94:97], v[174:177], v[206:209], v[94:97]
	v_mfma_f32_16x16x32_bf16 v[86:89], v[166:169], v[232:235], v[86:89]
	v_mfma_f32_16x16x32_bf16 v[82:85], v[174:177], v[232:235], v[82:85]
	v_mfma_f32_16x16x32_bf16 v[70:73], v[166:169], v[240:243], v[70:73]
	v_mfma_f32_16x16x32_bf16 v[66:69], v[174:177], v[240:243], v[66:69]
	v_mfma_f32_16x16x32_bf16 v[118:121], v[170:173], v[202:205], v[118:121]
	v_mfma_f32_16x16x32_bf16 v[110:113], v[178:181], v[202:205], v[110:113]
	v_mfma_f32_16x16x32_bf16 v[102:105], v[170:173], v[210:213], v[102:105]
	v_mfma_f32_16x16x32_bf16 v[94:97], v[178:181], v[210:213], v[94:97]
	v_mfma_f32_16x16x32_bf16 v[86:89], v[170:173], v[236:239], v[86:89]
	v_mfma_f32_16x16x32_bf16 v[82:85], v[178:181], v[236:239], v[82:85]
	v_mfma_f32_16x16x32_bf16 v[70:73], v[170:173], v[244:247], v[70:73]
	v_mfma_f32_16x16x32_bf16 v[66:69], v[178:181], v[244:247], v[66:69]
	s_setprio 0
	s_barrier
; #define PG8_STAGE(bufoff, gbase, voff) do { _Pragma("unroll") for (int _i = 0; _i < 2; ++_i) \
;         __builtin_amdgcn_global_load_lds((const unsigned*)((const char*)(gbase) + (voff)[_i]), (PG8_LAS unsigned*)(lds + (bufoff) + ldsw + _i * 8192), 16, 0, 0); } while (0)
; #define PG8_LDA(dst, b, h) do { _Pragma("unroll") for (int m = 0; m < 4; ++m) _Pragma("unroll") for (int k = 0; k < 2; ++k) dst[m][k] = *(const PG8_LAS bf16x8*)(lds + PG8_SA(b, h) + aoff + m * 2048 + k * 1024); } while (0)
; #define PG8_MMA(ai, bj, At, Bt) do { __builtin_amdgcn_s_setprio(1); _Pragma("unroll") for (int m = 0; m < 4; ++m) _Pragma("unroll") for (int n = 0; n < 2; ++n) _Pragma("unroll") for (int k = 0; k < 2; ++k) \
;         acc[ai][bj][m][n] = __builtin_amdgcn_mfma_f32_16x16x32_bf16(Bt[n][k], At[m][k], acc[ai][bj][m][n], 0, 0, 0); __builtin_amdgcn_s_setprio(0); } while (0)
; #define PG8_WAIT_V(n) asm volatile("s_waitcnt vmcnt(" #n ")" ::: "memory")
; #define PG8_WAIT_L(n) asm volatile("s_waitcnt lgkmcnt(" #n ")" ::: "memory")
; #define PG8_BAR __builtin_amdgcn_s_barrier()
; #define PG8_SCHED __builtin_amdgcn_sched_barrier(0)
; template <class Epi, class Sched, bool ALIGN_EPI = false, bool SP2 = false>
; __device__ __forceinline__ void gemm_phase(PG8_LAS unsigned char* lds, const Gemm g, const Sched& S, const Epi& E) {
;     ...
;         for (int t = 0; t < nt; t += 2) {
;     ...
;             PG8_LDA(At, 1, 1); PG8_STAGE(PG8_SB(1, 0), b3, voffB); PG8_STAGE(PG8_SB(1, 1), b3 + hstepB, voffB); PG8_STAGE(PG8_SA(1, 0), a3, voffA);
;             PG8_WAIT_V(8); PG8_WAIT_L(0); PG8_BAR; PG8_MMA(1, 0, At, B0); PG8_MMA(1, 1, At, B1); PG8_BAR; PG8_SCHED;
	s_add_i32 s26, s49, s34
	v_lshl_add_u64 v[142:143], v[142:143], 0, s[96:97]
	s_mov_b32 m0, s26
	ds_read_b128 v[182:185], v148 offset:49152
	ds_read_b128 v[202:205], v148 offset:50176
	ds_read_b128 v[206:209], v148 offset:51200
	ds_read_b128 v[210:213], v148 offset:52224
	ds_read_b128 v[232:235], v148 offset:53248
	ds_read_b128 v[236:239], v148 offset:54272
	ds_read_b128 v[240:243], v148 offset:55296
	ds_read_b128 v[244:247], v148 offset:56320
	global_load_lds_dwordx4 v[142:143], off
	s_add_i32 m0, s26, 0x2000
	s_add_u32 s24, s24, 0x40080
	v_lshl_add_u64 v[142:143], v[186:187], 0, s[96:97]
	s_addc_u32 s25, s25, 0
	s_add_i32 s26, s50, s34
	global_load_lds_dwordx4 v[142:143], off
	s_mov_b32 m0, s26
	s_nop 0
	global_load_lds_dwordx4 v134, s[24:25]
	s_add_i32 m0, s26, 0x2000
	s_nop 0
	global_load_lds_dwordx4 v130, s[24:25]
	v_lshl_add_u64 v[142:143], v[214:215], 0, s[96:97]
	s_mov_b32 m0, s40
	s_nop 0
	global_load_lds_dwordx4 v[142:143], off
	v_lshl_add_u64 v[142:143], v[248:249], 0, s[96:97]
	s_mov_b32 m0, s41
	s_nop 0
	global_load_lds_dwordx4 v[142:143], off
	s_waitcnt vmcnt(8)
	s_waitcnt lgkmcnt(0)
	s_barrier
	s_setprio 1
	s_waitcnt lgkmcnt(0)
	v_mfma_f32_16x16x32_bf16 v[62:65], v[150:153], v[182:185], v[62:65]
	v_mfma_f32_16x16x32_bf16 v[58:61], v[158:161], v[182:185], v[58:61]
	v_mfma_f32_16x16x32_bf16 v[46:49], v[150:153], v[206:209], v[46:49]
	v_mfma_f32_16x16x32_bf16 v[42:45], v[158:161], v[206:209], v[42:45]
	v_mfma_f32_16x16x32_bf16 v[30:33], v[150:153], v[232:235], v[30:33]
	v_mfma_f32_16x16x32_bf16 v[26:29], v[158:161], v[232:235], v[26:29]
	v_mfma_f32_16x16x32_bf16 v[14:17], v[150:153], v[240:243], v[14:17]
	v_mfma_f32_16x16x32_bf16 v[10:13], v[158:161], v[240:243], v[10:13]
	v_mfma_f32_16x16x32_bf16 v[62:65], v[154:157], v[202:205], v[62:65]
	v_mfma_f32_16x16x32_bf16 v[58:61], v[162:165], v[202:205], v[58:61]
	v_mfma_f32_16x16x32_bf16 v[46:49], v[154:157], v[210:213], v[46:49]
	v_mfma_f32_16x16x32_bf16 v[42:45], v[162:165], v[210:213], v[42:45]
	v_mfma_f32_16x16x32_bf16 v[30:33], v[154:157], v[236:239], v[30:33]
	v_mfma_f32_16x16x32_bf16 v[26:29], v[162:165], v[236:239], v[26:29]
	v_mfma_f32_16x16x32_bf16 v[14:17], v[154:157], v[244:247], v[14:17]
	v_mfma_f32_16x16x32_bf16 v[10:13], v[162:165], v[244:247], v[10:13]
	s_setprio 0
	s_setprio 1
	v_mfma_f32_16x16x32_bf16 v[54:57], v[166:169], v[182:185], v[54:57]
	v_mfma_f32_16x16x32_bf16 v[50:53], v[174:177], v[182:185], v[50:53]
	v_mfma_f32_16x16x32_bf16 v[38:41], v[166:169], v[206:209], v[38:41]
	v_mfma_f32_16x16x32_bf16 v[34:37], v[174:177], v[206:209], v[34:37]
	v_mfma_f32_16x16x32_bf16 v[22:25], v[166:169], v[232:235], v[22:25]
	v_mfma_f32_16x16x32_bf16 v[18:21], v[174:177], v[232:235], v[18:21]
	v_mfma_f32_16x16x32_bf16 v[6:9], v[166:169], v[240:243], v[6:9]
	v_mfma_f32_16x16x32_bf16 v[2:5], v[174:177], v[240:243], v[2:5]
	v_mfma_f32_16x16x32_bf16 v[54:57], v[170:173], v[202:205], v[54:57]
	v_mfma_f32_16x16x32_bf16 v[50:53], v[178:181], v[202:205], v[50:53]
	v_mfma_f32_16x16x32_bf16 v[38:41], v[170:173], v[210:213], v[38:41]
	v_mfma_f32_16x16x32_bf16 v[34:37], v[178:181], v[210:213], v[34:37]
	v_mfma_f32_16x16x32_bf16 v[22:25], v[170:173], v[236:239], v[22:25]
	v_mfma_f32_16x16x32_bf16 v[18:21], v[178:181], v[236:239], v[18:21]
	v_mfma_f32_16x16x32_bf16 v[6:9], v[170:173], v[244:247], v[6:9]
	v_mfma_f32_16x16x32_bf16 v[2:5], v[178:181], v[244:247], v[2:5]
	s_setprio 0
	s_barrier
	s_add_i32 s48, s48, 2
	s_add_u32 s22, s22, 0x100
	s_addc_u32 s23, s23, 0
	s_add_u32 s46, s46, 0x100
	s_addc_u32 s47, s47, 0
	s_cmp_gt_u32 s48, 13
	s_cbranch_scc0 .LBB0_1354
	s_and_b64 vcc, exec, s[10:11]
	s_cbranch_vccz .LBB0_1357
	s_barrier

; #define PG8_STAGE(bufoff, gbase, voff) do { _Pragma("unroll") for (int _i = 0; _i < 2; ++_i) \
;         __builtin_amdgcn_global_load_lds((const unsigned*)((const char*)(gbase) + (voff)[_i]), (PG8_LAS unsigned*)(lds + (bufoff) + ldsw + _i * 8192), 16, 0, 0); } while (0)
; #define PG8_LDA(dst, b, h) do { _Pragma("unroll") for (int m = 0; m < 4; ++m) _Pragma("unroll") for (int k = 0; k < 2; ++k) dst[m][k] = *(const PG8_LAS bf16x8*)(lds + PG8_SA(b, h) + aoff + m * 2048 + k * 1024); } while (0)
; #define PG8_LDB(dst, b, h) do { _Pragma("unroll") for (int n = 0; n < 2; ++n) _Pragma("unroll") for (int k = 0; k < 2; ++k) dst[n][k] = *(const PG8_LAS bf16x8*)(lds + PG8_SB(b, h) + boff + n * 2048 + k * 1024); } while (0)
; #define PG8_MMA(ai, bj, At, Bt) do { __builtin_amdgcn_s_setprio(1); _Pragma("unroll") for (int m = 0; m < 4; ++m) _Pragma("unroll") for (int n = 0; n < 2; ++n) _Pragma("unroll") for (int k = 0; k < 2; ++k) \
;         acc[ai][bj][m][n] = __builtin_amdgcn_mfma_f32_16x16x32_bf16(Bt[n][k], At[m][k], acc[ai][bj][m][n], 0, 0, 0); __builtin_amdgcn_s_setprio(0); } while (0)
; #define PG8_WAIT_V(n) asm volatile("s_waitcnt vmcnt(" #n ")" ::: "memory")
; #define PG8_WAIT_L(n) asm volatile("s_waitcnt lgkmcnt(" #n ")" ::: "memory")
; #define PG8_BAR __builtin_amdgcn_s_barrier()
; #define PG8_SCHED __builtin_amdgcn_sched_barrier(0)
; template <class Epi, class Sched, bool ALIGN_EPI = false, bool SP2 = false>
; __device__ __forceinline__ void gemm_phase(PG8_LAS unsigned char* lds, const Gemm g, const Sched& S, const Epi& E) {
;     ...
;             PG8_LDB(B0, 0, 0); PG8_LDB(B1, 0, 1); PG8_SCHED; PG8_LDA(At, 0, 0); PG8_STAGE(PG8_SA(1, 1), a1 + hstepA, voffA);
;             PG8_WAIT_V(8); PG8_WAIT_L(0); PG8_BAR; PG8_MMA(0, 0, At, B0); PG8_MMA(0, 1, At, B1); PG8_BAR; PG8_SCHED;
;             PG8_LDA(At, 0, 1); PG8_STAGE(PG8_SB(0, 0), b2, voffB); PG8_STAGE(PG8_SB(0, 1), b2 + hstepB, voffB); PG8_STAGE(PG8_SA(0, 0), a2, voffA);
;             PG8_WAIT_V(8); PG8_WAIT_L(0); PG8_BAR; PG8_MMA(1, 0, At, B0); PG8_MMA(1, 1, At, B1); PG8_BAR; PG8_SCHED;
.LBB0_1438:
	s_add_u32 s20, s18, 0x100
	s_addc_u32 s21, s19, 0
	s_add_i32 s50, 0, 0x10000
	s_cmp_eq_u32 s49, 40
	s_cselect_b32 s25, s9, s21
	s_cselect_b32 s24, s8, s20
	s_cselect_b32 s23, s17, s48
	s_cselect_b32 s22, s16, s47
	s_add_i32 s51, 0, 0x14000
	v_add_u32_e32 v142, s50, v186
	v_add_u32_e32 v172, s51, v186
	ds_read_b128 v[130:133], v142
	ds_read_b128 v[134:137], v142 offset:1024
	ds_read_b128 v[138:141], v142 offset:2048
	ds_read_b128 v[142:145], v142 offset:3072
	ds_read_b128 v[146:149], v172
	ds_read_b128 v[150:153], v172 offset:1024
	ds_read_b128 v[168:171], v172 offset:2048
	ds_read_b128 v[172:175], v172 offset:3072
	s_add_i32 m0, s31, 0xc000
	ds_read_b128 v[176:179], v200
	ds_read_b128 v[180:183], v200 offset:1024
	ds_read_b128 v[202:205], v200 offset:2048
	ds_read_b128 v[206:209], v200 offset:3072
	ds_read_b128 v[210:213], v200 offset:4096
	ds_read_b128 v[232:235], v200 offset:5120
	ds_read_b128 v[236:239], v200 offset:6144
	ds_read_b128 v[240:243], v200 offset:7168
	global_load_lds_dwordx4 v164, s[18:19]
	s_add_i32 m0, s31, 0xe000
	s_nop 0
	global_load_lds_dwordx4 v166, s[18:19]
	s_waitcnt vmcnt(8)
	s_waitcnt lgkmcnt(0)
	s_barrier
	s_setprio 1
	s_waitcnt lgkmcnt(0)
	v_mfma_f32_16x16x32_bf16 v[126:129], v[130:133], v[176:179], v[126:129]
	v_mfma_f32_16x16x32_bf16 v[122:125], v[138:141], v[176:179], v[122:125]
	v_mfma_f32_16x16x32_bf16 v[110:113], v[130:133], v[202:205], v[110:113]
	v_mfma_f32_16x16x32_bf16 v[106:109], v[138:141], v[202:205], v[106:109]
	v_mfma_f32_16x16x32_bf16 v[94:97], v[130:133], v[210:213], v[94:97]
	v_mfma_f32_16x16x32_bf16 v[90:93], v[138:141], v[210:213], v[90:93]
	v_mfma_f32_16x16x32_bf16 v[78:81], v[130:133], v[236:239], v[78:81]
	v_mfma_f32_16x16x32_bf16 v[74:77], v[138:141], v[236:239], v[74:77]
	v_mfma_f32_16x16x32_bf16 v[126:129], v[134:137], v[180:183], v[126:129]
	v_mfma_f32_16x16x32_bf16 v[122:125], v[142:145], v[180:183], v[122:125]
	v_mfma_f32_16x16x32_bf16 v[110:113], v[134:137], v[206:209], v[110:113]
	v_mfma_f32_16x16x32_bf16 v[106:109], v[142:145], v[206:209], v[106:109]
	v_mfma_f32_16x16x32_bf16 v[94:97], v[134:137], v[232:235], v[94:97]
	v_mfma_f32_16x16x32_bf16 v[90:93], v[142:145], v[232:235], v[90:93]
	v_mfma_f32_16x16x32_bf16 v[78:81], v[134:137], v[240:243], v[78:81]
	v_mfma_f32_16x16x32_bf16 v[74:77], v[142:145], v[240:243], v[74:77]
	s_setprio 0
	s_setprio 1
	v_mfma_f32_16x16x32_bf16 v[118:121], v[146:149], v[176:179], v[118:121]
	v_mfma_f32_16x16x32_bf16 v[114:117], v[168:171], v[176:179], v[114:117]
	v_mfma_f32_16x16x32_bf16 v[102:105], v[146:149], v[202:205], v[102:105]
	v_mfma_f32_16x16x32_bf16 v[98:101], v[168:171], v[202:205], v[98:101]
	v_mfma_f32_16x16x32_bf16 v[86:89], v[146:149], v[210:213], v[86:89]
	v_mfma_f32_16x16x32_bf16 v[82:85], v[168:171], v[210:213], v[82:85]
	v_mfma_f32_16x16x32_bf16 v[70:73], v[146:149], v[236:239], v[70:73]
	v_mfma_f32_16x16x32_bf16 v[66:69], v[168:171], v[236:239], v[66:69]
	v_mfma_f32_16x16x32_bf16 v[118:121], v[150:153], v[180:183], v[118:121]
	v_mfma_f32_16x16x32_bf16 v[114:117], v[172:175], v[180:183], v[114:117]
	v_mfma_f32_16x16x32_bf16 v[102:105], v[150:153], v[206:209], v[102:105]
	v_mfma_f32_16x16x32_bf16 v[98:101], v[172:175], v[206:209], v[98:101]
	v_mfma_f32_16x16x32_bf16 v[86:89], v[150:153], v[232:235], v[86:89]
	v_mfma_f32_16x16x32_bf16 v[82:85], v[172:175], v[232:235], v[82:85]
	v_mfma_f32_16x16x32_bf16 v[70:73], v[150:153], v[240:243], v[70:73]
	v_mfma_f32_16x16x32_bf16 v[66:69], v[172:175], v[240:243], v[66:69]
	s_setprio 0
	s_barrier
	s_add_i32 s18, s50, s30
	v_lshl_add_u64 v[184:185], s[22:23], 0, v[156:157]
	s_mov_b32 m0, s18
	ds_read_b128 v[176:179], v200 offset:16384
	ds_read_b128 v[180:183], v200 offset:17408
	ds_read_b128 v[202:205], v200 offset:18432
	ds_read_b128 v[206:209], v200 offset:19456
	ds_read_b128 v[210:213], v200 offset:20480
	ds_read_b128 v[232:235], v200 offset:21504
	ds_read_b128 v[236:239], v200 offset:22528
	ds_read_b128 v[240:243], v200 offset:23552
	global_load_lds_dwordx4 v[184:185], off
	s_add_i32 m0, s18, 0x2000
	s_add_u32 s18, s22, 0xb0000
	v_lshl_add_u64 v[214:215], s[22:23], 0, v[160:161]
	s_addc_u32 s19, s23, 0
	s_add_i32 s50, s51, s30
	global_load_lds_dwordx4 v[214:215], off
	s_mov_b32 m0, s50
	v_lshl_add_u64 v[246:247], s[24:25], 0, v[158:159]
	global_load_lds_dwordx4 v156, s[18:19]
	s_add_i32 m0, s50, 0x2000
	s_nop 0
	global_load_lds_dwordx4 v160, s[18:19]
	v_lshl_add_u64 v[244:245], s[24:25], 0, v[154:155]
	s_mov_b32 m0, s31
	s_nop 0
	global_load_lds_dwordx4 v[244:245], off
	s_mov_b32 m0, s34
	s_nop 0
	global_load_lds_dwordx4 v[246:247], off
	s_waitcnt vmcnt(8)
	s_waitcnt lgkmcnt(0)
	s_barrier
; #define PG8_STAGE(bufoff, gbase, voff) do { _Pragma("unroll") for (int _i = 0; _i < 2; ++_i) \
;         __builtin_amdgcn_global_load_lds((const unsigned*)((const char*)(gbase) + (voff)[_i]), (PG8_LAS unsigned*)(lds + (bufoff) + ldsw + _i * 8192), 16, 0, 0); } while (0)
; #define PG8_LDA(dst, b, h) do { _Pragma("unroll") for (int m = 0; m < 4; ++m) _Pragma("unroll") for (int k = 0; k < 2; ++k) dst[m][k] = *(const PG8_LAS bf16x8*)(lds + PG8_SA(b, h) + aoff + m * 2048 + k * 1024); } while (0)
; #define PG8_LDB(dst, b, h) do { _Pragma("unroll") for (int n = 0; n < 2; ++n) _Pragma("unroll") for (int k = 0; k < 2; ++k) dst[n][k] = *(const PG8_LAS bf16x8*)(lds + PG8_SB(b, h) + boff + n * 2048 + k * 1024); } while (0)
; #define PG8_MMA(ai, bj, At, Bt) do { __builtin_amdgcn_s_setprio(1); _Pragma("unroll") for (int m = 0; m < 4; ++m) _Pragma("unroll") for (int n = 0; n < 2; ++n) _Pragma("unroll") for (int k = 0; k < 2; ++k) \
;         acc[ai][bj][m][n] = __builtin_amdgcn_mfma_f32_16x16x32_bf16(Bt[n][k], At[m][k], acc[ai][bj][m][n], 0, 0, 0); __builtin_amdgcn_s_setprio(0); } while (0)
; #define PG8_WAIT_V(n) asm volatile("s_waitcnt vmcnt(" #n ")" ::: "memory")
; #define PG8_WAIT_L(n) asm volatile("s_waitcnt lgkmcnt(" #n ")" ::: "memory")
; #define PG8_BAR __builtin_amdgcn_s_barrier()
; #define PG8_SCHED __builtin_amdgcn_sched_barrier(0)
; template <class Epi, class Sched, bool ALIGN_EPI = false, bool SP2 = false>
; __device__ __forceinline__ void gemm_phase(PG8_LAS unsigned char* lds, const Gemm g, const Sched& S, const Epi& E) {
;     ...
;             PG8_WAIT_V(8); PG8_WAIT_L(0); PG8_BAR; PG8_MMA(1, 0, At, B0); PG8_MMA(1, 1, At, B1); PG8_BAR; PG8_SCHED;
;             PG8_LDB(B0, 1, 0); PG8_LDB(B1, 1, 1); PG8_SCHED; PG8_LDA(At, 1, 0); PG8_STAGE(PG8_SA(0, 1), a2 + hstepA, voffA);
;             PG8_WAIT_V(8); PG8_WAIT_L(0); PG8_BAR; PG8_MMA(0, 0, At, B0); PG8_MMA(0, 1, At, B1); PG8_BAR; PG8_SCHED;
	s_setprio 1
	s_waitcnt lgkmcnt(0)
	v_mfma_f32_16x16x32_bf16 v[62:65], v[130:133], v[176:179], v[62:65]
	v_mfma_f32_16x16x32_bf16 v[58:61], v[138:141], v[176:179], v[58:61]
	v_mfma_f32_16x16x32_bf16 v[46:49], v[130:133], v[202:205], v[46:49]
	v_mfma_f32_16x16x32_bf16 v[42:45], v[138:141], v[202:205], v[42:45]
	v_mfma_f32_16x16x32_bf16 v[30:33], v[130:133], v[210:213], v[30:33]
	v_mfma_f32_16x16x32_bf16 v[26:29], v[138:141], v[210:213], v[26:29]
	v_mfma_f32_16x16x32_bf16 v[14:17], v[130:133], v[236:239], v[14:17]
	v_mfma_f32_16x16x32_bf16 v[10:13], v[138:141], v[236:239], v[10:13]
	v_mfma_f32_16x16x32_bf16 v[62:65], v[134:137], v[180:183], v[62:65]
	v_mfma_f32_16x16x32_bf16 v[58:61], v[142:145], v[180:183], v[58:61]
	v_mfma_f32_16x16x32_bf16 v[46:49], v[134:137], v[206:209], v[46:49]
	v_mfma_f32_16x16x32_bf16 v[42:45], v[142:145], v[206:209], v[42:45]
	v_mfma_f32_16x16x32_bf16 v[30:33], v[134:137], v[232:235], v[30:33]
	v_mfma_f32_16x16x32_bf16 v[26:29], v[142:145], v[232:235], v[26:29]
	v_mfma_f32_16x16x32_bf16 v[14:17], v[134:137], v[240:243], v[14:17]
	v_mfma_f32_16x16x32_bf16 v[10:13], v[142:145], v[240:243], v[10:13]
	s_setprio 0
	s_setprio 1
	v_mfma_f32_16x16x32_bf16 v[54:57], v[146:149], v[176:179], v[54:57]
	v_mfma_f32_16x16x32_bf16 v[50:53], v[168:171], v[176:179], v[50:53]
	v_mfma_f32_16x16x32_bf16 v[38:41], v[146:149], v[202:205], v[38:41]
	v_mfma_f32_16x16x32_bf16 v[34:37], v[168:171], v[202:205], v[34:37]
	v_mfma_f32_16x16x32_bf16 v[22:25], v[146:149], v[210:213], v[22:25]
	v_mfma_f32_16x16x32_bf16 v[18:21], v[168:171], v[210:213], v[18:21]
	v_mfma_f32_16x16x32_bf16 v[6:9], v[146:149], v[236:239], v[6:9]
	v_mfma_f32_16x16x32_bf16 v[2:5], v[168:171], v[236:239], v[2:5]
	v_mfma_f32_16x16x32_bf16 v[54:57], v[150:153], v[180:183], v[54:57]
	v_mfma_f32_16x16x32_bf16 v[50:53], v[172:175], v[180:183], v[50:53]
	v_mfma_f32_16x16x32_bf16 v[38:41], v[150:153], v[206:209], v[38:41]
	v_mfma_f32_16x16x32_bf16 v[34:37], v[172:175], v[206:209], v[34:37]
	v_mfma_f32_16x16x32_bf16 v[22:25], v[150:153], v[232:235], v[22:25]
	v_mfma_f32_16x16x32_bf16 v[18:21], v[172:175], v[232:235], v[18:21]
	v_mfma_f32_16x16x32_bf16 v[6:9], v[150:153], v[240:243], v[6:9]
	v_mfma_f32_16x16x32_bf16 v[2:5], v[172:175], v[240:243], v[2:5]
	s_setprio 0
	s_barrier
	s_add_i32 s50, 0, 0x18000
	s_add_i32 s51, 0, 0x1c000
	v_add_u32_e32 v142, s50, v186
	v_add_u32_e32 v172, s51, v186
	ds_read_b128 v[130:133], v142
	ds_read_b128 v[134:137], v142 offset:1024
	ds_read_b128 v[138:141], v142 offset:2048
	ds_read_b128 v[142:145], v142 offset:3072
	ds_read_b128 v[146:149], v172
	ds_read_b128 v[150:153], v172 offset:1024
	ds_read_b128 v[168:171], v172 offset:2048
	ds_read_b128 v[172:175], v172 offset:3072
	s_add_u32 s18, s24, 0xb0000
	s_addc_u32 s19, s25, 0
	s_mov_b32 m0, s35
	ds_read_b128 v[176:179], v200 offset:32768
	ds_read_b128 v[180:183], v200 offset:33792
	ds_read_b128 v[202:205], v200 offset:34816
	ds_read_b128 v[206:209], v200 offset:35840
	ds_read_b128 v[210:213], v200 offset:36864
	ds_read_b128 v[232:235], v200 offset:37888
	ds_read_b128 v[236:239], v200 offset:38912
	ds_read_b128 v[240:243], v200 offset:39936
	global_load_lds_dwordx4 v154, s[18:19]
	s_mov_b32 m0, s36
	s_nop 0
	global_load_lds_dwordx4 v158, s[18:19]
	s_waitcnt vmcnt(8)
	s_waitcnt lgkmcnt(0)
	s_barrier
	s_setprio 1
	s_waitcnt lgkmcnt(0)
	v_mfma_f32_16x16x32_bf16 v[126:129], v[130:133], v[176:179], v[126:129]
	v_mfma_f32_16x16x32_bf16 v[122:125], v[138:141], v[176:179], v[122:125]
	v_mfma_f32_16x16x32_bf16 v[110:113], v[130:133], v[202:205], v[110:113]
	v_mfma_f32_16x16x32_bf16 v[106:109], v[138:141], v[202:205], v[106:109]
	v_mfma_f32_16x16x32_bf16 v[94:97], v[130:133], v[210:213], v[94:97]
	v_mfma_f32_16x16x32_bf16 v[90:93], v[138:141], v[210:213], v[90:93]
	v_mfma_f32_16x16x32_bf16 v[78:81], v[130:133], v[236:239], v[78:81]
	v_mfma_f32_16x16x32_bf16 v[74:77], v[138:141], v[236:239], v[74:77]
	v_mfma_f32_16x16x32_bf16 v[126:129], v[134:137], v[180:183], v[126:129]
	v_mfma_f32_16x16x32_bf16 v[122:125], v[142:145], v[180:183], v[122:125]
	v_mfma_f32_16x16x32_bf16 v[110:113], v[134:137], v[206:209], v[110:113]
	v_mfma_f32_16x16x32_bf16 v[106:109], v[142:145], v[206:209], v[106:109]
	v_mfma_f32_16x16x32_bf16 v[94:97], v[134:137], v[232:235], v[94:97]
	v_mfma_f32_16x16x32_bf16 v[90:93], v[142:145], v[232:235], v[90:93]
	v_mfma_f32_16x16x32_bf16 v[78:81], v[134:137], v[240:243], v[78:81]
	v_mfma_f32_16x16x32_bf16 v[74:77], v[142:145], v[240:243], v[74:77]
	s_setprio 0
	s_setprio 1
	v_mfma_f32_16x16x32_bf16 v[118:121], v[146:149], v[176:179], v[118:121]
	v_mfma_f32_16x16x32_bf16 v[114:117], v[168:171], v[176:179], v[114:117]
	v_mfma_f32_16x16x32_bf16 v[102:105], v[146:149], v[202:205], v[102:105]
	v_mfma_f32_16x16x32_bf16 v[98:101], v[168:171], v[202:205], v[98:101]
	v_mfma_f32_16x16x32_bf16 v[86:89], v[146:149], v[210:213], v[86:89]
	v_mfma_f32_16x16x32_bf16 v[82:85], v[168:171], v[210:213], v[82:85]
	v_mfma_f32_16x16x32_bf16 v[70:73], v[146:149], v[236:239], v[70:73]
	v_mfma_f32_16x16x32_bf16 v[66:69], v[168:171], v[236:239], v[66:69]
	v_mfma_f32_16x16x32_bf16 v[118:121], v[150:153], v[180:183], v[118:121]
	v_mfma_f32_16x16x32_bf16 v[114:117], v[172:175], v[180:183], v[114:117]
	v_mfma_f32_16x16x32_bf16 v[102:105], v[150:153], v[206:209], v[102:105]
	v_mfma_f32_16x16x32_bf16 v[98:101], v[172:175], v[206:209], v[98:101]
	v_mfma_f32_16x16x32_bf16 v[86:89], v[150:153], v[232:235], v[86:89]
	v_mfma_f32_16x16x32_bf16 v[82:85], v[172:175], v[232:235], v[82:85]
	v_mfma_f32_16x16x32_bf16 v[70:73], v[150:153], v[240:243], v[70:73]
	v_mfma_f32_16x16x32_bf16 v[66:69], v[172:175], v[240:243], v[66:69]
	s_setprio 0
	s_barrier
; #define PG8_STAGE(bufoff, gbase, voff) do { _Pragma("unroll") for (int _i = 0; _i < 2; ++_i) \
;         __builtin_amdgcn_global_load_lds((const unsigned*)((const char*)(gbase) + (voff)[_i]), (PG8_LAS unsigned*)(lds + (bufoff) + ldsw + _i * 8192), 16, 0, 0); } while (0)
; #define PG8_LDA(dst, b, h) do { _Pragma("unroll") for (int m = 0; m < 4; ++m) _Pragma("unroll") for (int k = 0; k < 2; ++k) dst[m][k] = *(const PG8_LAS bf16x8*)(lds + PG8_SA(b, h) + aoff + m * 2048 + k * 1024); } while (0)
; #define PG8_MMA(ai, bj, At, Bt) do { __builtin_amdgcn_s_setprio(1); _Pragma("unroll") for (int m = 0; m < 4; ++m) _Pragma("unroll") for (int n = 0; n < 2; ++n) _Pragma("unroll") for (int k = 0; k < 2; ++k) \
;         acc[ai][bj][m][n] = __builtin_amdgcn_mfma_f32_16x16x32_bf16(Bt[n][k], At[m][k], acc[ai][bj][m][n], 0, 0, 0); __builtin_amdgcn_s_setprio(0); } while (0)
; #define PG8_WAIT_V(n) asm volatile("s_waitcnt vmcnt(" #n ")" ::: "memory")
; #define PG8_WAIT_L(n) asm volatile("s_waitcnt lgkmcnt(" #n ")" ::: "memory")
; #define PG8_BAR __builtin_amdgcn_s_barrier()
; #define PG8_SCHED __builtin_amdgcn_sched_barrier(0)
; template <class Epi, class Sched, bool ALIGN_EPI = false, bool SP2 = false>
; __device__ __forceinline__ void gemm_phase(PG8_LAS unsigned char* lds, const Gemm g, const Sched& S, const Epi& E) {
;     ...
;             PG8_LDA(At, 1, 1); PG8_STAGE(PG8_SB(1, 0), b3, voffB); PG8_STAGE(PG8_SB(1, 1), b3 + hstepB, voffB); PG8_STAGE(PG8_SA(1, 0), a3, voffA);
;             PG8_WAIT_V(8); PG8_WAIT_L(0); PG8_BAR; PG8_MMA(1, 0, At, B0); PG8_MMA(1, 1, At, B1); PG8_BAR; PG8_SCHED;
	s_add_i32 s18, s50, s30
	v_lshl_add_u64 v[184:185], v[184:185], 0, s[96:97]
	s_mov_b32 m0, s18
	ds_read_b128 v[176:179], v200 offset:49152
	ds_read_b128 v[180:183], v200 offset:50176
	ds_read_b128 v[202:205], v200 offset:51200
	ds_read_b128 v[206:209], v200 offset:52224
	ds_read_b128 v[210:213], v200 offset:53248
	ds_read_b128 v[232:235], v200 offset:54272
	ds_read_b128 v[236:239], v200 offset:55296
	ds_read_b128 v[240:243], v200 offset:56320
	global_load_lds_dwordx4 v[184:185], off
	s_add_i32 m0, s18, 0x2000
	s_add_u32 s18, s22, 0xb0080
	v_lshl_add_u64 v[184:185], v[214:215], 0, s[96:97]
	s_addc_u32 s19, s23, 0
	s_add_i32 s22, s51, s30
	global_load_lds_dwordx4 v[184:185], off
	s_mov_b32 m0, s22
	s_nop 0
	global_load_lds_dwordx4 v156, s[18:19]
	s_add_i32 m0, s22, 0x2000
	s_nop 0
	global_load_lds_dwordx4 v160, s[18:19]
	v_lshl_add_u64 v[184:185], v[244:245], 0, s[96:97]
	s_mov_b32 m0, s38
	s_nop 0
	global_load_lds_dwordx4 v[184:185], off
	v_lshl_add_u64 v[184:185], v[246:247], 0, s[96:97]
	s_mov_b32 m0, s39
	s_nop 0
	global_load_lds_dwordx4 v[184:185], off
	s_waitcnt vmcnt(8)
	s_waitcnt lgkmcnt(0)
	s_barrier
	s_setprio 1
	s_waitcnt lgkmcnt(0)
	v_mfma_f32_16x16x32_bf16 v[62:65], v[130:133], v[176:179], v[62:65]
	v_mfma_f32_16x16x32_bf16 v[58:61], v[138:141], v[176:179], v[58:61]
	v_mfma_f32_16x16x32_bf16 v[46:49], v[130:133], v[202:205], v[46:49]
	v_mfma_f32_16x16x32_bf16 v[42:45], v[138:141], v[202:205], v[42:45]
	v_mfma_f32_16x16x32_bf16 v[30:33], v[130:133], v[210:213], v[30:33]
	v_mfma_f32_16x16x32_bf16 v[26:29], v[138:141], v[210:213], v[26:29]
	v_mfma_f32_16x16x32_bf16 v[14:17], v[130:133], v[236:239], v[14:17]
	v_mfma_f32_16x16x32_bf16 v[10:13], v[138:141], v[236:239], v[10:13]
	v_mfma_f32_16x16x32_bf16 v[62:65], v[134:137], v[180:183], v[62:65]
	v_mfma_f32_16x16x32_bf16 v[58:61], v[142:145], v[180:183], v[58:61]
	v_mfma_f32_16x16x32_bf16 v[46:49], v[134:137], v[206:209], v[46:49]
	v_mfma_f32_16x16x32_bf16 v[42:45], v[142:145], v[206:209], v[42:45]
	v_mfma_f32_16x16x32_bf16 v[30:33], v[134:137], v[232:235], v[30:33]
	v_mfma_f32_16x16x32_bf16 v[26:29], v[142:145], v[232:235], v[26:29]
	v_mfma_f32_16x16x32_bf16 v[14:17], v[134:137], v[240:243], v[14:17]
	v_mfma_f32_16x16x32_bf16 v[10:13], v[142:145], v[240:243], v[10:13]
	s_setprio 0
	s_setprio 1
	v_mfma_f32_16x16x32_bf16 v[54:57], v[146:149], v[176:179], v[54:57]
	v_mfma_f32_16x16x32_bf16 v[50:53], v[168:171], v[176:179], v[50:53]
	v_mfma_f32_16x16x32_bf16 v[38:41], v[146:149], v[202:205], v[38:41]
	v_mfma_f32_16x16x32_bf16 v[34:37], v[168:171], v[202:205], v[34:37]
	v_mfma_f32_16x16x32_bf16 v[22:25], v[146:149], v[210:213], v[22:25]
	v_mfma_f32_16x16x32_bf16 v[18:21], v[168:171], v[210:213], v[18:21]
	v_mfma_f32_16x16x32_bf16 v[6:9], v[146:149], v[236:239], v[6:9]
	v_mfma_f32_16x16x32_bf16 v[2:5], v[168:171], v[236:239], v[2:5]
	v_mfma_f32_16x16x32_bf16 v[54:57], v[150:153], v[180:183], v[54:57]
	v_mfma_f32_16x16x32_bf16 v[50:53], v[172:175], v[180:183], v[50:53]
	v_mfma_f32_16x16x32_bf16 v[38:41], v[150:153], v[206:209], v[38:41]
	v_mfma_f32_16x16x32_bf16 v[34:37], v[172:175], v[206:209], v[34:37]
	v_mfma_f32_16x16x32_bf16 v[22:25], v[150:153], v[232:235], v[22:25]
	v_mfma_f32_16x16x32_bf16 v[18:21], v[172:175], v[232:235], v[18:21]
	v_mfma_f32_16x16x32_bf16 v[6:9], v[150:153], v[240:243], v[6:9]
	v_mfma_f32_16x16x32_bf16 v[2:5], v[172:175], v[240:243], v[2:5]
	s_setprio 0
	s_barrier
	s_add_i32 s49, s49, 2
	s_add_u32 s47, s47, 0x100
	s_addc_u32 s48, s48, 0
	s_cmp_gt_u32 s49, 41
	s_mov_b64 s[18:19], s[20:21]
	s_cbranch_scc0 .LBB0_1438
	s_and_b64 vcc, exec, s[14:15]
	s_cbranch_vccz .LBB0_1441
	s_barrier
